# v63 + stage-buffer literal SGPRs folded into their users and two more DMA address pairs per body via SGPR base + offset:128
# baseline (speedup 1.0000x reference)
; #define PG8_STAGE(bufoff, gbase, voff) do { _Pragma("unroll") for (int _i = 0; _i < 2; ++_i) \
;         __builtin_amdgcn_global_load_lds((const unsigned*)((const char*)(gbase) + (voff)[_i]), (PG8_LAS unsigned*)(lds + (bufoff) + ldsw + _i * 8192), 16, 0, 0); } while (0)
; #define PG8_LDA(dst, b, h) do { _Pragma("unroll") for (int m = 0; m < 4; ++m) _Pragma("unroll") for (int k = 0; k < 2; ++k) dst[m][k] = *(const PG8_LAS bf16x8*)(lds + PG8_SA(b, h) + aoff + m * 2048 + k * 1024); } while (0)
; #define PG8_LDB(dst, b, h) do { _Pragma("unroll") for (int n = 0; n < 2; ++n) _Pragma("unroll") for (int k = 0; k < 2; ++k) dst[n][k] = *(const PG8_LAS bf16x8*)(lds + PG8_SB(b, h) + boff + n * 2048 + k * 1024); } while (0)
; #define PG8_MMA(ai, bj, At, Bt) do { __builtin_amdgcn_s_setprio(1); _Pragma("unroll") for (int m = 0; m < 4; ++m) _Pragma("unroll") for (int n = 0; n < 2; ++n) _Pragma("unroll") for (int k = 0; k < 2; ++k) \
;         acc[ai][bj][m][n] = __builtin_amdgcn_mfma_f32_16x16x32_bf16(Bt[n][k], At[m][k], acc[ai][bj][m][n], 0, 0, 0); __builtin_amdgcn_s_setprio(0); } while (0)
; #define PG8_WAIT_V(n) asm volatile("s_waitcnt vmcnt(" #n ")" ::: "memory")
; #define PG8_WAIT_L(n) asm volatile("s_waitcnt lgkmcnt(" #n ")" ::: "memory")
; template <class Epi, class Sched, bool ALIGN_EPI = false, bool SP2 = false>
; __device__ __forceinline__ void gemm_phase(PG8_LAS unsigned char* lds, const Gemm g, const Sched& S, const Epi& E, const int wv) {
;     ...
;             const bool last = (t == nt - 2);
;             const char* a1 = cA + (size_t)(t + 1) * kstep;
;             const char* a2 = last ? nA : cA + (size_t)(t + 2) * kstep; const char* b2 = last ? nB : cB + (size_t)(t + 2) * kstep;
;             const char* a3 = a2 + kstep; const char* b3 = b2 + kstep;
;             if (last && has_next) S.a_ready(nxt);
;             if constexpr (SP2) {
;             PG8_LDB(B0, 0, 0); PG8_LDB(B1, 0, 1); PG8_SCHED; PG8_LDA(At, 0, 0); PG8_STAGE(PG8_SA(1, 1), a1 + hstepA, voffA);
;             PG8_WAIT_V(8); PG8_WAIT_L(0); PG8_BAR; PG8_MMA(0, 0, At, B0); PG8_MMA(0, 1, At, B1); PG8_BAR; PG8_SCHED;
;             PG8_LDA(At, 0, 1); PG8_STAGE(PG8_SB(0, 0), b2, voffB); PG8_STAGE(PG8_SB(0, 1), b2 + hstepB, voffB); PG8_STAGE(PG8_SA(0, 0), a2, voffA);
;             PG8_WAIT_V(8); PG8_WAIT_L(0); PG8_BAR; PG8_MMA(1, 0, At, B0); PG8_MMA(1, 1, At, B1); PG8_BAR; PG8_SCHED;
.LBB0_176:
	s_add_i32 s67, s14, 2
	s_add_u32 s68, s12, 0xfff80080
	s_addc_u32 s15, s13, -1
	s_cmp_eq_u32 s61, s14
	s_cselect_b32 s15, s11, s15
	s_cselect_b32 s14, s35, s68
	s_cselect_b32 s69, s45, s43
	s_cselect_b32 s68, s44, s42
	ds_read_b128 v[66:69], v171
	ds_read_b128 v[74:77], v171 offset:1024
	ds_read_b128 v[82:85], v171 offset:2048
	ds_read_b128 v[86:89], v171 offset:3072
	ds_read_b128 v[154:157], v173
	ds_read_b128 v[158:161], v173 offset:1024
	ds_read_b128 v[174:177], v173 offset:2048
	ds_read_b128 v[178:181], v173 offset:3072
	s_add_i32 m0, s54, 0xc000
	ds_read_b128 v[202:205], v200
	ds_read_b128 v[206:209], v200 offset:1024
	ds_read_b128 v[210:213], v200 offset:2048
	ds_read_b128 v[214:217], v200 offset:3072
	ds_read_b128 v[228:231], v200 offset:4096
	ds_read_b128 v[232:235], v200 offset:5120
	ds_read_b128 v[236:239], v200 offset:6144
	ds_read_b128 v[240:243], v200 offset:7168
	global_load_lds_dwordx4 v170, s[12:13]
	s_add_i32 m0, s54, 0xe000
	s_nop 0
	global_load_lds_dwordx4 v172, s[12:13]
	s_waitcnt vmcnt(8)
	s_waitcnt lgkmcnt(0)
	s_barrier
	v_mfma_f32_16x16x32_bf16 v[150:153], v[66:69], v[202:205], v[150:153]
	v_mfma_f32_16x16x32_bf16 v[146:149], v[82:85], v[202:205], v[146:149]
	v_mfma_f32_16x16x32_bf16 v[134:137], v[66:69], v[210:213], v[134:137]
	v_mfma_f32_16x16x32_bf16 v[130:133], v[82:85], v[210:213], v[130:133]
	v_mfma_f32_16x16x32_bf16 v[118:121], v[66:69], v[228:231], v[118:121]
	v_mfma_f32_16x16x32_bf16 v[114:117], v[82:85], v[228:231], v[114:117]
	v_mfma_f32_16x16x32_bf16 v[102:105], v[66:69], v[236:239], v[102:105]
	v_mfma_f32_16x16x32_bf16 v[98:101], v[82:85], v[236:239], v[98:101]
	v_mfma_f32_16x16x32_bf16 v[150:153], v[74:77], v[206:209], v[150:153]
	v_mfma_f32_16x16x32_bf16 v[146:149], v[86:89], v[206:209], v[146:149]
	v_mfma_f32_16x16x32_bf16 v[134:137], v[74:77], v[214:217], v[134:137]
	v_mfma_f32_16x16x32_bf16 v[130:133], v[86:89], v[214:217], v[130:133]
	v_mfma_f32_16x16x32_bf16 v[118:121], v[74:77], v[232:235], v[118:121]
	v_mfma_f32_16x16x32_bf16 v[114:117], v[86:89], v[232:235], v[114:117]
	v_mfma_f32_16x16x32_bf16 v[102:105], v[74:77], v[240:243], v[102:105]
	v_mfma_f32_16x16x32_bf16 v[98:101], v[86:89], v[240:243], v[98:101]
	v_mfma_f32_16x16x32_bf16 v[142:145], v[154:157], v[202:205], v[142:145]
	v_mfma_f32_16x16x32_bf16 v[138:141], v[174:177], v[202:205], v[138:141]
	v_mfma_f32_16x16x32_bf16 v[126:129], v[154:157], v[210:213], v[126:129]
	v_mfma_f32_16x16x32_bf16 v[122:125], v[174:177], v[210:213], v[122:125]
	v_mfma_f32_16x16x32_bf16 v[110:113], v[154:157], v[228:231], v[110:113]
	v_mfma_f32_16x16x32_bf16 v[106:109], v[174:177], v[228:231], v[106:109]
	v_mfma_f32_16x16x32_bf16 v[94:97], v[154:157], v[236:239], v[94:97]
	v_mfma_f32_16x16x32_bf16 v[90:93], v[174:177], v[236:239], v[90:93]
	v_mfma_f32_16x16x32_bf16 v[142:145], v[158:161], v[206:209], v[142:145]
	v_mfma_f32_16x16x32_bf16 v[138:141], v[178:181], v[206:209], v[138:141]
	v_mfma_f32_16x16x32_bf16 v[126:129], v[158:161], v[214:217], v[126:129]
	v_mfma_f32_16x16x32_bf16 v[122:125], v[178:181], v[214:217], v[122:125]
	v_mfma_f32_16x16x32_bf16 v[110:113], v[158:161], v[232:235], v[110:113]
	v_mfma_f32_16x16x32_bf16 v[106:109], v[178:181], v[232:235], v[106:109]
	v_mfma_f32_16x16x32_bf16 v[94:97], v[158:161], v[240:243], v[94:97]
	v_mfma_f32_16x16x32_bf16 v[90:93], v[178:181], v[240:243], v[90:93]
	s_barrier
	s_add_i32 s70, s53, 0x10000
	v_lshl_add_u64 v[218:219], s[68:69], 0, v[0:1]
	s_mov_b32 m0, s70
	ds_read_b128 v[202:205], v200 offset:16384
	ds_read_b128 v[206:209], v200 offset:17408
	ds_read_b128 v[210:213], v200 offset:18432
	ds_read_b128 v[214:217], v200 offset:19456
	ds_read_b128 v[228:231], v200 offset:20480
	ds_read_b128 v[232:235], v200 offset:21504
	ds_read_b128 v[236:239], v200 offset:22528
	ds_read_b128 v[240:243], v200 offset:23552
	global_load_lds_dwordx4 v[218:219], off
	s_add_i32 m0, s70, 0x2000
	v_lshl_add_u64 v[244:245], s[68:69], 0, v[166:167]
	s_add_u32 s68, s68, s24
	s_addc_u32 s69, s69, s25
	s_add_i32 s70, s53, 0x14000
	global_load_lds_dwordx4 v[244:245], off
	s_mov_b32 m0, s70
	global_load_lds_dwordx4 v0, s[68:69]
	s_add_i32 m0, s70, 0x2000
	v_lshl_add_u64 v[250:251], s[14:15], 0, v[162:163]
	global_load_lds_dwordx4 v166, s[68:69]
	s_mov_b32 m0, s54
	v_lshl_add_u64 v[252:253], s[14:15], 0, v[164:165]
	global_load_lds_dwordx4 v[250:251], off
	s_mov_b32 m0, s55
	s_nop 0
	global_load_lds_dwordx4 v[252:253], off
	s_waitcnt vmcnt(8)
	s_waitcnt lgkmcnt(0)
	s_barrier
	v_mfma_f32_16x16x32_bf16 v[78:81], v[66:69], v[202:205], v[78:81]
	v_mfma_f32_16x16x32_bf16 v[70:73], v[82:85], v[202:205], v[70:73]
	v_mfma_f32_16x16x32_bf16 v[46:49], v[66:69], v[210:213], v[46:49]
	v_mfma_f32_16x16x32_bf16 v[42:45], v[82:85], v[210:213], v[42:45]
	v_mfma_f32_16x16x32_bf16 v[30:33], v[66:69], v[228:231], v[30:33]
	v_mfma_f32_16x16x32_bf16 v[26:29], v[82:85], v[228:231], v[26:29]
	v_mfma_f32_16x16x32_bf16 v[14:17], v[66:69], v[236:239], v[14:17]
	v_mfma_f32_16x16x32_bf16 v[10:13], v[82:85], v[236:239], v[10:13]
	v_mfma_f32_16x16x32_bf16 v[78:81], v[74:77], v[206:209], v[78:81]
	v_mfma_f32_16x16x32_bf16 v[70:73], v[86:89], v[206:209], v[70:73]
	v_mfma_f32_16x16x32_bf16 v[46:49], v[74:77], v[214:217], v[46:49]
	v_mfma_f32_16x16x32_bf16 v[42:45], v[86:89], v[214:217], v[42:45]
	v_mfma_f32_16x16x32_bf16 v[30:33], v[74:77], v[232:235], v[30:33]
	v_mfma_f32_16x16x32_bf16 v[26:29], v[86:89], v[232:235], v[26:29]
	v_mfma_f32_16x16x32_bf16 v[14:17], v[74:77], v[240:243], v[14:17]
	v_mfma_f32_16x16x32_bf16 v[10:13], v[86:89], v[240:243], v[10:13]
	v_mfma_f32_16x16x32_bf16 v[60:63], v[154:157], v[202:205], v[62:65]
	v_mfma_f32_16x16x32_bf16 v[54:57], v[174:177], v[202:205], v[54:57]
	v_mfma_f32_16x16x32_bf16 v[38:41], v[154:157], v[210:213], v[38:41]
	v_mfma_f32_16x16x32_bf16 v[34:37], v[174:177], v[210:213], v[34:37]
	v_mfma_f32_16x16x32_bf16 v[22:25], v[154:157], v[228:231], v[22:25]
	v_mfma_f32_16x16x32_bf16 v[18:21], v[174:177], v[228:231], v[18:21]
	v_mfma_f32_16x16x32_bf16 v[6:9], v[154:157], v[236:239], v[6:9]
	v_mfma_f32_16x16x32_bf16 v[2:5], v[174:177], v[236:239], v[2:5]
	v_mfma_f32_16x16x32_bf16 v[60:63], v[158:161], v[206:209], v[60:63]
	v_mfma_f32_16x16x32_bf16 v[54:57], v[178:181], v[206:209], v[54:57]
	v_mfma_f32_16x16x32_bf16 v[38:41], v[158:161], v[214:217], v[38:41]
	v_mfma_f32_16x16x32_bf16 v[34:37], v[178:181], v[214:217], v[34:37]
	v_mfma_f32_16x16x32_bf16 v[22:25], v[158:161], v[232:235], v[22:25]
	v_mfma_f32_16x16x32_bf16 v[18:21], v[178:181], v[232:235], v[18:21]
	v_mfma_f32_16x16x32_bf16 v[6:9], v[158:161], v[240:243], v[6:9]
	v_mfma_f32_16x16x32_bf16 v[2:5], v[178:181], v[240:243], v[2:5]
	s_barrier
; #define PG8_STAGE(bufoff, gbase, voff) do { _Pragma("unroll") for (int _i = 0; _i < 2; ++_i) \
;         __builtin_amdgcn_global_load_lds((const unsigned*)((const char*)(gbase) + (voff)[_i]), (PG8_LAS unsigned*)(lds + (bufoff) + ldsw + _i * 8192), 16, 0, 0); } while (0)
; #define PG8_LDA(dst, b, h) do { _Pragma("unroll") for (int m = 0; m < 4; ++m) _Pragma("unroll") for (int k = 0; k < 2; ++k) dst[m][k] = *(const PG8_LAS bf16x8*)(lds + PG8_SA(b, h) + aoff + m * 2048 + k * 1024); } while (0)
; #define PG8_LDB(dst, b, h) do { _Pragma("unroll") for (int n = 0; n < 2; ++n) _Pragma("unroll") for (int k = 0; k < 2; ++k) dst[n][k] = *(const PG8_LAS bf16x8*)(lds + PG8_SB(b, h) + boff + n * 2048 + k * 1024); } while (0)
; #define PG8_MMA(ai, bj, At, Bt) do { __builtin_amdgcn_s_setprio(1); _Pragma("unroll") for (int m = 0; m < 4; ++m) _Pragma("unroll") for (int n = 0; n < 2; ++n) _Pragma("unroll") for (int k = 0; k < 2; ++k) \
;         acc[ai][bj][m][n] = __builtin_amdgcn_mfma_f32_16x16x32_bf16(Bt[n][k], At[m][k], acc[ai][bj][m][n], 0, 0, 0); __builtin_amdgcn_s_setprio(0); } while (0)
; #define PG8_WAIT_V(n) asm volatile("s_waitcnt vmcnt(" #n ")" ::: "memory")
; #define PG8_WAIT_L(n) asm volatile("s_waitcnt lgkmcnt(" #n ")" ::: "memory")
; #define PG8_BAR __builtin_amdgcn_s_barrier()
; #define PG8_SCHED __builtin_amdgcn_sched_barrier(0)
; template <class Epi, class Sched, bool ALIGN_EPI = false, bool SP2 = false>
; __device__ __forceinline__ void gemm_phase(PG8_LAS unsigned char* lds, const Gemm g, const Sched& S, const Epi& E, const int wv) {
;     ...
;             PG8_LDB(B0, 1, 0); PG8_LDB(B1, 1, 1); PG8_SCHED; PG8_LDA(At, 1, 0); PG8_STAGE(PG8_SA(0, 1), a2 + hstepA, voffA);
;             PG8_WAIT_V(8); PG8_WAIT_L(0); PG8_BAR; PG8_MMA(0, 0, At, B0); PG8_MMA(0, 1, At, B1); PG8_BAR; PG8_SCHED;
;             PG8_LDA(At, 1, 1); PG8_STAGE(PG8_SB(1, 0), b3, voffB); PG8_STAGE(PG8_SB(1, 1), b3 + hstepB, voffB); PG8_STAGE(PG8_SA(1, 0), a3, voffA);
;             PG8_WAIT_V(8); PG8_WAIT_L(0); PG8_BAR; PG8_MMA(1, 0, At, B0); PG8_MMA(1, 1, At, B1); PG8_BAR; PG8_SCHED;
	ds_read_b128 v[64:67], v201
	ds_read_b128 v[74:77], v201 offset:1024
	ds_read_b128 v[82:85], v201 offset:2048
	ds_read_b128 v[86:89], v201 offset:3072
	ds_read_b128 v[154:157], v227
	ds_read_b128 v[158:161], v227 offset:1024
	ds_read_b128 v[174:177], v227 offset:2048
	ds_read_b128 v[178:181], v227 offset:3072
	s_add_u32 s14, s14, 0x80000
	s_addc_u32 s15, s15, 0
	s_mov_b32 m0, s56
	ds_read_b128 v[202:205], v200 offset:32768
	ds_read_b128 v[206:209], v200 offset:33792
	ds_read_b128 v[210:213], v200 offset:34816
	ds_read_b128 v[214:217], v200 offset:35840
	ds_read_b128 v[228:231], v200 offset:36864
	ds_read_b128 v[232:235], v200 offset:37888
	ds_read_b128 v[236:239], v200 offset:38912
	ds_read_b128 v[240:243], v200 offset:39936
	global_load_lds_dwordx4 v162, s[14:15]
	s_mov_b32 m0, s57
	s_nop 0
	global_load_lds_dwordx4 v164, s[14:15]
	s_waitcnt vmcnt(8)
	s_waitcnt lgkmcnt(0)
	s_barrier
	v_mfma_f32_16x16x32_bf16 v[150:153], v[64:67], v[202:205], v[150:153]
	v_mfma_f32_16x16x32_bf16 v[146:149], v[82:85], v[202:205], v[146:149]
	v_mfma_f32_16x16x32_bf16 v[134:137], v[64:67], v[210:213], v[134:137]
	v_mfma_f32_16x16x32_bf16 v[130:133], v[82:85], v[210:213], v[130:133]
	v_mfma_f32_16x16x32_bf16 v[118:121], v[64:67], v[228:231], v[118:121]
	v_mfma_f32_16x16x32_bf16 v[114:117], v[82:85], v[228:231], v[114:117]
	v_mfma_f32_16x16x32_bf16 v[102:105], v[64:67], v[236:239], v[102:105]
	v_mfma_f32_16x16x32_bf16 v[98:101], v[82:85], v[236:239], v[98:101]
	v_mfma_f32_16x16x32_bf16 v[150:153], v[74:77], v[206:209], v[150:153]
	v_mfma_f32_16x16x32_bf16 v[146:149], v[86:89], v[206:209], v[146:149]
	v_mfma_f32_16x16x32_bf16 v[134:137], v[74:77], v[214:217], v[134:137]
	v_mfma_f32_16x16x32_bf16 v[130:133], v[86:89], v[214:217], v[130:133]
	v_mfma_f32_16x16x32_bf16 v[118:121], v[74:77], v[232:235], v[118:121]
	v_mfma_f32_16x16x32_bf16 v[114:117], v[86:89], v[232:235], v[114:117]
	v_mfma_f32_16x16x32_bf16 v[102:105], v[74:77], v[240:243], v[102:105]
	v_mfma_f32_16x16x32_bf16 v[98:101], v[86:89], v[240:243], v[98:101]
	v_mfma_f32_16x16x32_bf16 v[142:145], v[154:157], v[202:205], v[142:145]
	v_mfma_f32_16x16x32_bf16 v[138:141], v[174:177], v[202:205], v[138:141]
	v_mfma_f32_16x16x32_bf16 v[126:129], v[154:157], v[210:213], v[126:129]
	v_mfma_f32_16x16x32_bf16 v[122:125], v[174:177], v[210:213], v[122:125]
	v_mfma_f32_16x16x32_bf16 v[110:113], v[154:157], v[228:231], v[110:113]
	v_mfma_f32_16x16x32_bf16 v[106:109], v[174:177], v[228:231], v[106:109]
	v_mfma_f32_16x16x32_bf16 v[94:97], v[154:157], v[236:239], v[94:97]
	v_mfma_f32_16x16x32_bf16 v[90:93], v[174:177], v[236:239], v[90:93]
	v_mfma_f32_16x16x32_bf16 v[142:145], v[158:161], v[206:209], v[142:145]
	v_mfma_f32_16x16x32_bf16 v[138:141], v[178:181], v[206:209], v[138:141]
	v_mfma_f32_16x16x32_bf16 v[126:129], v[158:161], v[214:217], v[126:129]
	v_mfma_f32_16x16x32_bf16 v[122:125], v[178:181], v[214:217], v[122:125]
	v_mfma_f32_16x16x32_bf16 v[110:113], v[158:161], v[232:235], v[110:113]
	v_mfma_f32_16x16x32_bf16 v[106:109], v[178:181], v[232:235], v[106:109]
	v_mfma_f32_16x16x32_bf16 v[94:97], v[158:161], v[240:243], v[94:97]
	v_mfma_f32_16x16x32_bf16 v[90:93], v[178:181], v[240:243], v[90:93]
	s_barrier
	s_add_i32 s14, s53, 0x18000
	s_add_i32 m0, s14, 0xffffff80
	ds_read_b128 v[202:205], v200 offset:49152
	ds_read_b128 v[206:209], v200 offset:50176
	ds_read_b128 v[210:213], v200 offset:51200
	ds_read_b128 v[214:217], v200 offset:52224
	ds_read_b128 v[228:231], v200 offset:53248
	ds_read_b128 v[232:235], v200 offset:54272
	ds_read_b128 v[236:239], v200 offset:55296
	ds_read_b128 v[240:243], v200 offset:56320
	global_load_lds_dwordx4 v[218:219], off offset:128
	s_add_i32 m0, s14, 0x1f80
	s_add_i32 s14, s53, 0x1c000
	global_load_lds_dwordx4 v[244:245], off offset:128
	s_add_i32 m0, s14, 0xffffff80
	s_nop 0
	global_load_lds_dwordx4 v0, s[68:69] offset:128
	s_add_i32 m0, s14, 0x1f80
	s_nop 0
	global_load_lds_dwordx4 v166, s[68:69] offset:128
	s_add_i32 m0, s58, 0xffffff80
	s_nop 0
	global_load_lds_dwordx4 v[250:251], off offset:128
	s_add_i32 m0, s59, 0xffffff80
	s_nop 0
	global_load_lds_dwordx4 v[252:253], off offset:128
	s_waitcnt vmcnt(8)
	s_waitcnt lgkmcnt(0)
	s_barrier
	v_mfma_f32_16x16x32_bf16 v[78:81], v[64:67], v[202:205], v[78:81]
	v_mfma_f32_16x16x32_bf16 v[68:71], v[82:85], v[202:205], v[70:73]
	v_mfma_f32_16x16x32_bf16 v[46:49], v[64:67], v[210:213], v[46:49]
	v_mfma_f32_16x16x32_bf16 v[42:45], v[82:85], v[210:213], v[42:45]
	v_mfma_f32_16x16x32_bf16 v[30:33], v[64:67], v[228:231], v[30:33]
	v_mfma_f32_16x16x32_bf16 v[26:29], v[82:85], v[228:231], v[26:29]
	v_mfma_f32_16x16x32_bf16 v[14:17], v[64:67], v[236:239], v[14:17]
	v_mfma_f32_16x16x32_bf16 v[10:13], v[82:85], v[236:239], v[10:13]
	v_mfma_f32_16x16x32_bf16 v[78:81], v[74:77], v[206:209], v[78:81]
	v_mfma_f32_16x16x32_bf16 v[70:73], v[86:89], v[206:209], v[68:71]
	v_mfma_f32_16x16x32_bf16 v[46:49], v[74:77], v[214:217], v[46:49]
	v_mfma_f32_16x16x32_bf16 v[42:45], v[86:89], v[214:217], v[42:45]
	v_mfma_f32_16x16x32_bf16 v[30:33], v[74:77], v[232:235], v[30:33]
	v_mfma_f32_16x16x32_bf16 v[26:29], v[86:89], v[232:235], v[26:29]
	v_mfma_f32_16x16x32_bf16 v[14:17], v[74:77], v[240:243], v[14:17]
	v_mfma_f32_16x16x32_bf16 v[10:13], v[86:89], v[240:243], v[10:13]
	v_mfma_f32_16x16x32_bf16 v[60:63], v[154:157], v[202:205], v[60:63]
	v_mfma_f32_16x16x32_bf16 v[54:57], v[174:177], v[202:205], v[54:57]
	v_mfma_f32_16x16x32_bf16 v[38:41], v[154:157], v[210:213], v[38:41]
	v_mfma_f32_16x16x32_bf16 v[34:37], v[174:177], v[210:213], v[34:37]
	v_mfma_f32_16x16x32_bf16 v[22:25], v[154:157], v[228:231], v[22:25]
	v_mfma_f32_16x16x32_bf16 v[18:21], v[174:177], v[228:231], v[18:21]
	v_mfma_f32_16x16x32_bf16 v[6:9], v[154:157], v[236:239], v[6:9]
	v_mfma_f32_16x16x32_bf16 v[2:5], v[174:177], v[236:239], v[2:5]
	v_mfma_f32_16x16x32_bf16 v[62:65], v[158:161], v[206:209], v[60:63]
	v_mfma_f32_16x16x32_bf16 v[54:57], v[178:181], v[206:209], v[54:57]
	v_mfma_f32_16x16x32_bf16 v[38:41], v[158:161], v[214:217], v[38:41]
	v_mfma_f32_16x16x32_bf16 v[34:37], v[178:181], v[214:217], v[34:37]
	v_mfma_f32_16x16x32_bf16 v[22:25], v[158:161], v[232:235], v[22:25]
	v_mfma_f32_16x16x32_bf16 v[18:21], v[178:181], v[232:235], v[18:21]
	v_mfma_f32_16x16x32_bf16 v[6:9], v[158:161], v[240:243], v[6:9]
	v_mfma_f32_16x16x32_bf16 v[2:5], v[178:181], v[240:243], v[2:5]
	s_barrier
	s_add_u32 s12, s12, 0x100
	s_addc_u32 s13, s13, 0
	s_add_u32 s42, s42, 0x100
	s_addc_u32 s43, s43, 0
	s_cmp_ge_i32 s67, s60
	s_mov_b32 s14, s67
	s_cbranch_scc0 .LBB0_176
	s_movk_i32 s68, 0x4000
	s_movk_i32 s69, 0x6000
	s_mov_b32 s70, 0x18000
	s_mov_b32 s71, 0x3f317217

; #define PG8_STAGE(bufoff, gbase, voff) do { _Pragma("unroll") for (int _i = 0; _i < 2; ++_i) \
;         __builtin_amdgcn_global_load_lds((const unsigned*)((const char*)(gbase) + (voff)[_i]), (PG8_LAS unsigned*)(lds + (bufoff) + ldsw + _i * 8192), 16, 0, 0); } while (0)
; #define PG8_LDA(dst, b, h) do { _Pragma("unroll") for (int m = 0; m < 4; ++m) _Pragma("unroll") for (int k = 0; k < 2; ++k) dst[m][k] = *(const PG8_LAS bf16x8*)(lds + PG8_SA(b, h) + aoff + m * 2048 + k * 1024); } while (0)
; #define PG8_LDB(dst, b, h) do { _Pragma("unroll") for (int n = 0; n < 2; ++n) _Pragma("unroll") for (int k = 0; k < 2; ++k) dst[n][k] = *(const PG8_LAS bf16x8*)(lds + PG8_SB(b, h) + boff + n * 2048 + k * 1024); } while (0)
; #define PG8_MMA(ai, bj, At, Bt) do { __builtin_amdgcn_s_setprio(1); _Pragma("unroll") for (int m = 0; m < 4; ++m) _Pragma("unroll") for (int n = 0; n < 2; ++n) _Pragma("unroll") for (int k = 0; k < 2; ++k) \
;         acc[ai][bj][m][n] = __builtin_amdgcn_mfma_f32_16x16x32_bf16(Bt[n][k], At[m][k], acc[ai][bj][m][n], 0, 0, 0); __builtin_amdgcn_s_setprio(0); } while (0)
; #define PG8_WAIT_V(n) asm volatile("s_waitcnt vmcnt(" #n ")" ::: "memory")
; #define PG8_WAIT_L(n) asm volatile("s_waitcnt lgkmcnt(" #n ")" ::: "memory")
; template <class Epi, class Sched, bool ALIGN_EPI = false, bool SP2 = false>
; __device__ __forceinline__ void gemm_phase(PG8_LAS unsigned char* lds, const Gemm g, const Sched& S, const Epi& E, const int wv) {
;     ...
;             const bool last = (t == nt - 2);
;             const char* a1 = cA + (size_t)(t + 1) * kstep;
;             const char* a2 = last ? nA : cA + (size_t)(t + 2) * kstep; const char* b2 = last ? nB : cB + (size_t)(t + 2) * kstep;
;             const char* a3 = a2 + kstep; const char* b3 = b2 + kstep;
;             if (last && has_next) S.a_ready(nxt);
;             if constexpr (SP2) {
;             PG8_LDB(B0, 0, 0); PG8_LDB(B1, 0, 1); PG8_SCHED; PG8_LDA(At, 0, 0); PG8_STAGE(PG8_SA(1, 1), a1 + hstepA, voffA);
;             PG8_WAIT_V(8); PG8_WAIT_L(0); PG8_BAR; PG8_MMA(0, 0, At, B0); PG8_MMA(0, 1, At, B1); PG8_BAR; PG8_SCHED;
;             PG8_LDA(At, 0, 1); PG8_STAGE(PG8_SB(0, 0), b2, voffB); PG8_STAGE(PG8_SB(0, 1), b2 + hstepB, voffB); PG8_STAGE(PG8_SA(0, 0), a2, voffA);
;             PG8_WAIT_V(8); PG8_WAIT_L(0); PG8_BAR; PG8_MMA(1, 0, At, B0); PG8_MMA(1, 1, At, B1); PG8_BAR; PG8_SCHED;
.LBB0_336:
	s_add_i32 s40, s14, 2
	s_add_u32 s41, s12, 0xfff80080
	s_addc_u32 s15, s13, -1
	s_cmp_eq_u32 s62, s14
	s_cselect_b32 s15, s93, s15
	s_cselect_b32 s14, s92, s41
	s_cselect_b32 s45, s25, s17
	s_cselect_b32 s44, s24, s11
	ds_read_b128 v[26:29], v171
	ds_read_b128 v[30:33], v171 offset:1024
	ds_read_b128 v[42:45], v171 offset:2048
	ds_read_b128 v[46:49], v171 offset:3072
	ds_read_b128 v[146:149], v227
	ds_read_b128 v[150:153], v227 offset:1024
	ds_read_b128 v[154:157], v227 offset:2048
	ds_read_b128 v[158:161], v227 offset:3072
	s_add_i32 m0, s55, 0xc000
	ds_read_b128 v[172:175], v199
	ds_read_b128 v[176:179], v199 offset:1024
	ds_read_b128 v[180:183], v199 offset:2048
	ds_read_b128 v[200:203], v199 offset:3072
	ds_read_b128 v[204:207], v199 offset:4096
	ds_read_b128 v[208:211], v199 offset:5120
	ds_read_b128 v[212:215], v199 offset:6144
	ds_read_b128 v[216:219], v199 offset:7168
	global_load_lds_dwordx4 v168, s[12:13]
	s_add_i32 m0, s55, 0xe000
	s_nop 0
	global_load_lds_dwordx4 v170, s[12:13]
	s_waitcnt vmcnt(8)
	s_waitcnt lgkmcnt(0)
	s_barrier
	v_mfma_f32_16x16x32_bf16 v[138:141], v[26:29], v[172:175], v[138:141]
	v_mfma_f32_16x16x32_bf16 v[142:145], v[42:45], v[172:175], v[142:145]
	v_mfma_f32_16x16x32_bf16 v[126:129], v[26:29], v[180:183], v[126:129]
	v_mfma_f32_16x16x32_bf16 v[122:125], v[42:45], v[180:183], v[122:125]
	v_mfma_f32_16x16x32_bf16 v[110:113], v[26:29], v[204:207], v[110:113]
	v_mfma_f32_16x16x32_bf16 v[106:109], v[42:45], v[204:207], v[106:109]
	v_mfma_f32_16x16x32_bf16 v[94:97], v[26:29], v[212:215], v[94:97]
	v_mfma_f32_16x16x32_bf16 v[90:93], v[42:45], v[212:215], v[90:93]
	v_mfma_f32_16x16x32_bf16 v[138:141], v[30:33], v[176:179], v[138:141]
	v_mfma_f32_16x16x32_bf16 v[142:145], v[46:49], v[176:179], v[142:145]
	v_mfma_f32_16x16x32_bf16 v[126:129], v[30:33], v[200:203], v[126:129]
	v_mfma_f32_16x16x32_bf16 v[122:125], v[46:49], v[200:203], v[122:125]
	v_mfma_f32_16x16x32_bf16 v[110:113], v[30:33], v[208:211], v[110:113]
	v_mfma_f32_16x16x32_bf16 v[106:109], v[46:49], v[208:211], v[106:109]
	v_mfma_f32_16x16x32_bf16 v[94:97], v[30:33], v[216:219], v[94:97]
	v_mfma_f32_16x16x32_bf16 v[90:93], v[46:49], v[216:219], v[90:93]
	v_mfma_f32_16x16x32_bf16 v[134:137], v[146:149], v[172:175], v[134:137]
	v_mfma_f32_16x16x32_bf16 v[130:133], v[154:157], v[172:175], v[130:133]
	v_mfma_f32_16x16x32_bf16 v[118:121], v[146:149], v[180:183], v[118:121]
	v_mfma_f32_16x16x32_bf16 v[114:117], v[154:157], v[180:183], v[114:117]
	v_mfma_f32_16x16x32_bf16 v[102:105], v[146:149], v[204:207], v[102:105]
	v_mfma_f32_16x16x32_bf16 v[98:101], v[154:157], v[204:207], v[98:101]
	v_mfma_f32_16x16x32_bf16 v[86:89], v[146:149], v[212:215], v[86:89]
	v_mfma_f32_16x16x32_bf16 v[82:85], v[154:157], v[212:215], v[82:85]
	v_mfma_f32_16x16x32_bf16 v[134:137], v[150:153], v[176:179], v[134:137]
	v_mfma_f32_16x16x32_bf16 v[130:133], v[158:161], v[176:179], v[130:133]
	v_mfma_f32_16x16x32_bf16 v[118:121], v[150:153], v[200:203], v[118:121]
	v_mfma_f32_16x16x32_bf16 v[114:117], v[158:161], v[200:203], v[114:117]
	v_mfma_f32_16x16x32_bf16 v[102:105], v[150:153], v[208:211], v[102:105]
	v_mfma_f32_16x16x32_bf16 v[98:101], v[158:161], v[208:211], v[98:101]
	v_mfma_f32_16x16x32_bf16 v[86:89], v[150:153], v[216:219], v[86:89]
	v_mfma_f32_16x16x32_bf16 v[82:85], v[158:161], v[216:219], v[82:85]
	s_barrier
	s_add_i32 s65, s54, 0x10000
	v_lshl_add_u64 v[184:185], s[44:45], 0, v[0:1]
	s_mov_b32 m0, s65
	ds_read_b128 v[172:175], v199 offset:16384
	ds_read_b128 v[176:179], v199 offset:17408
	ds_read_b128 v[180:183], v199 offset:18432
	ds_read_b128 v[200:203], v199 offset:19456
	ds_read_b128 v[204:207], v199 offset:20480
	ds_read_b128 v[208:211], v199 offset:21504
	ds_read_b128 v[212:215], v199 offset:22528
	ds_read_b128 v[216:219], v199 offset:23552
	global_load_lds_dwordx4 v[184:185], off
	s_add_i32 m0, s65, 0x2000
	v_lshl_add_u64 v[194:195], s[44:45], 0, v[162:163]
	s_add_u32 s44, s44, s28
	s_addc_u32 s45, s45, s29
	s_add_i32 s41, s54, 0x14000
	global_load_lds_dwordx4 v[194:195], off
	s_mov_b32 m0, s41
	global_load_lds_dwordx4 v0, s[44:45]
	s_add_i32 m0, s41, 0x2000
	v_lshl_add_u64 v[232:233], s[14:15], 0, v[166:167]
	global_load_lds_dwordx4 v162, s[44:45]
	s_mov_b32 m0, s55
	v_lshl_add_u64 v[234:235], s[14:15], 0, v[164:165]
	global_load_lds_dwordx4 v[232:233], off
	s_mov_b32 m0, s56
	s_nop 0
	global_load_lds_dwordx4 v[234:235], off
	s_waitcnt vmcnt(8)
	s_waitcnt lgkmcnt(0)
	s_barrier
	v_mfma_f32_16x16x32_bf16 v[78:81], v[26:29], v[172:175], v[78:81]
	v_mfma_f32_16x16x32_bf16 v[74:77], v[42:45], v[172:175], v[74:77]
	v_mfma_f32_16x16x32_bf16 v[62:65], v[26:29], v[180:183], v[62:65]
	v_mfma_f32_16x16x32_bf16 v[58:61], v[42:45], v[180:183], v[58:61]
	v_mfma_f32_16x16x32_bf16 v[38:41], v[26:29], v[204:207], v[38:41]
	v_mfma_f32_16x16x32_bf16 v[34:37], v[42:45], v[204:207], v[34:37]
	v_mfma_f32_16x16x32_bf16 v[14:17], v[26:29], v[212:215], v[14:17]
	v_mfma_f32_16x16x32_bf16 v[10:13], v[42:45], v[212:215], v[10:13]
	v_mfma_f32_16x16x32_bf16 v[78:81], v[30:33], v[176:179], v[78:81]
	v_mfma_f32_16x16x32_bf16 v[74:77], v[46:49], v[176:179], v[74:77]
	v_mfma_f32_16x16x32_bf16 v[62:65], v[30:33], v[200:203], v[62:65]
	v_mfma_f32_16x16x32_bf16 v[58:61], v[46:49], v[200:203], v[58:61]
	v_mfma_f32_16x16x32_bf16 v[38:41], v[30:33], v[208:211], v[38:41]
	v_mfma_f32_16x16x32_bf16 v[34:37], v[46:49], v[208:211], v[34:37]
	v_mfma_f32_16x16x32_bf16 v[14:17], v[30:33], v[216:219], v[14:17]
	v_mfma_f32_16x16x32_bf16 v[10:13], v[46:49], v[216:219], v[10:13]
	v_mfma_f32_16x16x32_bf16 v[22:25], v[146:149], v[204:207], v[22:25]
	v_mfma_f32_16x16x32_bf16 v[18:21], v[154:157], v[204:207], v[18:21]
	v_mfma_f32_16x16x32_bf16 v[6:9], v[146:149], v[212:215], v[6:9]
	v_mfma_f32_16x16x32_bf16 v[2:5], v[154:157], v[212:215], v[2:5]
	v_mfma_f32_16x16x32_bf16 v[26:29], v[146:149], v[172:175], v[70:73]
	v_mfma_f32_16x16x32_bf16 v[30:33], v[154:157], v[172:175], v[66:69]
	v_mfma_f32_16x16x32_bf16 v[42:45], v[146:149], v[180:183], v[54:57]
	v_mfma_f32_16x16x32_bf16 v[46:49], v[154:157], v[180:183], v[50:53]
	v_mfma_f32_16x16x32_bf16 v[22:25], v[150:153], v[208:211], v[22:25]
	v_mfma_f32_16x16x32_bf16 v[18:21], v[158:161], v[208:211], v[18:21]
	v_mfma_f32_16x16x32_bf16 v[6:9], v[150:153], v[216:219], v[6:9]
	v_mfma_f32_16x16x32_bf16 v[2:5], v[158:161], v[216:219], v[2:5]
	v_mfma_f32_16x16x32_bf16 v[26:29], v[150:153], v[176:179], v[26:29]
	v_mfma_f32_16x16x32_bf16 v[30:33], v[158:161], v[176:179], v[30:33]
	v_mfma_f32_16x16x32_bf16 v[42:45], v[150:153], v[200:203], v[42:45]
	v_mfma_f32_16x16x32_bf16 v[46:49], v[158:161], v[200:203], v[46:49]
	s_barrier
; #define PG8_STAGE(bufoff, gbase, voff) do { _Pragma("unroll") for (int _i = 0; _i < 2; ++_i) \
;         __builtin_amdgcn_global_load_lds((const unsigned*)((const char*)(gbase) + (voff)[_i]), (PG8_LAS unsigned*)(lds + (bufoff) + ldsw + _i * 8192), 16, 0, 0); } while (0)
; #define PG8_LDA(dst, b, h) do { _Pragma("unroll") for (int m = 0; m < 4; ++m) _Pragma("unroll") for (int k = 0; k < 2; ++k) dst[m][k] = *(const PG8_LAS bf16x8*)(lds + PG8_SA(b, h) + aoff + m * 2048 + k * 1024); } while (0)
; #define PG8_LDB(dst, b, h) do { _Pragma("unroll") for (int n = 0; n < 2; ++n) _Pragma("unroll") for (int k = 0; k < 2; ++k) dst[n][k] = *(const PG8_LAS bf16x8*)(lds + PG8_SB(b, h) + boff + n * 2048 + k * 1024); } while (0)
; #define PG8_MMA(ai, bj, At, Bt) do { __builtin_amdgcn_s_setprio(1); _Pragma("unroll") for (int m = 0; m < 4; ++m) _Pragma("unroll") for (int n = 0; n < 2; ++n) _Pragma("unroll") for (int k = 0; k < 2; ++k) \
;         acc[ai][bj][m][n] = __builtin_amdgcn_mfma_f32_16x16x32_bf16(Bt[n][k], At[m][k], acc[ai][bj][m][n], 0, 0, 0); __builtin_amdgcn_s_setprio(0); } while (0)
; #define PG8_WAIT_V(n) asm volatile("s_waitcnt vmcnt(" #n ")" ::: "memory")
; #define PG8_WAIT_L(n) asm volatile("s_waitcnt lgkmcnt(" #n ")" ::: "memory")
; #define PG8_BAR __builtin_amdgcn_s_barrier()
; #define PG8_SCHED __builtin_amdgcn_sched_barrier(0)
; template <class Epi, class Sched, bool ALIGN_EPI = false, bool SP2 = false>
; __device__ __forceinline__ void gemm_phase(PG8_LAS unsigned char* lds, const Gemm g, const Sched& S, const Epi& E, const int wv) {
;     ...
;             PG8_LDB(B0, 1, 0); PG8_LDB(B1, 1, 1); PG8_SCHED; PG8_LDA(At, 1, 0); PG8_STAGE(PG8_SA(0, 1), a2 + hstepA, voffA);
;             PG8_WAIT_V(8); PG8_WAIT_L(0); PG8_BAR; PG8_MMA(0, 0, At, B0); PG8_MMA(0, 1, At, B1); PG8_BAR; PG8_SCHED;
;             PG8_LDA(At, 1, 1); PG8_STAGE(PG8_SB(1, 0), b3, voffB); PG8_STAGE(PG8_SB(1, 1), b3 + hstepB, voffB); PG8_STAGE(PG8_SA(1, 0), a3, voffA);
;             PG8_WAIT_V(8); PG8_WAIT_L(0); PG8_BAR; PG8_MMA(1, 0, At, B0); PG8_MMA(1, 1, At, B1); PG8_BAR; PG8_SCHED;
	ds_read_b128 v[50:53], v244
	ds_read_b128 v[54:57], v244 offset:1024
	ds_read_b128 v[66:69], v244 offset:2048
	ds_read_b128 v[70:73], v244 offset:3072
	ds_read_b128 v[146:149], v245
	ds_read_b128 v[150:153], v245 offset:1024
	ds_read_b128 v[154:157], v245 offset:2048
	ds_read_b128 v[158:161], v245 offset:3072
	s_add_u32 s14, s14, 0x80000
	s_addc_u32 s15, s15, 0
	s_mov_b32 m0, s57
	ds_read_b128 v[172:175], v199 offset:32768
	ds_read_b128 v[176:179], v199 offset:33792
	ds_read_b128 v[180:183], v199 offset:34816
	ds_read_b128 v[200:203], v199 offset:35840
	ds_read_b128 v[204:207], v199 offset:36864
	ds_read_b128 v[208:211], v199 offset:37888
	ds_read_b128 v[212:215], v199 offset:38912
	ds_read_b128 v[216:219], v199 offset:39936
	global_load_lds_dwordx4 v166, s[14:15]
	s_mov_b32 m0, s58
	s_nop 0
	global_load_lds_dwordx4 v164, s[14:15]
	s_waitcnt vmcnt(8)
	s_waitcnt lgkmcnt(0)
	s_barrier
	v_mfma_f32_16x16x32_bf16 v[138:141], v[50:53], v[172:175], v[138:141]
	v_mfma_f32_16x16x32_bf16 v[142:145], v[66:69], v[172:175], v[142:145]
	v_mfma_f32_16x16x32_bf16 v[126:129], v[50:53], v[180:183], v[126:129]
	v_mfma_f32_16x16x32_bf16 v[122:125], v[66:69], v[180:183], v[122:125]
	v_mfma_f32_16x16x32_bf16 v[110:113], v[50:53], v[204:207], v[110:113]
	v_mfma_f32_16x16x32_bf16 v[106:109], v[66:69], v[204:207], v[106:109]
	v_mfma_f32_16x16x32_bf16 v[94:97], v[50:53], v[212:215], v[94:97]
	v_mfma_f32_16x16x32_bf16 v[90:93], v[66:69], v[212:215], v[90:93]
	v_mfma_f32_16x16x32_bf16 v[138:141], v[54:57], v[176:179], v[138:141]
	v_mfma_f32_16x16x32_bf16 v[142:145], v[70:73], v[176:179], v[142:145]
	v_mfma_f32_16x16x32_bf16 v[126:129], v[54:57], v[200:203], v[126:129]
	v_mfma_f32_16x16x32_bf16 v[122:125], v[70:73], v[200:203], v[122:125]
	v_mfma_f32_16x16x32_bf16 v[110:113], v[54:57], v[208:211], v[110:113]
	v_mfma_f32_16x16x32_bf16 v[106:109], v[70:73], v[208:211], v[106:109]
	v_mfma_f32_16x16x32_bf16 v[94:97], v[54:57], v[216:219], v[94:97]
	v_mfma_f32_16x16x32_bf16 v[90:93], v[70:73], v[216:219], v[90:93]
	v_mfma_f32_16x16x32_bf16 v[134:137], v[146:149], v[172:175], v[134:137]
	v_mfma_f32_16x16x32_bf16 v[130:133], v[154:157], v[172:175], v[130:133]
	v_mfma_f32_16x16x32_bf16 v[118:121], v[146:149], v[180:183], v[118:121]
	v_mfma_f32_16x16x32_bf16 v[114:117], v[154:157], v[180:183], v[114:117]
	v_mfma_f32_16x16x32_bf16 v[102:105], v[146:149], v[204:207], v[102:105]
	v_mfma_f32_16x16x32_bf16 v[98:101], v[154:157], v[204:207], v[98:101]
	v_mfma_f32_16x16x32_bf16 v[86:89], v[146:149], v[212:215], v[86:89]
	v_mfma_f32_16x16x32_bf16 v[82:85], v[154:157], v[212:215], v[82:85]
	v_mfma_f32_16x16x32_bf16 v[134:137], v[150:153], v[176:179], v[134:137]
	v_mfma_f32_16x16x32_bf16 v[130:133], v[158:161], v[176:179], v[130:133]
	v_mfma_f32_16x16x32_bf16 v[118:121], v[150:153], v[200:203], v[118:121]
	v_mfma_f32_16x16x32_bf16 v[114:117], v[158:161], v[200:203], v[114:117]
	v_mfma_f32_16x16x32_bf16 v[102:105], v[150:153], v[208:211], v[102:105]
	v_mfma_f32_16x16x32_bf16 v[98:101], v[158:161], v[208:211], v[98:101]
	v_mfma_f32_16x16x32_bf16 v[86:89], v[150:153], v[216:219], v[86:89]
	v_mfma_f32_16x16x32_bf16 v[82:85], v[158:161], v[216:219], v[82:85]
	s_barrier
	s_add_i32 s14, s54, 0x18000
	s_add_i32 m0, s14, 0xffffff80
	ds_read_b128 v[172:175], v199 offset:49152
	ds_read_b128 v[176:179], v199 offset:50176
	ds_read_b128 v[180:183], v199 offset:51200
	ds_read_b128 v[200:203], v199 offset:52224
	ds_read_b128 v[204:207], v199 offset:53248
	ds_read_b128 v[208:211], v199 offset:54272
	ds_read_b128 v[212:215], v199 offset:55296
	ds_read_b128 v[216:219], v199 offset:56320
	global_load_lds_dwordx4 v[184:185], off offset:128
	s_add_i32 m0, s14, 0x1f80
	s_add_i32 s14, s54, 0x1c000
	global_load_lds_dwordx4 v[194:195], off offset:128
	s_add_i32 m0, s14, 0xffffff80
	s_nop 0
	global_load_lds_dwordx4 v0, s[44:45] offset:128
	s_add_i32 m0, s14, 0x1f80
	s_nop 0
	global_load_lds_dwordx4 v162, s[44:45] offset:128
	s_add_i32 m0, s60, 0xffffff80
	s_nop 0
	global_load_lds_dwordx4 v[232:233], off offset:128
	s_add_i32 m0, s61, 0xffffff80
	s_nop 0
	global_load_lds_dwordx4 v[234:235], off offset:128
	s_waitcnt vmcnt(8)
	s_waitcnt lgkmcnt(0)
	s_barrier
	v_mfma_f32_16x16x32_bf16 v[78:81], v[50:53], v[172:175], v[78:81]
	v_mfma_f32_16x16x32_bf16 v[74:77], v[66:69], v[172:175], v[74:77]
	v_mfma_f32_16x16x32_bf16 v[62:65], v[50:53], v[180:183], v[62:65]
	v_mfma_f32_16x16x32_bf16 v[58:61], v[66:69], v[180:183], v[58:61]
	v_mfma_f32_16x16x32_bf16 v[38:41], v[50:53], v[204:207], v[38:41]
	v_mfma_f32_16x16x32_bf16 v[34:37], v[66:69], v[204:207], v[34:37]
	v_mfma_f32_16x16x32_bf16 v[14:17], v[50:53], v[212:215], v[14:17]
	v_mfma_f32_16x16x32_bf16 v[10:13], v[66:69], v[212:215], v[10:13]
	v_mfma_f32_16x16x32_bf16 v[78:81], v[54:57], v[176:179], v[78:81]
	v_mfma_f32_16x16x32_bf16 v[74:77], v[70:73], v[176:179], v[74:77]
	v_mfma_f32_16x16x32_bf16 v[62:65], v[54:57], v[200:203], v[62:65]
	v_mfma_f32_16x16x32_bf16 v[58:61], v[70:73], v[200:203], v[58:61]
	v_mfma_f32_16x16x32_bf16 v[38:41], v[54:57], v[208:211], v[38:41]
	v_mfma_f32_16x16x32_bf16 v[34:37], v[70:73], v[208:211], v[34:37]
	v_mfma_f32_16x16x32_bf16 v[14:17], v[54:57], v[216:219], v[14:17]
	v_mfma_f32_16x16x32_bf16 v[10:13], v[70:73], v[216:219], v[10:13]
	v_mfma_f32_16x16x32_bf16 v[26:29], v[146:149], v[172:175], v[26:29]
	v_mfma_f32_16x16x32_bf16 v[70:73], v[150:153], v[176:179], v[26:29]
	v_mfma_f32_16x16x32_bf16 v[26:29], v[154:157], v[172:175], v[30:33]
	v_mfma_f32_16x16x32_bf16 v[66:69], v[158:161], v[176:179], v[26:29]
	v_mfma_f32_16x16x32_bf16 v[26:29], v[146:149], v[180:183], v[42:45]
	v_mfma_f32_16x16x32_bf16 v[54:57], v[150:153], v[200:203], v[26:29]
	v_mfma_f32_16x16x32_bf16 v[26:29], v[154:157], v[180:183], v[46:49]
	v_mfma_f32_16x16x32_bf16 v[22:25], v[146:149], v[204:207], v[22:25]
	v_mfma_f32_16x16x32_bf16 v[18:21], v[154:157], v[204:207], v[18:21]
	v_mfma_f32_16x16x32_bf16 v[6:9], v[146:149], v[212:215], v[6:9]
	v_mfma_f32_16x16x32_bf16 v[2:5], v[154:157], v[212:215], v[2:5]
	v_mfma_f32_16x16x32_bf16 v[50:53], v[158:161], v[200:203], v[26:29]
	v_mfma_f32_16x16x32_bf16 v[22:25], v[150:153], v[208:211], v[22:25]
	v_mfma_f32_16x16x32_bf16 v[18:21], v[158:161], v[208:211], v[18:21]
	v_mfma_f32_16x16x32_bf16 v[6:9], v[150:153], v[216:219], v[6:9]
	v_mfma_f32_16x16x32_bf16 v[2:5], v[158:161], v[216:219], v[2:5]
	s_barrier
	s_add_u32 s12, s12, 0x100
	s_addc_u32 s13, s13, 0
	s_add_u32 s11, s11, 0x100
	s_addc_u32 s17, s17, 0
	s_cmp_ge_i32 s40, s59
	s_mov_b32 s14, s40
	s_cbranch_scc0 .LBB0_336

; #define PG8_STAGE(bufoff, gbase, voff) do { _Pragma("unroll") for (int _i = 0; _i < 2; ++_i) \
;         __builtin_amdgcn_global_load_lds((const unsigned*)((const char*)(gbase) + (voff)[_i]), (PG8_LAS unsigned*)(lds + (bufoff) + ldsw + _i * 8192), 16, 0, 0); } while (0)
; #define PG8_LDA(dst, b, h) do { _Pragma("unroll") for (int m = 0; m < 4; ++m) _Pragma("unroll") for (int k = 0; k < 2; ++k) dst[m][k] = *(const PG8_LAS bf16x8*)(lds + PG8_SA(b, h) + aoff + m * 2048 + k * 1024); } while (0)
; #define PG8_LDB(dst, b, h) do { _Pragma("unroll") for (int n = 0; n < 2; ++n) _Pragma("unroll") for (int k = 0; k < 2; ++k) dst[n][k] = *(const PG8_LAS bf16x8*)(lds + PG8_SB(b, h) + boff + n * 2048 + k * 1024); } while (0)
; #define PG8_MMA(ai, bj, At, Bt) do { __builtin_amdgcn_s_setprio(1); _Pragma("unroll") for (int m = 0; m < 4; ++m) _Pragma("unroll") for (int n = 0; n < 2; ++n) _Pragma("unroll") for (int k = 0; k < 2; ++k) \
;         acc[ai][bj][m][n] = __builtin_amdgcn_mfma_f32_16x16x32_bf16(Bt[n][k], At[m][k], acc[ai][bj][m][n], 0, 0, 0); __builtin_amdgcn_s_setprio(0); } while (0)
; #define PG8_WAIT_V(n) asm volatile("s_waitcnt vmcnt(" #n ")" ::: "memory")
; #define PG8_WAIT_L(n) asm volatile("s_waitcnt lgkmcnt(" #n ")" ::: "memory")
; template <class Epi, class Sched, bool ALIGN_EPI = false, bool SP2 = false>
; __device__ __forceinline__ void gemm_phase(PG8_LAS unsigned char* lds, const Gemm g, const Sched& S, const Epi& E, const int wv) {
;     ...
;             const bool last = (t == nt - 2);
;             const char* a1 = cA + (size_t)(t + 1) * kstep;
;             const char* a2 = last ? nA : cA + (size_t)(t + 2) * kstep; const char* b2 = last ? nB : cB + (size_t)(t + 2) * kstep;
;             const char* a3 = a2 + kstep; const char* b3 = b2 + kstep;
;             if (last && has_next) S.a_ready(nxt);
;             if constexpr (SP2) {
;             PG8_LDB(B0, 0, 0); PG8_LDB(B1, 0, 1); PG8_SCHED; PG8_LDA(At, 0, 0); PG8_STAGE(PG8_SA(1, 1), a1 + hstepA, voffA);
;             PG8_WAIT_V(8); PG8_WAIT_L(0); PG8_BAR; PG8_MMA(0, 0, At, B0); PG8_MMA(0, 1, At, B1); PG8_BAR; PG8_SCHED;
;             PG8_LDA(At, 0, 1); PG8_STAGE(PG8_SB(0, 0), b2, voffB); PG8_STAGE(PG8_SB(0, 1), b2 + hstepB, voffB); PG8_STAGE(PG8_SA(0, 0), a2, voffA);
;             PG8_WAIT_V(8); PG8_WAIT_L(0); PG8_BAR; PG8_MMA(1, 0, At, B0); PG8_MMA(1, 1, At, B1); PG8_BAR; PG8_SCHED;
.LBB0_699:
	s_add_i32 s72, s54, 2
	s_add_u32 s73, s44, 0xfff80080
	s_addc_u32 s55, s45, -1
	s_cmp_eq_u32 s66, s54
	s_cselect_b32 s55, s31, s55
	s_cselect_b32 s54, s71, s73
	s_cselect_b32 s75, s13, s57
	s_cselect_b32 s74, s12, s56
	ds_read_b128 v[126:129], v190
	ds_read_b128 v[138:141], v190 offset:1024
	ds_read_b128 v[142:145], v190 offset:2048
	ds_read_b128 v[146:149], v190 offset:3072
	ds_read_b128 v[150:153], v191
	ds_read_b128 v[154:157], v191 offset:1024
	ds_read_b128 v[158:161], v191 offset:2048
	ds_read_b128 v[162:165], v191 offset:3072
	s_add_i32 m0, s59, 0xc000
	ds_read_b128 v[166:169], v235
	ds_read_b128 v[170:173], v235 offset:1024
	ds_read_b128 v[174:177], v235 offset:2048
	ds_read_b128 v[178:181], v235 offset:3072
	ds_read_b128 v[182:185], v235 offset:4096
	ds_read_b128 v[204:207], v235 offset:5120
	ds_read_b128 v[208:211], v235 offset:6144
	ds_read_b128 v[212:215], v235 offset:7168
	global_load_lds_dwordx4 v200, s[44:45]
	s_add_i32 m0, s59, 0xe000
	s_nop 0
	global_load_lds_dwordx4 v202, s[44:45]
	s_waitcnt vmcnt(8)
	s_waitcnt lgkmcnt(0)
	s_barrier
	v_mfma_f32_16x16x32_bf16 v[134:137], v[126:129], v[166:169], v[134:137]
	v_mfma_f32_16x16x32_bf16 v[130:133], v[142:145], v[166:169], v[130:133]
	v_mfma_f32_16x16x32_bf16 v[110:113], v[126:129], v[174:177], v[110:113]
	v_mfma_f32_16x16x32_bf16 v[106:109], v[142:145], v[174:177], v[106:109]
	v_mfma_f32_16x16x32_bf16 v[94:97], v[126:129], v[182:185], v[94:97]
	v_mfma_f32_16x16x32_bf16 v[90:93], v[142:145], v[182:185], v[90:93]
	v_mfma_f32_16x16x32_bf16 v[78:81], v[126:129], v[208:211], v[78:81]
	v_mfma_f32_16x16x32_bf16 v[74:77], v[142:145], v[208:211], v[74:77]
	v_mfma_f32_16x16x32_bf16 v[134:137], v[138:141], v[170:173], v[134:137]
	v_mfma_f32_16x16x32_bf16 v[130:133], v[146:149], v[170:173], v[130:133]
	v_mfma_f32_16x16x32_bf16 v[110:113], v[138:141], v[178:181], v[110:113]
	v_mfma_f32_16x16x32_bf16 v[106:109], v[146:149], v[178:181], v[106:109]
	v_mfma_f32_16x16x32_bf16 v[94:97], v[138:141], v[204:207], v[94:97]
	v_mfma_f32_16x16x32_bf16 v[90:93], v[146:149], v[204:207], v[90:93]
	v_mfma_f32_16x16x32_bf16 v[78:81], v[138:141], v[212:215], v[78:81]
	v_mfma_f32_16x16x32_bf16 v[74:77], v[146:149], v[212:215], v[74:77]
	v_mfma_f32_16x16x32_bf16 v[122:125], v[150:153], v[166:169], v[122:125]
	v_mfma_f32_16x16x32_bf16 v[116:119], v[158:161], v[166:169], v[118:121]
	v_mfma_f32_16x16x32_bf16 v[102:105], v[150:153], v[174:177], v[102:105]
	v_mfma_f32_16x16x32_bf16 v[98:101], v[158:161], v[174:177], v[98:101]
	v_mfma_f32_16x16x32_bf16 v[86:89], v[150:153], v[182:185], v[86:89]
	v_mfma_f32_16x16x32_bf16 v[82:85], v[158:161], v[182:185], v[82:85]
	v_mfma_f32_16x16x32_bf16 v[70:73], v[150:153], v[208:211], v[70:73]
	v_mfma_f32_16x16x32_bf16 v[66:69], v[158:161], v[208:211], v[66:69]
	v_mfma_f32_16x16x32_bf16 v[122:125], v[154:157], v[170:173], v[122:125]
	v_mfma_f32_16x16x32_bf16 v[116:119], v[162:165], v[170:173], v[116:119]
	v_mfma_f32_16x16x32_bf16 v[102:105], v[154:157], v[178:181], v[102:105]
	v_mfma_f32_16x16x32_bf16 v[98:101], v[162:165], v[178:181], v[98:101]
	v_mfma_f32_16x16x32_bf16 v[86:89], v[154:157], v[204:207], v[86:89]
	v_mfma_f32_16x16x32_bf16 v[82:85], v[162:165], v[204:207], v[82:85]
	v_mfma_f32_16x16x32_bf16 v[70:73], v[154:157], v[212:215], v[70:73]
	v_mfma_f32_16x16x32_bf16 v[66:69], v[162:165], v[212:215], v[66:69]
	s_barrier
	s_add_i32 s76, s53, 0x10000
	v_lshl_add_u64 v[216:217], s[74:75], 0, v[0:1]
	s_mov_b32 m0, s76
	ds_read_b128 v[166:169], v235 offset:16384
	ds_read_b128 v[170:173], v235 offset:17408
	ds_read_b128 v[174:177], v235 offset:18432
	ds_read_b128 v[178:181], v235 offset:19456
	ds_read_b128 v[182:185], v235 offset:20480
	ds_read_b128 v[204:207], v235 offset:21504
	ds_read_b128 v[208:211], v235 offset:22528
	ds_read_b128 v[212:215], v235 offset:23552
	global_load_lds_dwordx4 v[216:217], off
	s_add_i32 m0, s76, 0x2000
	v_lshl_add_u64 v[218:219], s[74:75], 0, v[198:199]
	s_add_u32 s74, s74, s34
	s_addc_u32 s75, s75, s35
	s_add_i32 s73, s53, 0x14000
	global_load_lds_dwordx4 v[218:219], off
	s_mov_b32 m0, s73
	global_load_lds_dwordx4 v0, s[74:75]
	s_add_i32 m0, s73, 0x2000
	v_lshl_add_u64 v[240:241], s[54:55], 0, v[194:195]
	global_load_lds_dwordx4 v198, s[74:75]
	s_mov_b32 m0, s59
	v_lshl_add_u64 v[242:243], s[54:55], 0, v[196:197]
	global_load_lds_dwordx4 v[240:241], off
	s_mov_b32 m0, s60
	s_nop 0
	global_load_lds_dwordx4 v[242:243], off
	s_waitcnt vmcnt(8)
	s_waitcnt lgkmcnt(0)
	s_barrier
	v_mfma_f32_16x16x32_bf16 v[62:65], v[126:129], v[166:169], v[62:65]
	v_mfma_f32_16x16x32_bf16 v[58:61], v[142:145], v[166:169], v[58:61]
	v_mfma_f32_16x16x32_bf16 v[46:49], v[126:129], v[174:177], v[46:49]
	v_mfma_f32_16x16x32_bf16 v[42:45], v[142:145], v[174:177], v[42:45]
	v_mfma_f32_16x16x32_bf16 v[30:33], v[126:129], v[182:185], v[30:33]
	v_mfma_f32_16x16x32_bf16 v[26:29], v[142:145], v[182:185], v[26:29]
	v_mfma_f32_16x16x32_bf16 v[14:17], v[126:129], v[208:211], v[14:17]
	v_mfma_f32_16x16x32_bf16 v[10:13], v[142:145], v[208:211], v[10:13]
	v_mfma_f32_16x16x32_bf16 v[62:65], v[138:141], v[170:173], v[62:65]
	v_mfma_f32_16x16x32_bf16 v[58:61], v[146:149], v[170:173], v[58:61]
	v_mfma_f32_16x16x32_bf16 v[46:49], v[138:141], v[178:181], v[46:49]
	v_mfma_f32_16x16x32_bf16 v[42:45], v[146:149], v[178:181], v[42:45]
	v_mfma_f32_16x16x32_bf16 v[30:33], v[138:141], v[204:207], v[30:33]
	v_mfma_f32_16x16x32_bf16 v[26:29], v[146:149], v[204:207], v[26:29]
	v_mfma_f32_16x16x32_bf16 v[14:17], v[138:141], v[212:215], v[14:17]
	v_mfma_f32_16x16x32_bf16 v[10:13], v[146:149], v[212:215], v[10:13]
	v_mfma_f32_16x16x32_bf16 v[54:57], v[150:153], v[166:169], v[54:57]
	v_mfma_f32_16x16x32_bf16 v[50:53], v[158:161], v[166:169], v[50:53]
	v_mfma_f32_16x16x32_bf16 v[38:41], v[150:153], v[174:177], v[38:41]
	v_mfma_f32_16x16x32_bf16 v[34:37], v[158:161], v[174:177], v[34:37]
	v_mfma_f32_16x16x32_bf16 v[22:25], v[150:153], v[182:185], v[22:25]
	v_mfma_f32_16x16x32_bf16 v[18:21], v[158:161], v[182:185], v[18:21]
	v_mfma_f32_16x16x32_bf16 v[6:9], v[150:153], v[208:211], v[6:9]
	v_mfma_f32_16x16x32_bf16 v[2:5], v[158:161], v[208:211], v[2:5]
	v_mfma_f32_16x16x32_bf16 v[54:57], v[154:157], v[170:173], v[54:57]
	v_mfma_f32_16x16x32_bf16 v[50:53], v[162:165], v[170:173], v[50:53]
	v_mfma_f32_16x16x32_bf16 v[38:41], v[154:157], v[178:181], v[38:41]
	v_mfma_f32_16x16x32_bf16 v[34:37], v[162:165], v[178:181], v[34:37]
	v_mfma_f32_16x16x32_bf16 v[22:25], v[154:157], v[204:207], v[22:25]
	v_mfma_f32_16x16x32_bf16 v[18:21], v[162:165], v[204:207], v[18:21]
	v_mfma_f32_16x16x32_bf16 v[6:9], v[154:157], v[212:215], v[6:9]
	v_mfma_f32_16x16x32_bf16 v[2:5], v[162:165], v[212:215], v[2:5]
	s_barrier
; #define PG8_STAGE(bufoff, gbase, voff) do { _Pragma("unroll") for (int _i = 0; _i < 2; ++_i) \
;         __builtin_amdgcn_global_load_lds((const unsigned*)((const char*)(gbase) + (voff)[_i]), (PG8_LAS unsigned*)(lds + (bufoff) + ldsw + _i * 8192), 16, 0, 0); } while (0)
; #define PG8_LDA(dst, b, h) do { _Pragma("unroll") for (int m = 0; m < 4; ++m) _Pragma("unroll") for (int k = 0; k < 2; ++k) dst[m][k] = *(const PG8_LAS bf16x8*)(lds + PG8_SA(b, h) + aoff + m * 2048 + k * 1024); } while (0)
; #define PG8_LDB(dst, b, h) do { _Pragma("unroll") for (int n = 0; n < 2; ++n) _Pragma("unroll") for (int k = 0; k < 2; ++k) dst[n][k] = *(const PG8_LAS bf16x8*)(lds + PG8_SB(b, h) + boff + n * 2048 + k * 1024); } while (0)
; #define PG8_MMA(ai, bj, At, Bt) do { __builtin_amdgcn_s_setprio(1); _Pragma("unroll") for (int m = 0; m < 4; ++m) _Pragma("unroll") for (int n = 0; n < 2; ++n) _Pragma("unroll") for (int k = 0; k < 2; ++k) \
;         acc[ai][bj][m][n] = __builtin_amdgcn_mfma_f32_16x16x32_bf16(Bt[n][k], At[m][k], acc[ai][bj][m][n], 0, 0, 0); __builtin_amdgcn_s_setprio(0); } while (0)
; #define PG8_WAIT_V(n) asm volatile("s_waitcnt vmcnt(" #n ")" ::: "memory")
; #define PG8_WAIT_L(n) asm volatile("s_waitcnt lgkmcnt(" #n ")" ::: "memory")
; #define PG8_BAR __builtin_amdgcn_s_barrier()
; #define PG8_SCHED __builtin_amdgcn_sched_barrier(0)
; template <class Epi, class Sched, bool ALIGN_EPI = false, bool SP2 = false>
; __device__ __forceinline__ void gemm_phase(PG8_LAS unsigned char* lds, const Gemm g, const Sched& S, const Epi& E, const int wv) {
;     ...
;             PG8_LDB(B0, 1, 0); PG8_LDB(B1, 1, 1); PG8_SCHED; PG8_LDA(At, 1, 0); PG8_STAGE(PG8_SA(0, 1), a2 + hstepA, voffA);
;             PG8_WAIT_V(8); PG8_WAIT_L(0); PG8_BAR; PG8_MMA(0, 0, At, B0); PG8_MMA(0, 1, At, B1); PG8_BAR; PG8_SCHED;
;             PG8_LDA(At, 1, 1); PG8_STAGE(PG8_SB(1, 0), b3, voffB); PG8_STAGE(PG8_SB(1, 1), b3 + hstepB, voffB); PG8_STAGE(PG8_SA(1, 0), a3, voffA);
;             PG8_WAIT_V(8); PG8_WAIT_L(0); PG8_BAR; PG8_MMA(1, 0, At, B0); PG8_MMA(1, 1, At, B1); PG8_BAR; PG8_SCHED;
	ds_read_b128 v[126:129], v192
	ds_read_b128 v[138:141], v192 offset:1024
	ds_read_b128 v[142:145], v192 offset:2048
	ds_read_b128 v[146:149], v192 offset:3072
	ds_read_b128 v[150:153], v193
	ds_read_b128 v[154:157], v193 offset:1024
	ds_read_b128 v[158:161], v193 offset:2048
	ds_read_b128 v[162:165], v193 offset:3072
	s_add_u32 s54, s54, 0x80000
	s_addc_u32 s55, s55, 0
	s_mov_b32 m0, s61
	ds_read_b128 v[166:169], v235 offset:32768
	ds_read_b128 v[170:173], v235 offset:33792
	ds_read_b128 v[174:177], v235 offset:34816
	ds_read_b128 v[178:181], v235 offset:35840
	ds_read_b128 v[182:185], v235 offset:36864
	ds_read_b128 v[204:207], v235 offset:37888
	ds_read_b128 v[208:211], v235 offset:38912
	ds_read_b128 v[212:215], v235 offset:39936
	global_load_lds_dwordx4 v194, s[54:55]
	s_mov_b32 m0, s62
	s_nop 0
	global_load_lds_dwordx4 v196, s[54:55]
	s_waitcnt vmcnt(8)
	s_waitcnt lgkmcnt(0)
	s_barrier
	v_mfma_f32_16x16x32_bf16 v[134:137], v[126:129], v[166:169], v[134:137]
	v_mfma_f32_16x16x32_bf16 v[130:133], v[142:145], v[166:169], v[130:133]
	v_mfma_f32_16x16x32_bf16 v[110:113], v[126:129], v[174:177], v[110:113]
	v_mfma_f32_16x16x32_bf16 v[106:109], v[142:145], v[174:177], v[106:109]
	v_mfma_f32_16x16x32_bf16 v[94:97], v[126:129], v[182:185], v[94:97]
	v_mfma_f32_16x16x32_bf16 v[90:93], v[142:145], v[182:185], v[90:93]
	v_mfma_f32_16x16x32_bf16 v[78:81], v[126:129], v[208:211], v[78:81]
	v_mfma_f32_16x16x32_bf16 v[74:77], v[142:145], v[208:211], v[74:77]
	v_mfma_f32_16x16x32_bf16 v[134:137], v[138:141], v[170:173], v[134:137]
	v_mfma_f32_16x16x32_bf16 v[130:133], v[146:149], v[170:173], v[130:133]
	v_mfma_f32_16x16x32_bf16 v[110:113], v[138:141], v[178:181], v[110:113]
	v_mfma_f32_16x16x32_bf16 v[106:109], v[146:149], v[178:181], v[106:109]
	v_mfma_f32_16x16x32_bf16 v[94:97], v[138:141], v[204:207], v[94:97]
	v_mfma_f32_16x16x32_bf16 v[90:93], v[146:149], v[204:207], v[90:93]
	v_mfma_f32_16x16x32_bf16 v[78:81], v[138:141], v[212:215], v[78:81]
	v_mfma_f32_16x16x32_bf16 v[74:77], v[146:149], v[212:215], v[74:77]
	v_mfma_f32_16x16x32_bf16 v[120:123], v[150:153], v[166:169], v[122:125]
	v_mfma_f32_16x16x32_bf16 v[116:119], v[158:161], v[166:169], v[116:119]
	v_mfma_f32_16x16x32_bf16 v[102:105], v[150:153], v[174:177], v[102:105]
	v_mfma_f32_16x16x32_bf16 v[98:101], v[158:161], v[174:177], v[98:101]
	v_mfma_f32_16x16x32_bf16 v[86:89], v[150:153], v[182:185], v[86:89]
	v_mfma_f32_16x16x32_bf16 v[82:85], v[158:161], v[182:185], v[82:85]
	v_mfma_f32_16x16x32_bf16 v[70:73], v[150:153], v[208:211], v[70:73]
	v_mfma_f32_16x16x32_bf16 v[66:69], v[158:161], v[208:211], v[66:69]
	v_mfma_f32_16x16x32_bf16 v[122:125], v[154:157], v[170:173], v[120:123]
	v_mfma_f32_16x16x32_bf16 v[118:121], v[162:165], v[170:173], v[116:119]
	v_mfma_f32_16x16x32_bf16 v[102:105], v[154:157], v[178:181], v[102:105]
	v_mfma_f32_16x16x32_bf16 v[98:101], v[162:165], v[178:181], v[98:101]
	v_mfma_f32_16x16x32_bf16 v[86:89], v[154:157], v[204:207], v[86:89]
	v_mfma_f32_16x16x32_bf16 v[82:85], v[162:165], v[204:207], v[82:85]
	v_mfma_f32_16x16x32_bf16 v[70:73], v[154:157], v[212:215], v[70:73]
	v_mfma_f32_16x16x32_bf16 v[66:69], v[162:165], v[212:215], v[66:69]
	s_barrier
	s_add_i32 s54, s53, 0x18000
	s_add_i32 m0, s54, 0xffffff80
	ds_read_b128 v[166:169], v235 offset:49152
	ds_read_b128 v[170:173], v235 offset:50176
	ds_read_b128 v[174:177], v235 offset:51200
	ds_read_b128 v[178:181], v235 offset:52224
	ds_read_b128 v[182:185], v235 offset:53248
	ds_read_b128 v[204:207], v235 offset:54272
	ds_read_b128 v[208:211], v235 offset:55296
	ds_read_b128 v[212:215], v235 offset:56320
	global_load_lds_dwordx4 v[216:217], off offset:128
	s_add_i32 m0, s54, 0x1f80
	s_add_i32 s54, s53, 0x1c000
	global_load_lds_dwordx4 v[218:219], off offset:128
	s_add_i32 m0, s54, 0xffffff80
	s_nop 0
	global_load_lds_dwordx4 v0, s[74:75] offset:128
	s_add_i32 m0, s54, 0x1f80
	s_nop 0
	global_load_lds_dwordx4 v198, s[74:75] offset:128
	s_add_i32 m0, s64, 0xffffff80
	s_nop 0
	global_load_lds_dwordx4 v[240:241], off offset:128
	s_add_i32 m0, s65, 0xffffff80
	s_nop 0
	global_load_lds_dwordx4 v[242:243], off offset:128
	s_waitcnt vmcnt(8)
	s_waitcnt lgkmcnt(0)
	s_barrier
	v_mfma_f32_16x16x32_bf16 v[62:65], v[126:129], v[166:169], v[62:65]
	v_mfma_f32_16x16x32_bf16 v[58:61], v[142:145], v[166:169], v[58:61]
	v_mfma_f32_16x16x32_bf16 v[46:49], v[126:129], v[174:177], v[46:49]
	v_mfma_f32_16x16x32_bf16 v[42:45], v[142:145], v[174:177], v[42:45]
	v_mfma_f32_16x16x32_bf16 v[30:33], v[126:129], v[182:185], v[30:33]
	v_mfma_f32_16x16x32_bf16 v[26:29], v[142:145], v[182:185], v[26:29]
	v_mfma_f32_16x16x32_bf16 v[14:17], v[126:129], v[208:211], v[14:17]
	v_mfma_f32_16x16x32_bf16 v[10:13], v[142:145], v[208:211], v[10:13]
	v_mfma_f32_16x16x32_bf16 v[62:65], v[138:141], v[170:173], v[62:65]
	v_mfma_f32_16x16x32_bf16 v[58:61], v[146:149], v[170:173], v[58:61]
	v_mfma_f32_16x16x32_bf16 v[46:49], v[138:141], v[178:181], v[46:49]
	v_mfma_f32_16x16x32_bf16 v[42:45], v[146:149], v[178:181], v[42:45]
	v_mfma_f32_16x16x32_bf16 v[30:33], v[138:141], v[204:207], v[30:33]
	v_mfma_f32_16x16x32_bf16 v[26:29], v[146:149], v[204:207], v[26:29]
	v_mfma_f32_16x16x32_bf16 v[14:17], v[138:141], v[212:215], v[14:17]
	v_mfma_f32_16x16x32_bf16 v[10:13], v[146:149], v[212:215], v[10:13]
	v_mfma_f32_16x16x32_bf16 v[54:57], v[150:153], v[166:169], v[54:57]
	v_mfma_f32_16x16x32_bf16 v[50:53], v[158:161], v[166:169], v[50:53]
	v_mfma_f32_16x16x32_bf16 v[38:41], v[150:153], v[174:177], v[38:41]
	v_mfma_f32_16x16x32_bf16 v[34:37], v[158:161], v[174:177], v[34:37]
	v_mfma_f32_16x16x32_bf16 v[22:25], v[150:153], v[182:185], v[22:25]
	v_mfma_f32_16x16x32_bf16 v[18:21], v[158:161], v[182:185], v[18:21]
	v_mfma_f32_16x16x32_bf16 v[6:9], v[150:153], v[208:211], v[6:9]
	v_mfma_f32_16x16x32_bf16 v[2:5], v[158:161], v[208:211], v[2:5]
	v_mfma_f32_16x16x32_bf16 v[54:57], v[154:157], v[170:173], v[54:57]
	v_mfma_f32_16x16x32_bf16 v[50:53], v[162:165], v[170:173], v[50:53]
	v_mfma_f32_16x16x32_bf16 v[38:41], v[154:157], v[178:181], v[38:41]
	v_mfma_f32_16x16x32_bf16 v[34:37], v[162:165], v[178:181], v[34:37]
	v_mfma_f32_16x16x32_bf16 v[22:25], v[154:157], v[204:207], v[22:25]
	v_mfma_f32_16x16x32_bf16 v[18:21], v[162:165], v[204:207], v[18:21]
	v_mfma_f32_16x16x32_bf16 v[6:9], v[154:157], v[212:215], v[6:9]
	v_mfma_f32_16x16x32_bf16 v[2:5], v[162:165], v[212:215], v[2:5]
	s_barrier
	s_add_u32 s44, s44, 0x100
	s_addc_u32 s45, s45, 0
	s_add_u32 s56, s56, 0x100
	s_addc_u32 s57, s57, 0
	s_cmp_ge_i32 s72, s63
	s_mov_b32 s54, s72
	s_cbranch_scc0 .LBB0_699
	s_movk_i32 s75, 0x2000
	s_mov_b32 s72, 0x10000
	s_mov_b32 s73, 0x12000
	s_mov_b32 s74, 0x14000
	s_mov_b32 s71, 0x3f317217
	s_and_b64 vcc, exec, s[48:49]
	s_cbranch_vccz .LBB0_673

; #define PG8_STAGE(bufoff, gbase, voff) do { _Pragma("unroll") for (int _i = 0; _i < 2; ++_i) \
;         __builtin_amdgcn_global_load_lds((const unsigned*)((const char*)(gbase) + (voff)[_i]), (PG8_LAS unsigned*)(lds + (bufoff) + ldsw + _i * 8192), 16, 0, 0); } while (0)
; #define PG8_LDA(dst, b, h) do { _Pragma("unroll") for (int m = 0; m < 4; ++m) _Pragma("unroll") for (int k = 0; k < 2; ++k) dst[m][k] = *(const PG8_LAS bf16x8*)(lds + PG8_SA(b, h) + aoff + m * 2048 + k * 1024); } while (0)
; #define PG8_LDB(dst, b, h) do { _Pragma("unroll") for (int n = 0; n < 2; ++n) _Pragma("unroll") for (int k = 0; k < 2; ++k) dst[n][k] = *(const PG8_LAS bf16x8*)(lds + PG8_SB(b, h) + boff + n * 2048 + k * 1024); } while (0)
; #define PG8_MMA(ai, bj, At, Bt) do { __builtin_amdgcn_s_setprio(1); _Pragma("unroll") for (int m = 0; m < 4; ++m) _Pragma("unroll") for (int n = 0; n < 2; ++n) _Pragma("unroll") for (int k = 0; k < 2; ++k) \
;         acc[ai][bj][m][n] = __builtin_amdgcn_mfma_f32_16x16x32_bf16(Bt[n][k], At[m][k], acc[ai][bj][m][n], 0, 0, 0); __builtin_amdgcn_s_setprio(0); } while (0)
; #define PG8_WAIT_V(n) asm volatile("s_waitcnt vmcnt(" #n ")" ::: "memory")
; #define PG8_WAIT_L(n) asm volatile("s_waitcnt lgkmcnt(" #n ")" ::: "memory")
; template <class Epi, class Sched, bool ALIGN_EPI = false, bool SP2 = false>
; __device__ __forceinline__ void gemm_phase(PG8_LAS unsigned char* lds, const Gemm g, const Sched& S, const Epi& E, const int wv) {
;     ...
;             const bool last = (t == nt - 2);
;             const char* a1 = cA + (size_t)(t + 1) * kstep;
;             const char* a2 = last ? nA : cA + (size_t)(t + 2) * kstep; const char* b2 = last ? nB : cB + (size_t)(t + 2) * kstep;
;             const char* a3 = a2 + kstep; const char* b3 = b2 + kstep;
;             if (last && has_next) S.a_ready(nxt);
;             if constexpr (SP2) {
;             PG8_LDB(B0, 0, 0); PG8_LDB(B1, 0, 1); PG8_SCHED; PG8_LDA(At, 0, 0); PG8_STAGE(PG8_SA(1, 1), a1 + hstepA, voffA);
;             PG8_WAIT_V(8); PG8_WAIT_L(0); PG8_BAR; PG8_MMA(0, 0, At, B0); PG8_MMA(0, 1, At, B1); PG8_BAR; PG8_SCHED;
;             PG8_LDA(At, 0, 1); PG8_STAGE(PG8_SB(0, 0), b2, voffB); PG8_STAGE(PG8_SB(0, 1), b2 + hstepB, voffB); PG8_STAGE(PG8_SA(0, 0), a2, voffA);
;             PG8_WAIT_V(8); PG8_WAIT_L(0); PG8_BAR; PG8_MMA(1, 0, At, B0); PG8_MMA(1, 1, At, B1); PG8_BAR; PG8_SCHED;
.LBB0_809:
	s_add_i32 s52, s46, 2
	s_add_u32 s14, s48, 0x100
	s_addc_u32 s15, s49, 0
	s_cmp_eq_u32 s71, s46
	s_cselect_b32 s47, s11, s15
	s_cselect_b32 s46, s13, s14
	s_cselect_b32 s77, s87, s51
	s_cselect_b32 s76, s86, s35
	ds_read_b128 v[138:141], v192
	ds_read_b128 v[142:145], v192 offset:1024
	ds_read_b128 v[146:149], v192 offset:2048
	ds_read_b128 v[150:153], v192 offset:3072
	ds_read_b128 v[154:157], v193
	ds_read_b128 v[158:161], v193 offset:1024
	ds_read_b128 v[162:165], v193 offset:2048
	ds_read_b128 v[166:169], v193 offset:3072
	s_add_i32 m0, s63, 0xc000
	ds_read_b128 v[194:197], v211
	ds_read_b128 v[198:201], v211 offset:1024
	ds_read_b128 v[202:205], v211 offset:2048
	ds_read_b128 v[214:217], v211 offset:3072
	ds_read_b128 v[228:231], v211 offset:4096
	ds_read_b128 v[232:235], v211 offset:5120
	ds_read_b128 v[236:239], v211 offset:6144
	ds_read_b128 v[240:243], v211 offset:7168
	global_load_lds_dwordx4 v182, s[48:49]
	v_lshl_add_u64 v[190:191], s[48:49], 0, v[184:185]
	s_add_i32 m0, s63, 0xe000
	s_nop 0
	global_load_lds_dwordx4 v[190:191], off
	s_waitcnt vmcnt(8)
	s_waitcnt lgkmcnt(0)
	s_barrier
	v_mfma_f32_16x16x32_bf16 v[118:121], v[138:141], v[194:197], v[118:121]
	v_mfma_f32_16x16x32_bf16 v[46:49], v[146:149], v[194:197], v[46:49]
	v_mfma_f32_16x16x32_bf16 v[110:113], v[138:141], v[202:205], v[110:113]
	v_mfma_f32_16x16x32_bf16 v[38:41], v[146:149], v[202:205], v[38:41]
	v_mfma_f32_16x16x32_bf16 v[134:137], v[138:141], v[228:231], v[134:137]
	v_mfma_f32_16x16x32_bf16 v[62:65], v[146:149], v[228:231], v[62:65]
	v_mfma_f32_16x16x32_bf16 v[130:133], v[138:141], v[236:239], v[130:133]
	v_mfma_f32_16x16x32_bf16 v[58:61], v[146:149], v[236:239], v[58:61]
	v_mfma_f32_16x16x32_bf16 v[118:121], v[142:145], v[198:201], v[118:121]
	v_mfma_f32_16x16x32_bf16 v[46:49], v[150:153], v[198:201], v[46:49]
	v_mfma_f32_16x16x32_bf16 v[110:113], v[142:145], v[214:217], v[110:113]
	v_mfma_f32_16x16x32_bf16 v[38:41], v[150:153], v[214:217], v[38:41]
	v_mfma_f32_16x16x32_bf16 v[134:137], v[142:145], v[232:235], v[134:137]
	v_mfma_f32_16x16x32_bf16 v[62:65], v[150:153], v[232:235], v[62:65]
	v_mfma_f32_16x16x32_bf16 v[130:133], v[142:145], v[240:243], v[130:133]
	v_mfma_f32_16x16x32_bf16 v[58:61], v[150:153], v[240:243], v[58:61]
	v_mfma_f32_16x16x32_bf16 v[114:117], v[154:157], v[194:197], v[114:117]
	v_mfma_f32_16x16x32_bf16 v[42:45], v[162:165], v[194:197], v[42:45]
	v_mfma_f32_16x16x32_bf16 v[106:109], v[154:157], v[202:205], v[106:109]
	v_mfma_f32_16x16x32_bf16 v[34:37], v[162:165], v[202:205], v[34:37]
	v_mfma_f32_16x16x32_bf16 v[126:129], v[154:157], v[228:231], v[126:129]
	v_mfma_f32_16x16x32_bf16 v[54:57], v[162:165], v[228:231], v[54:57]
	v_mfma_f32_16x16x32_bf16 v[122:125], v[154:157], v[236:239], v[122:125]
	v_mfma_f32_16x16x32_bf16 v[50:53], v[162:165], v[236:239], v[50:53]
	v_mfma_f32_16x16x32_bf16 v[114:117], v[158:161], v[198:201], v[114:117]
	v_mfma_f32_16x16x32_bf16 v[42:45], v[166:169], v[198:201], v[42:45]
	v_mfma_f32_16x16x32_bf16 v[106:109], v[158:161], v[214:217], v[106:109]
	v_mfma_f32_16x16x32_bf16 v[34:37], v[166:169], v[214:217], v[34:37]
	v_mfma_f32_16x16x32_bf16 v[126:129], v[158:161], v[232:235], v[126:129]
	v_mfma_f32_16x16x32_bf16 v[54:57], v[166:169], v[232:235], v[54:57]
	v_mfma_f32_16x16x32_bf16 v[122:125], v[158:161], v[240:243], v[122:125]
	v_mfma_f32_16x16x32_bf16 v[50:53], v[166:169], v[240:243], v[50:53]
	s_barrier
	s_add_i32 s48, s62, 0x10000
	s_mov_b32 m0, s48
	ds_read_b128 v[194:197], v211 offset:16384
	ds_read_b128 v[198:201], v211 offset:17408
	ds_read_b128 v[202:205], v211 offset:18432
	ds_read_b128 v[214:217], v211 offset:19456
	ds_read_b128 v[228:231], v211 offset:20480
	ds_read_b128 v[232:235], v211 offset:21504
	ds_read_b128 v[236:239], v211 offset:22528
	ds_read_b128 v[240:243], v211 offset:23552
	global_load_lds_dwordx4 v0, s[76:77]
	s_add_i32 m0, s48, 0x2000
	s_add_u32 s48, s76, s16
	s_addc_u32 s49, s77, s17
	s_add_i32 s53, s62, 0x14000
	global_load_lds_dwordx4 v174, s[76:77]
	s_mov_b32 m0, s53
	global_load_lds_dwordx4 v0, s[48:49]
	s_add_i32 m0, s53, 0x2000
	v_lshl_add_u64 v[246:247], s[46:47], 0, v[170:171]
	global_load_lds_dwordx4 v174, s[48:49]
	s_mov_b32 m0, s63
	v_lshl_add_u64 v[248:249], s[46:47], 0, v[172:173]
	global_load_lds_dwordx4 v[246:247], off
	s_mov_b32 m0, s64
	s_nop 0
	global_load_lds_dwordx4 v[248:249], off
	s_waitcnt vmcnt(8)
	s_waitcnt lgkmcnt(0)
	s_barrier
	v_mfma_f32_16x16x32_bf16 v[86:89], v[138:141], v[194:197], v[86:89]
	v_mfma_f32_16x16x32_bf16 v[14:17], v[146:149], v[194:197], v[14:17]
	v_mfma_f32_16x16x32_bf16 v[70:73], v[138:141], v[202:205], v[70:73]
	v_mfma_f32_16x16x32_bf16 v[6:9], v[146:149], v[202:205], v[6:9]
	v_mfma_f32_16x16x32_bf16 v[102:105], v[138:141], v[228:231], v[102:105]
	v_mfma_f32_16x16x32_bf16 v[30:33], v[146:149], v[228:231], v[30:33]
	v_mfma_f32_16x16x32_bf16 v[98:101], v[138:141], v[236:239], v[98:101]
	v_mfma_f32_16x16x32_bf16 v[26:29], v[146:149], v[236:239], v[26:29]
	v_mfma_f32_16x16x32_bf16 v[86:89], v[142:145], v[198:201], v[86:89]
	v_mfma_f32_16x16x32_bf16 v[14:17], v[150:153], v[198:201], v[14:17]
	v_mfma_f32_16x16x32_bf16 v[70:73], v[142:145], v[214:217], v[70:73]
	v_mfma_f32_16x16x32_bf16 v[6:9], v[150:153], v[214:217], v[6:9]
	v_mfma_f32_16x16x32_bf16 v[102:105], v[142:145], v[232:235], v[102:105]
	v_mfma_f32_16x16x32_bf16 v[30:33], v[150:153], v[232:235], v[30:33]
	v_mfma_f32_16x16x32_bf16 v[98:101], v[142:145], v[240:243], v[98:101]
	v_mfma_f32_16x16x32_bf16 v[26:29], v[150:153], v[240:243], v[26:29]
	v_mfma_f32_16x16x32_bf16 v[82:85], v[154:157], v[194:197], v[82:85]
	v_mfma_f32_16x16x32_bf16 v[10:13], v[162:165], v[194:197], v[10:13]
	v_mfma_f32_16x16x32_bf16 v[66:69], v[154:157], v[202:205], v[66:69]
	v_mfma_f32_16x16x32_bf16 v[2:5], v[162:165], v[202:205], v[2:5]
	v_mfma_f32_16x16x32_bf16 v[94:97], v[154:157], v[228:231], v[94:97]
	v_mfma_f32_16x16x32_bf16 v[22:25], v[162:165], v[228:231], v[22:25]
	v_mfma_f32_16x16x32_bf16 v[90:93], v[154:157], v[236:239], v[90:93]
	v_mfma_f32_16x16x32_bf16 v[18:21], v[162:165], v[236:239], v[18:21]
	v_mfma_f32_16x16x32_bf16 v[82:85], v[158:161], v[198:201], v[82:85]
	v_mfma_f32_16x16x32_bf16 v[10:13], v[166:169], v[198:201], v[10:13]
	v_mfma_f32_16x16x32_bf16 v[66:69], v[158:161], v[214:217], v[66:69]
	v_mfma_f32_16x16x32_bf16 v[2:5], v[166:169], v[214:217], v[2:5]
	v_mfma_f32_16x16x32_bf16 v[94:97], v[158:161], v[232:235], v[94:97]
	v_mfma_f32_16x16x32_bf16 v[22:25], v[166:169], v[232:235], v[22:25]
	v_mfma_f32_16x16x32_bf16 v[90:93], v[158:161], v[240:243], v[90:93]
	v_mfma_f32_16x16x32_bf16 v[18:21], v[166:169], v[240:243], v[18:21]
	s_barrier
; #define PG8_STAGE(bufoff, gbase, voff) do { _Pragma("unroll") for (int _i = 0; _i < 2; ++_i) \
;         __builtin_amdgcn_global_load_lds((const unsigned*)((const char*)(gbase) + (voff)[_i]), (PG8_LAS unsigned*)(lds + (bufoff) + ldsw + _i * 8192), 16, 0, 0); } while (0)
; #define PG8_LDA(dst, b, h) do { _Pragma("unroll") for (int m = 0; m < 4; ++m) _Pragma("unroll") for (int k = 0; k < 2; ++k) dst[m][k] = *(const PG8_LAS bf16x8*)(lds + PG8_SA(b, h) + aoff + m * 2048 + k * 1024); } while (0)
; #define PG8_LDB(dst, b, h) do { _Pragma("unroll") for (int n = 0; n < 2; ++n) _Pragma("unroll") for (int k = 0; k < 2; ++k) dst[n][k] = *(const PG8_LAS bf16x8*)(lds + PG8_SB(b, h) + boff + n * 2048 + k * 1024); } while (0)
; #define PG8_MMA(ai, bj, At, Bt) do { __builtin_amdgcn_s_setprio(1); _Pragma("unroll") for (int m = 0; m < 4; ++m) _Pragma("unroll") for (int n = 0; n < 2; ++n) _Pragma("unroll") for (int k = 0; k < 2; ++k) \
;         acc[ai][bj][m][n] = __builtin_amdgcn_mfma_f32_16x16x32_bf16(Bt[n][k], At[m][k], acc[ai][bj][m][n], 0, 0, 0); __builtin_amdgcn_s_setprio(0); } while (0)
; #define PG8_WAIT_V(n) asm volatile("s_waitcnt vmcnt(" #n ")" ::: "memory")
; #define PG8_WAIT_L(n) asm volatile("s_waitcnt lgkmcnt(" #n ")" ::: "memory")
; #define PG8_BAR __builtin_amdgcn_s_barrier()
; #define PG8_SCHED __builtin_amdgcn_sched_barrier(0)
; template <class Epi, class Sched, bool ALIGN_EPI = false, bool SP2 = false>
; __device__ __forceinline__ void gemm_phase(PG8_LAS unsigned char* lds, const Gemm g, const Sched& S, const Epi& E, const int wv) {
;     ...
;             PG8_LDB(B0, 1, 0); PG8_LDB(B1, 1, 1); PG8_SCHED; PG8_LDA(At, 1, 0); PG8_STAGE(PG8_SA(0, 1), a2 + hstepA, voffA);
;             PG8_WAIT_V(8); PG8_WAIT_L(0); PG8_BAR; PG8_MMA(0, 0, At, B0); PG8_MMA(0, 1, At, B1); PG8_BAR; PG8_SCHED;
;             PG8_LDA(At, 1, 1); PG8_STAGE(PG8_SB(1, 0), b3, voffB); PG8_STAGE(PG8_SB(1, 1), b3 + hstepB, voffB); PG8_STAGE(PG8_SA(1, 0), a3, voffA);
;             PG8_WAIT_V(8); PG8_WAIT_L(0); PG8_BAR; PG8_MMA(1, 0, At, B0); PG8_MMA(1, 1, At, B1); PG8_BAR; PG8_SCHED;
	ds_read_b128 v[138:141], v213
	ds_read_b128 v[142:145], v213 offset:1024
	ds_read_b128 v[146:149], v213 offset:2048
	ds_read_b128 v[150:153], v213 offset:3072
	ds_read_b128 v[154:157], v227
	ds_read_b128 v[158:161], v227 offset:1024
	ds_read_b128 v[162:165], v227 offset:2048
	ds_read_b128 v[166:169], v227 offset:3072
	s_add_u32 s46, s46, 0x80000
	s_addc_u32 s47, s47, 0
	s_mov_b32 m0, s65
	ds_read_b128 v[194:197], v211 offset:32768
	ds_read_b128 v[198:201], v211 offset:33792
	ds_read_b128 v[202:205], v211 offset:34816
	ds_read_b128 v[214:217], v211 offset:35840
	ds_read_b128 v[228:231], v211 offset:36864
	ds_read_b128 v[232:235], v211 offset:37888
	ds_read_b128 v[236:239], v211 offset:38912
	ds_read_b128 v[240:243], v211 offset:39936
	global_load_lds_dwordx4 v170, s[46:47]
	s_mov_b32 m0, s66
	s_nop 0
	global_load_lds_dwordx4 v172, s[46:47]
	s_waitcnt vmcnt(8)
	s_waitcnt lgkmcnt(0)
	s_barrier
	v_mfma_f32_16x16x32_bf16 v[118:121], v[138:141], v[194:197], v[118:121]
	v_mfma_f32_16x16x32_bf16 v[46:49], v[146:149], v[194:197], v[46:49]
	v_mfma_f32_16x16x32_bf16 v[110:113], v[138:141], v[202:205], v[110:113]
	v_mfma_f32_16x16x32_bf16 v[38:41], v[146:149], v[202:205], v[38:41]
	v_mfma_f32_16x16x32_bf16 v[134:137], v[138:141], v[228:231], v[134:137]
	v_mfma_f32_16x16x32_bf16 v[62:65], v[146:149], v[228:231], v[62:65]
	v_mfma_f32_16x16x32_bf16 v[130:133], v[138:141], v[236:239], v[130:133]
	v_mfma_f32_16x16x32_bf16 v[58:61], v[146:149], v[236:239], v[58:61]
	v_mfma_f32_16x16x32_bf16 v[118:121], v[142:145], v[198:201], v[118:121]
	v_mfma_f32_16x16x32_bf16 v[46:49], v[150:153], v[198:201], v[46:49]
	v_mfma_f32_16x16x32_bf16 v[110:113], v[142:145], v[214:217], v[110:113]
	v_mfma_f32_16x16x32_bf16 v[38:41], v[150:153], v[214:217], v[38:41]
	v_mfma_f32_16x16x32_bf16 v[134:137], v[142:145], v[232:235], v[134:137]
	v_mfma_f32_16x16x32_bf16 v[62:65], v[150:153], v[232:235], v[62:65]
	v_mfma_f32_16x16x32_bf16 v[130:133], v[142:145], v[240:243], v[130:133]
	v_mfma_f32_16x16x32_bf16 v[58:61], v[150:153], v[240:243], v[58:61]
	v_mfma_f32_16x16x32_bf16 v[114:117], v[154:157], v[194:197], v[114:117]
	v_mfma_f32_16x16x32_bf16 v[42:45], v[162:165], v[194:197], v[42:45]
	v_mfma_f32_16x16x32_bf16 v[106:109], v[154:157], v[202:205], v[106:109]
	v_mfma_f32_16x16x32_bf16 v[34:37], v[162:165], v[202:205], v[34:37]
	v_mfma_f32_16x16x32_bf16 v[126:129], v[154:157], v[228:231], v[126:129]
	v_mfma_f32_16x16x32_bf16 v[54:57], v[162:165], v[228:231], v[54:57]
	v_mfma_f32_16x16x32_bf16 v[122:125], v[154:157], v[236:239], v[122:125]
	v_mfma_f32_16x16x32_bf16 v[50:53], v[162:165], v[236:239], v[50:53]
	v_mfma_f32_16x16x32_bf16 v[114:117], v[158:161], v[198:201], v[114:117]
	v_mfma_f32_16x16x32_bf16 v[42:45], v[166:169], v[198:201], v[42:45]
	v_mfma_f32_16x16x32_bf16 v[106:109], v[158:161], v[214:217], v[106:109]
	v_mfma_f32_16x16x32_bf16 v[34:37], v[166:169], v[214:217], v[34:37]
	v_mfma_f32_16x16x32_bf16 v[126:129], v[158:161], v[232:235], v[126:129]
	v_mfma_f32_16x16x32_bf16 v[54:57], v[166:169], v[232:235], v[54:57]
	v_mfma_f32_16x16x32_bf16 v[122:125], v[158:161], v[240:243], v[122:125]
	v_mfma_f32_16x16x32_bf16 v[50:53], v[166:169], v[240:243], v[50:53]
	s_barrier
	s_add_i32 s46, s62, 0x18000
	s_add_i32 m0, s46, 0xffffff80
	ds_read_b128 v[194:197], v211 offset:49152
	ds_read_b128 v[198:201], v211 offset:50176
	ds_read_b128 v[202:205], v211 offset:51200
	ds_read_b128 v[214:217], v211 offset:52224
	ds_read_b128 v[228:231], v211 offset:53248
	ds_read_b128 v[232:235], v211 offset:54272
	ds_read_b128 v[236:239], v211 offset:55296
	ds_read_b128 v[240:243], v211 offset:56320
	global_load_lds_dwordx4 v0, s[76:77] offset:128
	s_add_i32 m0, s46, 0x1f80
	s_add_i32 s46, s62, 0x1c000
	global_load_lds_dwordx4 v174, s[76:77] offset:128
	s_add_i32 m0, s46, 0xffffff80
	s_nop 0
	global_load_lds_dwordx4 v0, s[48:49] offset:128
	s_add_i32 m0, s46, 0x1f80
	s_nop 0
	global_load_lds_dwordx4 v174, s[48:49] offset:128
	s_add_i32 m0, s69, 0xffffff80
	s_nop 0
	global_load_lds_dwordx4 v[246:247], off offset:128
	s_add_i32 m0, s70, 0xffffff80
	s_nop 0
	global_load_lds_dwordx4 v[248:249], off offset:128
	s_waitcnt vmcnt(8)
	s_waitcnt lgkmcnt(0)
	s_barrier
	v_mfma_f32_16x16x32_bf16 v[86:89], v[138:141], v[194:197], v[86:89]
	v_mfma_f32_16x16x32_bf16 v[14:17], v[146:149], v[194:197], v[14:17]
	v_mfma_f32_16x16x32_bf16 v[70:73], v[138:141], v[202:205], v[70:73]
	v_mfma_f32_16x16x32_bf16 v[6:9], v[146:149], v[202:205], v[6:9]
	v_mfma_f32_16x16x32_bf16 v[102:105], v[138:141], v[228:231], v[102:105]
	v_mfma_f32_16x16x32_bf16 v[30:33], v[146:149], v[228:231], v[30:33]
	v_mfma_f32_16x16x32_bf16 v[98:101], v[138:141], v[236:239], v[98:101]
	v_mfma_f32_16x16x32_bf16 v[26:29], v[146:149], v[236:239], v[26:29]
	v_mfma_f32_16x16x32_bf16 v[86:89], v[142:145], v[198:201], v[86:89]
	v_mfma_f32_16x16x32_bf16 v[14:17], v[150:153], v[198:201], v[14:17]
	v_mfma_f32_16x16x32_bf16 v[70:73], v[142:145], v[214:217], v[70:73]
	v_mfma_f32_16x16x32_bf16 v[6:9], v[150:153], v[214:217], v[6:9]
	v_mfma_f32_16x16x32_bf16 v[102:105], v[142:145], v[232:235], v[102:105]
	v_mfma_f32_16x16x32_bf16 v[30:33], v[150:153], v[232:235], v[30:33]
	v_mfma_f32_16x16x32_bf16 v[98:101], v[142:145], v[240:243], v[98:101]
	v_mfma_f32_16x16x32_bf16 v[26:29], v[150:153], v[240:243], v[26:29]
	v_mfma_f32_16x16x32_bf16 v[82:85], v[154:157], v[194:197], v[82:85]
	v_mfma_f32_16x16x32_bf16 v[10:13], v[162:165], v[194:197], v[10:13]
	v_mfma_f32_16x16x32_bf16 v[66:69], v[154:157], v[202:205], v[66:69]
	v_mfma_f32_16x16x32_bf16 v[2:5], v[162:165], v[202:205], v[2:5]
	v_mfma_f32_16x16x32_bf16 v[94:97], v[154:157], v[228:231], v[94:97]
	v_mfma_f32_16x16x32_bf16 v[22:25], v[162:165], v[228:231], v[22:25]
	v_mfma_f32_16x16x32_bf16 v[90:93], v[154:157], v[236:239], v[90:93]
	v_mfma_f32_16x16x32_bf16 v[18:21], v[162:165], v[236:239], v[18:21]
	v_mfma_f32_16x16x32_bf16 v[82:85], v[158:161], v[198:201], v[82:85]
	v_mfma_f32_16x16x32_bf16 v[10:13], v[166:169], v[198:201], v[10:13]
	v_mfma_f32_16x16x32_bf16 v[66:69], v[158:161], v[214:217], v[66:69]
	v_mfma_f32_16x16x32_bf16 v[2:5], v[166:169], v[214:217], v[2:5]
	v_mfma_f32_16x16x32_bf16 v[94:97], v[158:161], v[232:235], v[94:97]
	v_mfma_f32_16x16x32_bf16 v[22:25], v[166:169], v[232:235], v[22:25]
	v_mfma_f32_16x16x32_bf16 v[90:93], v[158:161], v[240:243], v[90:93]
	v_mfma_f32_16x16x32_bf16 v[18:21], v[166:169], v[240:243], v[18:21]
	s_barrier
	s_add_u32 s35, s35, 0x100
	s_addc_u32 s51, s51, 0
	s_cmp_ge_i32 s52, s67
	s_mov_b64 s[48:49], s[14:15]
	s_mov_b32 s46, s52
	s_cbranch_scc0 .LBB0_809
	s_movk_i32 s75, 0x2000
	s_movk_i32 s76, 0x3000
	s_and_b64 vcc, exec, s[30:31]
	s_cbranch_vccz .LBB0_784

; #define PG8_STAGE(bufoff, gbase, voff) do { _Pragma("unroll") for (int _i = 0; _i < 2; ++_i) \
;         __builtin_amdgcn_global_load_lds((const unsigned*)((const char*)(gbase) + (voff)[_i]), (PG8_LAS unsigned*)(lds + (bufoff) + ldsw + _i * 8192), 16, 0, 0); } while (0)
; #define PG8_LDA(dst, b, h) do { _Pragma("unroll") for (int m = 0; m < 4; ++m) _Pragma("unroll") for (int k = 0; k < 2; ++k) dst[m][k] = *(const PG8_LAS bf16x8*)(lds + PG8_SA(b, h) + aoff + m * 2048 + k * 1024); } while (0)
; #define PG8_LDB(dst, b, h) do { _Pragma("unroll") for (int n = 0; n < 2; ++n) _Pragma("unroll") for (int k = 0; k < 2; ++k) dst[n][k] = *(const PG8_LAS bf16x8*)(lds + PG8_SB(b, h) + boff + n * 2048 + k * 1024); } while (0)
; #define PG8_MMA(ai, bj, At, Bt) do { __builtin_amdgcn_s_setprio(1); _Pragma("unroll") for (int m = 0; m < 4; ++m) _Pragma("unroll") for (int n = 0; n < 2; ++n) _Pragma("unroll") for (int k = 0; k < 2; ++k) \
;         acc[ai][bj][m][n] = __builtin_amdgcn_mfma_f32_16x16x32_bf16(Bt[n][k], At[m][k], acc[ai][bj][m][n], 0, 0, 0); __builtin_amdgcn_s_setprio(0); } while (0)
; #define PG8_WAIT_V(n) asm volatile("s_waitcnt vmcnt(" #n ")" ::: "memory")
; #define PG8_WAIT_L(n) asm volatile("s_waitcnt lgkmcnt(" #n ")" ::: "memory")
; template <class Epi, class Sched, bool ALIGN_EPI = false, bool SP2 = false>
; __device__ __forceinline__ void gemm_phase(PG8_LAS unsigned char* lds, const Gemm g, const Sched& S, const Epi& E, const int wv) {
;     ...
;             const bool last = (t == nt - 2);
;             const char* a1 = cA + (size_t)(t + 1) * kstep;
;             const char* a2 = last ? nA : cA + (size_t)(t + 2) * kstep; const char* b2 = last ? nB : cB + (size_t)(t + 2) * kstep;
;             const char* a3 = a2 + kstep; const char* b3 = b2 + kstep;
;             if (last && has_next) S.a_ready(nxt);
;             if constexpr (SP2) {
;             PG8_LDB(B0, 0, 0); PG8_LDB(B1, 0, 1); PG8_SCHED; PG8_LDA(At, 0, 0); PG8_STAGE(PG8_SA(1, 1), a1 + hstepA, voffA);
;             PG8_WAIT_V(8); PG8_WAIT_L(0); PG8_BAR; PG8_MMA(0, 0, At, B0); PG8_MMA(0, 1, At, B1); PG8_BAR; PG8_SCHED;
;             PG8_LDA(At, 0, 1); PG8_STAGE(PG8_SB(0, 0), b2, voffB); PG8_STAGE(PG8_SB(0, 1), b2 + hstepB, voffB); PG8_STAGE(PG8_SA(0, 0), a2, voffA);
;             PG8_WAIT_V(8); PG8_WAIT_L(0); PG8_BAR; PG8_MMA(1, 0, At, B0); PG8_MMA(1, 1, At, B1); PG8_BAR; PG8_SCHED;
.LBB0_990:
	s_add_i32 s67, s44, 2
	s_add_u32 s34, s30, 0x100
	s_addc_u32 s35, s31, 0
	s_cmp_eq_u32 s59, s44
	s_cselect_b32 s45, s13, s35
	s_cselect_b32 s44, s12, s34
	s_cselect_b32 s69, s15, s66
	s_cselect_b32 s68, s14, s65
	ds_read_b128 v[114:117], v197
	ds_read_b128 v[126:129], v197 offset:1024
	ds_read_b128 v[138:141], v197 offset:2048
	ds_read_b128 v[142:145], v197 offset:3072
	ds_read_b128 v[146:149], v201
	ds_read_b128 v[150:153], v201 offset:1024
	ds_read_b128 v[154:157], v201 offset:2048
	ds_read_b128 v[158:161], v201 offset:3072
	s_add_i32 m0, s52, 0xc000
	ds_read_b128 v[162:165], v235
	ds_read_b128 v[166:169], v235 offset:1024
	ds_read_b128 v[170:173], v235 offset:2048
	ds_read_b128 v[174:177], v235 offset:3072
	ds_read_b128 v[178:181], v235 offset:4096
	ds_read_b128 v[182:185], v235 offset:5120
	ds_read_b128 v[204:207], v235 offset:6144
	ds_read_b128 v[208:211], v235 offset:7168
	global_load_lds_dwordx4 v200, s[30:31]
	s_add_i32 m0, s52, 0xe000
	s_nop 0
	global_load_lds_dwordx4 v202, s[30:31]
	s_waitcnt vmcnt(8)
	s_waitcnt lgkmcnt(0)
	s_barrier
	v_mfma_f32_16x16x32_bf16 v[134:137], v[114:117], v[162:165], v[134:137]
	v_mfma_f32_16x16x32_bf16 v[130:133], v[138:141], v[162:165], v[130:133]
	v_mfma_f32_16x16x32_bf16 v[110:113], v[114:117], v[170:173], v[110:113]
	v_mfma_f32_16x16x32_bf16 v[106:109], v[138:141], v[170:173], v[106:109]
	v_mfma_f32_16x16x32_bf16 v[94:97], v[114:117], v[178:181], v[94:97]
	v_mfma_f32_16x16x32_bf16 v[90:93], v[138:141], v[178:181], v[90:93]
	v_mfma_f32_16x16x32_bf16 v[78:81], v[114:117], v[204:207], v[78:81]
	v_mfma_f32_16x16x32_bf16 v[74:77], v[138:141], v[204:207], v[74:77]
	v_mfma_f32_16x16x32_bf16 v[134:137], v[126:129], v[166:169], v[134:137]
	v_mfma_f32_16x16x32_bf16 v[130:133], v[142:145], v[166:169], v[130:133]
	v_mfma_f32_16x16x32_bf16 v[110:113], v[126:129], v[174:177], v[110:113]
	v_mfma_f32_16x16x32_bf16 v[106:109], v[142:145], v[174:177], v[106:109]
	v_mfma_f32_16x16x32_bf16 v[94:97], v[126:129], v[182:185], v[94:97]
	v_mfma_f32_16x16x32_bf16 v[90:93], v[142:145], v[182:185], v[90:93]
	v_mfma_f32_16x16x32_bf16 v[78:81], v[126:129], v[208:211], v[78:81]
	v_mfma_f32_16x16x32_bf16 v[74:77], v[142:145], v[208:211], v[74:77]
	v_mfma_f32_16x16x32_bf16 v[122:125], v[146:149], v[162:165], v[122:125]
	v_mfma_f32_16x16x32_bf16 v[118:121], v[154:157], v[162:165], v[118:121]
	v_mfma_f32_16x16x32_bf16 v[102:105], v[146:149], v[170:173], v[102:105]
	v_mfma_f32_16x16x32_bf16 v[98:101], v[154:157], v[170:173], v[98:101]
	v_mfma_f32_16x16x32_bf16 v[86:89], v[146:149], v[178:181], v[86:89]
	v_mfma_f32_16x16x32_bf16 v[82:85], v[154:157], v[178:181], v[82:85]
	v_mfma_f32_16x16x32_bf16 v[70:73], v[146:149], v[204:207], v[70:73]
	v_mfma_f32_16x16x32_bf16 v[66:69], v[154:157], v[204:207], v[66:69]
	v_mfma_f32_16x16x32_bf16 v[122:125], v[150:153], v[166:169], v[122:125]
	v_mfma_f32_16x16x32_bf16 v[118:121], v[158:161], v[166:169], v[118:121]
	v_mfma_f32_16x16x32_bf16 v[102:105], v[150:153], v[174:177], v[102:105]
	v_mfma_f32_16x16x32_bf16 v[98:101], v[158:161], v[174:177], v[98:101]
	v_mfma_f32_16x16x32_bf16 v[86:89], v[150:153], v[182:185], v[86:89]
	v_mfma_f32_16x16x32_bf16 v[82:85], v[158:161], v[182:185], v[82:85]
	v_mfma_f32_16x16x32_bf16 v[70:73], v[150:153], v[208:211], v[70:73]
	v_mfma_f32_16x16x32_bf16 v[66:69], v[158:161], v[208:211], v[66:69]
	s_barrier
	s_add_i32 s30, s47, 0x10000
	v_lshl_add_u64 v[190:191], s[68:69], 0, v[0:1]
	s_mov_b32 m0, s30
	ds_read_b128 v[162:165], v235 offset:16384
	ds_read_b128 v[166:169], v235 offset:17408
	ds_read_b128 v[170:173], v235 offset:18432
	ds_read_b128 v[174:177], v235 offset:19456
	ds_read_b128 v[178:181], v235 offset:20480
	ds_read_b128 v[182:185], v235 offset:21504
	ds_read_b128 v[204:207], v235 offset:22528
	ds_read_b128 v[208:211], v235 offset:23552
	global_load_lds_dwordx4 v[190:191], off
	s_add_i32 m0, s30, 0x2000
	s_add_u32 s30, s68, s2
	v_lshl_add_u64 v[192:193], s[68:69], 0, v[198:199]
	s_addc_u32 s31, s69, s3
	s_add_i32 s68, s47, 0x14000
	global_load_lds_dwordx4 v[192:193], off
	v_lshl_add_u64 v[212:213], s[30:31], 0, v[0:1]
	s_mov_b32 m0, s68
	v_lshl_add_u64 v[214:215], s[30:31], 0, v[198:199]
	global_load_lds_dwordx4 v[212:213], off
	s_add_i32 m0, s68, 0x2000
	global_load_lds_dwordx4 v[214:215], off
	s_mov_b32 m0, s52
	global_load_lds_dwordx4 v194, s[44:45]
	s_mov_b32 m0, s53
	s_nop 0
	global_load_lds_dwordx4 v196, s[44:45]
	s_waitcnt vmcnt(8)
	s_waitcnt lgkmcnt(0)
	s_barrier
	v_mfma_f32_16x16x32_bf16 v[62:65], v[114:117], v[162:165], v[62:65]
	v_mfma_f32_16x16x32_bf16 v[58:61], v[138:141], v[162:165], v[58:61]
	v_mfma_f32_16x16x32_bf16 v[46:49], v[114:117], v[170:173], v[46:49]
	v_mfma_f32_16x16x32_bf16 v[42:45], v[138:141], v[170:173], v[42:45]
	v_mfma_f32_16x16x32_bf16 v[30:33], v[114:117], v[178:181], v[30:33]
	v_mfma_f32_16x16x32_bf16 v[26:29], v[138:141], v[178:181], v[26:29]
	v_mfma_f32_16x16x32_bf16 v[14:17], v[114:117], v[204:207], v[14:17]
	v_mfma_f32_16x16x32_bf16 v[10:13], v[138:141], v[204:207], v[10:13]
	v_mfma_f32_16x16x32_bf16 v[62:65], v[126:129], v[166:169], v[62:65]
	v_mfma_f32_16x16x32_bf16 v[58:61], v[142:145], v[166:169], v[58:61]
	v_mfma_f32_16x16x32_bf16 v[46:49], v[126:129], v[174:177], v[46:49]
	v_mfma_f32_16x16x32_bf16 v[42:45], v[142:145], v[174:177], v[42:45]
	v_mfma_f32_16x16x32_bf16 v[30:33], v[126:129], v[182:185], v[30:33]
	v_mfma_f32_16x16x32_bf16 v[26:29], v[142:145], v[182:185], v[26:29]
	v_mfma_f32_16x16x32_bf16 v[14:17], v[126:129], v[208:211], v[14:17]
	v_mfma_f32_16x16x32_bf16 v[10:13], v[142:145], v[208:211], v[10:13]
	v_mfma_f32_16x16x32_bf16 v[54:57], v[146:149], v[162:165], v[54:57]
	v_mfma_f32_16x16x32_bf16 v[50:53], v[154:157], v[162:165], v[50:53]
	v_mfma_f32_16x16x32_bf16 v[38:41], v[146:149], v[170:173], v[38:41]
	v_mfma_f32_16x16x32_bf16 v[34:37], v[154:157], v[170:173], v[34:37]
	v_mfma_f32_16x16x32_bf16 v[22:25], v[146:149], v[178:181], v[22:25]
	v_mfma_f32_16x16x32_bf16 v[18:21], v[154:157], v[178:181], v[18:21]
	v_mfma_f32_16x16x32_bf16 v[6:9], v[146:149], v[204:207], v[6:9]
	v_mfma_f32_16x16x32_bf16 v[2:5], v[154:157], v[204:207], v[2:5]
	v_mfma_f32_16x16x32_bf16 v[54:57], v[150:153], v[166:169], v[54:57]
	v_mfma_f32_16x16x32_bf16 v[50:53], v[158:161], v[166:169], v[50:53]
	v_mfma_f32_16x16x32_bf16 v[38:41], v[150:153], v[174:177], v[38:41]
	v_mfma_f32_16x16x32_bf16 v[34:37], v[158:161], v[174:177], v[34:37]
	v_mfma_f32_16x16x32_bf16 v[22:25], v[150:153], v[182:185], v[22:25]
	v_mfma_f32_16x16x32_bf16 v[18:21], v[158:161], v[182:185], v[18:21]
	v_mfma_f32_16x16x32_bf16 v[6:9], v[150:153], v[208:211], v[6:9]
	v_mfma_f32_16x16x32_bf16 v[2:5], v[158:161], v[208:211], v[2:5]
	s_barrier
; #define PG8_STAGE(bufoff, gbase, voff) do { _Pragma("unroll") for (int _i = 0; _i < 2; ++_i) \
;         __builtin_amdgcn_global_load_lds((const unsigned*)((const char*)(gbase) + (voff)[_i]), (PG8_LAS unsigned*)(lds + (bufoff) + ldsw + _i * 8192), 16, 0, 0); } while (0)
; #define PG8_LDA(dst, b, h) do { _Pragma("unroll") for (int m = 0; m < 4; ++m) _Pragma("unroll") for (int k = 0; k < 2; ++k) dst[m][k] = *(const PG8_LAS bf16x8*)(lds + PG8_SA(b, h) + aoff + m * 2048 + k * 1024); } while (0)
; #define PG8_LDB(dst, b, h) do { _Pragma("unroll") for (int n = 0; n < 2; ++n) _Pragma("unroll") for (int k = 0; k < 2; ++k) dst[n][k] = *(const PG8_LAS bf16x8*)(lds + PG8_SB(b, h) + boff + n * 2048 + k * 1024); } while (0)
; #define PG8_MMA(ai, bj, At, Bt) do { __builtin_amdgcn_s_setprio(1); _Pragma("unroll") for (int m = 0; m < 4; ++m) _Pragma("unroll") for (int n = 0; n < 2; ++n) _Pragma("unroll") for (int k = 0; k < 2; ++k) \
;         acc[ai][bj][m][n] = __builtin_amdgcn_mfma_f32_16x16x32_bf16(Bt[n][k], At[m][k], acc[ai][bj][m][n], 0, 0, 0); __builtin_amdgcn_s_setprio(0); } while (0)
; #define PG8_WAIT_V(n) asm volatile("s_waitcnt vmcnt(" #n ")" ::: "memory")
; #define PG8_WAIT_L(n) asm volatile("s_waitcnt lgkmcnt(" #n ")" ::: "memory")
; #define PG8_BAR __builtin_amdgcn_s_barrier()
; #define PG8_SCHED __builtin_amdgcn_sched_barrier(0)
; template <class Epi, class Sched, bool ALIGN_EPI = false, bool SP2 = false>
; __device__ __forceinline__ void gemm_phase(PG8_LAS unsigned char* lds, const Gemm g, const Sched& S, const Epi& E, const int wv) {
;     ...
;             PG8_LDB(B0, 1, 0); PG8_LDB(B1, 1, 1); PG8_SCHED; PG8_LDA(At, 1, 0); PG8_STAGE(PG8_SA(0, 1), a2 + hstepA, voffA);
;             PG8_WAIT_V(8); PG8_WAIT_L(0); PG8_BAR; PG8_MMA(0, 0, At, B0); PG8_MMA(0, 1, At, B1); PG8_BAR; PG8_SCHED;
;             PG8_LDA(At, 1, 1); PG8_STAGE(PG8_SB(1, 0), b3, voffB); PG8_STAGE(PG8_SB(1, 1), b3 + hstepB, voffB); PG8_STAGE(PG8_SA(1, 0), a3, voffA);
;             PG8_WAIT_V(8); PG8_WAIT_L(0); PG8_BAR; PG8_MMA(1, 0, At, B0); PG8_MMA(1, 1, At, B1); PG8_BAR; PG8_SCHED;
	ds_read_b128 v[114:117], v203
	ds_read_b128 v[126:129], v203 offset:1024
	ds_read_b128 v[138:141], v203 offset:2048
	ds_read_b128 v[142:145], v203 offset:3072
	ds_read_b128 v[146:149], v216
	ds_read_b128 v[150:153], v216 offset:1024
	ds_read_b128 v[154:157], v216 offset:2048
	ds_read_b128 v[158:161], v216 offset:3072
	s_add_u32 s30, s44, 0x180000
	s_addc_u32 s31, s45, 0
	s_mov_b32 m0, s54
	ds_read_b128 v[162:165], v235 offset:32768
	ds_read_b128 v[166:169], v235 offset:33792
	ds_read_b128 v[170:173], v235 offset:34816
	ds_read_b128 v[174:177], v235 offset:35840
	ds_read_b128 v[178:181], v235 offset:36864
	ds_read_b128 v[182:185], v235 offset:37888
	ds_read_b128 v[204:207], v235 offset:38912
	ds_read_b128 v[208:211], v235 offset:39936
	global_load_lds_dwordx4 v194, s[30:31]
	s_mov_b32 m0, s55
	s_nop 0
	global_load_lds_dwordx4 v196, s[30:31]
	s_waitcnt vmcnt(8)
	s_waitcnt lgkmcnt(0)
	s_barrier
	v_mfma_f32_16x16x32_bf16 v[134:137], v[114:117], v[162:165], v[134:137]
	v_mfma_f32_16x16x32_bf16 v[130:133], v[138:141], v[162:165], v[130:133]
	v_mfma_f32_16x16x32_bf16 v[110:113], v[114:117], v[170:173], v[110:113]
	v_mfma_f32_16x16x32_bf16 v[106:109], v[138:141], v[170:173], v[106:109]
	v_mfma_f32_16x16x32_bf16 v[94:97], v[114:117], v[178:181], v[94:97]
	v_mfma_f32_16x16x32_bf16 v[90:93], v[138:141], v[178:181], v[90:93]
	v_mfma_f32_16x16x32_bf16 v[78:81], v[114:117], v[204:207], v[78:81]
	v_mfma_f32_16x16x32_bf16 v[74:77], v[138:141], v[204:207], v[74:77]
	v_mfma_f32_16x16x32_bf16 v[134:137], v[126:129], v[166:169], v[134:137]
	v_mfma_f32_16x16x32_bf16 v[130:133], v[142:145], v[166:169], v[130:133]
	v_mfma_f32_16x16x32_bf16 v[110:113], v[126:129], v[174:177], v[110:113]
	v_mfma_f32_16x16x32_bf16 v[106:109], v[142:145], v[174:177], v[106:109]
	v_mfma_f32_16x16x32_bf16 v[94:97], v[126:129], v[182:185], v[94:97]
	v_mfma_f32_16x16x32_bf16 v[90:93], v[142:145], v[182:185], v[90:93]
	v_mfma_f32_16x16x32_bf16 v[78:81], v[126:129], v[208:211], v[78:81]
	v_mfma_f32_16x16x32_bf16 v[74:77], v[142:145], v[208:211], v[74:77]
	v_mfma_f32_16x16x32_bf16 v[122:125], v[146:149], v[162:165], v[122:125]
	v_mfma_f32_16x16x32_bf16 v[118:121], v[154:157], v[162:165], v[118:121]
	v_mfma_f32_16x16x32_bf16 v[102:105], v[146:149], v[170:173], v[102:105]
	v_mfma_f32_16x16x32_bf16 v[98:101], v[154:157], v[170:173], v[98:101]
	v_mfma_f32_16x16x32_bf16 v[86:89], v[146:149], v[178:181], v[86:89]
	v_mfma_f32_16x16x32_bf16 v[82:85], v[154:157], v[178:181], v[82:85]
	v_mfma_f32_16x16x32_bf16 v[70:73], v[146:149], v[204:207], v[70:73]
	v_mfma_f32_16x16x32_bf16 v[66:69], v[154:157], v[204:207], v[66:69]
	v_mfma_f32_16x16x32_bf16 v[122:125], v[150:153], v[166:169], v[122:125]
	v_mfma_f32_16x16x32_bf16 v[118:121], v[158:161], v[166:169], v[118:121]
	v_mfma_f32_16x16x32_bf16 v[102:105], v[150:153], v[174:177], v[102:105]
	v_mfma_f32_16x16x32_bf16 v[98:101], v[158:161], v[174:177], v[98:101]
	v_mfma_f32_16x16x32_bf16 v[86:89], v[150:153], v[182:185], v[86:89]
	v_mfma_f32_16x16x32_bf16 v[82:85], v[158:161], v[182:185], v[82:85]
	v_mfma_f32_16x16x32_bf16 v[70:73], v[150:153], v[208:211], v[70:73]
	v_mfma_f32_16x16x32_bf16 v[66:69], v[158:161], v[208:211], v[66:69]
	s_barrier
	s_add_i32 s30, s47, 0x18000
	s_add_i32 m0, s30, 0xffffff80
	ds_read_b128 v[162:165], v235 offset:49152
	ds_read_b128 v[166:169], v235 offset:50176
	ds_read_b128 v[170:173], v235 offset:51200
	ds_read_b128 v[174:177], v235 offset:52224
	ds_read_b128 v[178:181], v235 offset:53248
	ds_read_b128 v[182:185], v235 offset:54272
	ds_read_b128 v[204:207], v235 offset:55296
	ds_read_b128 v[208:211], v235 offset:56320
	global_load_lds_dwordx4 v[190:191], off offset:128
	s_add_i32 m0, s30, 0x1f80
	s_add_i32 s30, s47, 0x1c000
	global_load_lds_dwordx4 v[192:193], off offset:128
	s_add_i32 m0, s30, 0xffffff80
	s_nop 0
	global_load_lds_dwordx4 v[212:213], off offset:128
	s_add_i32 m0, s30, 0x1f80
	s_nop 0
	global_load_lds_dwordx4 v[214:215], off offset:128
	s_add_i32 m0, s57, 0xffffff80
	s_nop 0
	global_load_lds_dwordx4 v194, s[44:45] offset:128
	s_add_i32 m0, s58, 0xffffff80
	s_nop 0
	global_load_lds_dwordx4 v196, s[44:45] offset:128
	s_waitcnt vmcnt(8)
	s_waitcnt lgkmcnt(0)
	s_barrier
	v_mfma_f32_16x16x32_bf16 v[62:65], v[114:117], v[162:165], v[62:65]
	v_mfma_f32_16x16x32_bf16 v[58:61], v[138:141], v[162:165], v[58:61]
	v_mfma_f32_16x16x32_bf16 v[46:49], v[114:117], v[170:173], v[46:49]
	v_mfma_f32_16x16x32_bf16 v[42:45], v[138:141], v[170:173], v[42:45]
	v_mfma_f32_16x16x32_bf16 v[30:33], v[114:117], v[178:181], v[30:33]
	v_mfma_f32_16x16x32_bf16 v[26:29], v[138:141], v[178:181], v[26:29]
	v_mfma_f32_16x16x32_bf16 v[14:17], v[114:117], v[204:207], v[14:17]
	v_mfma_f32_16x16x32_bf16 v[10:13], v[138:141], v[204:207], v[10:13]
	v_mfma_f32_16x16x32_bf16 v[62:65], v[126:129], v[166:169], v[62:65]
	v_mfma_f32_16x16x32_bf16 v[58:61], v[142:145], v[166:169], v[58:61]
	v_mfma_f32_16x16x32_bf16 v[46:49], v[126:129], v[174:177], v[46:49]
	v_mfma_f32_16x16x32_bf16 v[42:45], v[142:145], v[174:177], v[42:45]
	v_mfma_f32_16x16x32_bf16 v[30:33], v[126:129], v[182:185], v[30:33]
	v_mfma_f32_16x16x32_bf16 v[26:29], v[142:145], v[182:185], v[26:29]
	v_mfma_f32_16x16x32_bf16 v[14:17], v[126:129], v[208:211], v[14:17]
	v_mfma_f32_16x16x32_bf16 v[10:13], v[142:145], v[208:211], v[10:13]
	v_mfma_f32_16x16x32_bf16 v[54:57], v[146:149], v[162:165], v[54:57]
	v_mfma_f32_16x16x32_bf16 v[50:53], v[154:157], v[162:165], v[50:53]
	v_mfma_f32_16x16x32_bf16 v[38:41], v[146:149], v[170:173], v[38:41]
	v_mfma_f32_16x16x32_bf16 v[34:37], v[154:157], v[170:173], v[34:37]
	v_mfma_f32_16x16x32_bf16 v[22:25], v[146:149], v[178:181], v[22:25]
	v_mfma_f32_16x16x32_bf16 v[18:21], v[154:157], v[178:181], v[18:21]
	v_mfma_f32_16x16x32_bf16 v[6:9], v[146:149], v[204:207], v[6:9]
	v_mfma_f32_16x16x32_bf16 v[2:5], v[154:157], v[204:207], v[2:5]
	v_mfma_f32_16x16x32_bf16 v[54:57], v[150:153], v[166:169], v[54:57]
	v_mfma_f32_16x16x32_bf16 v[50:53], v[158:161], v[166:169], v[50:53]
	v_mfma_f32_16x16x32_bf16 v[38:41], v[150:153], v[174:177], v[38:41]
	v_mfma_f32_16x16x32_bf16 v[34:37], v[158:161], v[174:177], v[34:37]
	v_mfma_f32_16x16x32_bf16 v[22:25], v[150:153], v[182:185], v[22:25]
	v_mfma_f32_16x16x32_bf16 v[18:21], v[158:161], v[182:185], v[18:21]
	v_mfma_f32_16x16x32_bf16 v[6:9], v[150:153], v[208:211], v[6:9]
	v_mfma_f32_16x16x32_bf16 v[2:5], v[158:161], v[208:211], v[2:5]
	s_barrier
	s_add_u32 s65, s65, 0x100
	s_addc_u32 s66, s66, 0
	s_cmp_ge_i32 s67, s56
	s_mov_b64 s[30:31], s[34:35]
	s_mov_b32 s44, s67
	s_cbranch_scc0 .LBB0_990
	s_movk_i32 s68, 0x4000
	s_movk_i32 s69, 0x6000
	s_mov_b32 s70, 0x18000
	s_mov_b32 s71, 0x3f317217
	v_readlane_b32 s67, v255, 30
	s_and_b64 vcc, exec, s[28:29]
	s_cbranch_vccz .LBB0_966

; #define PG8_STAGE(bufoff, gbase, voff) do { _Pragma("unroll") for (int _i = 0; _i < 2; ++_i) \
;         __builtin_amdgcn_global_load_lds((const unsigned*)((const char*)(gbase) + (voff)[_i]), (PG8_LAS unsigned*)(lds + (bufoff) + ldsw + _i * 8192), 16, 0, 0); } while (0)
; #define PG8_LDA(dst, b, h) do { _Pragma("unroll") for (int m = 0; m < 4; ++m) _Pragma("unroll") for (int k = 0; k < 2; ++k) dst[m][k] = *(const PG8_LAS bf16x8*)(lds + PG8_SA(b, h) + aoff + m * 2048 + k * 1024); } while (0)
; #define PG8_LDB(dst, b, h) do { _Pragma("unroll") for (int n = 0; n < 2; ++n) _Pragma("unroll") for (int k = 0; k < 2; ++k) dst[n][k] = *(const PG8_LAS bf16x8*)(lds + PG8_SB(b, h) + boff + n * 2048 + k * 1024); } while (0)
; #define PG8_MMA(ai, bj, At, Bt) do { __builtin_amdgcn_s_setprio(1); _Pragma("unroll") for (int m = 0; m < 4; ++m) _Pragma("unroll") for (int n = 0; n < 2; ++n) _Pragma("unroll") for (int k = 0; k < 2; ++k) \
;         acc[ai][bj][m][n] = __builtin_amdgcn_mfma_f32_16x16x32_bf16(Bt[n][k], At[m][k], acc[ai][bj][m][n], 0, 0, 0); __builtin_amdgcn_s_setprio(0); } while (0)
; #define PG8_WAIT_V(n) asm volatile("s_waitcnt vmcnt(" #n ")" ::: "memory")
; #define PG8_WAIT_L(n) asm volatile("s_waitcnt lgkmcnt(" #n ")" ::: "memory")
; template <class Epi, class Sched, bool ALIGN_EPI = false, bool SP2 = false>
; __device__ __forceinline__ void gemm_phase(PG8_LAS unsigned char* lds, const Gemm g, const Sched& S, const Epi& E, const int wv) {
;     ...
;             const bool last = (t == nt - 2);
;             const char* a1 = cA + (size_t)(t + 1) * kstep;
;             const char* a2 = last ? nA : cA + (size_t)(t + 2) * kstep; const char* b2 = last ? nB : cB + (size_t)(t + 2) * kstep;
;             const char* a3 = a2 + kstep; const char* b3 = b2 + kstep;
;             if (last && has_next) S.a_ready(nxt);
;             if constexpr (SP2) {
;             PG8_LDB(B0, 0, 0); PG8_LDB(B1, 0, 1); PG8_SCHED; PG8_LDA(At, 0, 0); PG8_STAGE(PG8_SA(1, 1), a1 + hstepA, voffA);
;             PG8_WAIT_V(8); PG8_WAIT_L(0); PG8_BAR; PG8_MMA(0, 0, At, B0); PG8_MMA(0, 1, At, B1); PG8_BAR; PG8_SCHED;
;             PG8_LDA(At, 0, 1); PG8_STAGE(PG8_SB(0, 0), b2, voffB); PG8_STAGE(PG8_SB(0, 1), b2 + hstepB, voffB); PG8_STAGE(PG8_SA(0, 0), a2, voffA);
;             PG8_WAIT_V(8); PG8_WAIT_L(0); PG8_BAR; PG8_MMA(1, 0, At, B0); PG8_MMA(1, 1, At, B1); PG8_BAR; PG8_SCHED;
.LBB0_1074:
	s_add_i32 s63, s30, 2
	s_add_u32 s64, s28, 0xfff80080
	s_addc_u32 s31, s29, -1
	s_cmp_eq_u32 s57, s30
	s_cselect_b32 s31, s17, s31
	s_cselect_b32 s30, s40, s64
	s_cselect_b32 s65, s19, s62
	s_cselect_b32 s64, s18, s41
	ds_read_b128 v[164:167], v147
	ds_read_b128 v[168:171], v147 offset:1024
	ds_read_b128 v[172:175], v147 offset:2048
	ds_read_b128 v[176:179], v147 offset:3072
	ds_read_b128 v[180:183], v149
	ds_read_b128 v[194:197], v149 offset:1024
	ds_read_b128 v[198:201], v149 offset:2048
	ds_read_b128 v[202:205], v149 offset:3072
	s_add_i32 m0, s47, 0xc000
	ds_read_b128 v[206:209], v163
	ds_read_b128 v[210:213], v163 offset:1024
	ds_read_b128 v[214:217], v163 offset:2048
	ds_read_b128 v[228:231], v163 offset:3072
	ds_read_b128 v[232:235], v163 offset:4096
	ds_read_b128 v[236:239], v163 offset:5120
	ds_read_b128 v[240:243], v163 offset:6144
	ds_read_b128 v[244:247], v163 offset:7168
	global_load_lds_dwordx4 v146, s[28:29]
	s_add_i32 m0, s47, 0xe000
	s_nop 0
	global_load_lds_dwordx4 v148, s[28:29]
	s_waitcnt vmcnt(8)
	s_waitcnt lgkmcnt(0)
	s_barrier
	v_mfma_f32_16x16x32_bf16 v[130:133], v[164:167], v[206:209], v[130:133]
	v_mfma_f32_16x16x32_bf16 v[126:129], v[172:175], v[206:209], v[126:129]
	v_mfma_f32_16x16x32_bf16 v[114:117], v[164:167], v[214:217], v[114:117]
	v_mfma_f32_16x16x32_bf16 v[110:113], v[172:175], v[214:217], v[110:113]
	v_mfma_f32_16x16x32_bf16 v[98:101], v[164:167], v[232:235], v[98:101]
	v_mfma_f32_16x16x32_bf16 v[94:97], v[172:175], v[232:235], v[94:97]
	v_mfma_f32_16x16x32_bf16 v[82:85], v[164:167], v[240:243], v[82:85]
	v_mfma_f32_16x16x32_bf16 v[78:81], v[172:175], v[240:243], v[78:81]
	v_mfma_f32_16x16x32_bf16 v[130:133], v[168:171], v[210:213], v[130:133]
	v_mfma_f32_16x16x32_bf16 v[126:129], v[176:179], v[210:213], v[126:129]
	v_mfma_f32_16x16x32_bf16 v[114:117], v[168:171], v[228:231], v[114:117]
	v_mfma_f32_16x16x32_bf16 v[110:113], v[176:179], v[228:231], v[110:113]
	v_mfma_f32_16x16x32_bf16 v[98:101], v[168:171], v[236:239], v[98:101]
	v_mfma_f32_16x16x32_bf16 v[94:97], v[176:179], v[236:239], v[94:97]
	v_mfma_f32_16x16x32_bf16 v[82:85], v[168:171], v[244:247], v[82:85]
	v_mfma_f32_16x16x32_bf16 v[78:81], v[176:179], v[244:247], v[78:81]
	v_mfma_f32_16x16x32_bf16 v[122:125], v[180:183], v[206:209], v[122:125]
	v_mfma_f32_16x16x32_bf16 v[118:121], v[198:201], v[206:209], v[118:121]
	v_mfma_f32_16x16x32_bf16 v[106:109], v[180:183], v[214:217], v[106:109]
	v_mfma_f32_16x16x32_bf16 v[102:105], v[198:201], v[214:217], v[102:105]
	v_mfma_f32_16x16x32_bf16 v[90:93], v[180:183], v[232:235], v[90:93]
	v_mfma_f32_16x16x32_bf16 v[86:89], v[198:201], v[232:235], v[86:89]
	v_mfma_f32_16x16x32_bf16 v[74:77], v[180:183], v[240:243], v[74:77]
	v_mfma_f32_16x16x32_bf16 v[70:73], v[198:201], v[240:243], v[70:73]
	v_mfma_f32_16x16x32_bf16 v[122:125], v[194:197], v[210:213], v[122:125]
	v_mfma_f32_16x16x32_bf16 v[118:121], v[202:205], v[210:213], v[118:121]
	v_mfma_f32_16x16x32_bf16 v[106:109], v[194:197], v[228:231], v[106:109]
	v_mfma_f32_16x16x32_bf16 v[102:105], v[202:205], v[228:231], v[102:105]
	v_mfma_f32_16x16x32_bf16 v[90:93], v[194:197], v[236:239], v[90:93]
	v_mfma_f32_16x16x32_bf16 v[86:89], v[202:205], v[236:239], v[86:89]
	v_mfma_f32_16x16x32_bf16 v[74:77], v[194:197], v[244:247], v[74:77]
	v_mfma_f32_16x16x32_bf16 v[70:73], v[202:205], v[244:247], v[70:73]
	s_barrier
	s_add_i32 s66, s45, 0x10000
	v_lshl_add_u64 v[150:151], s[64:65], 0, v[138:139]
	s_mov_b32 m0, s66
	ds_read_b128 v[206:209], v163 offset:16384
	ds_read_b128 v[210:213], v163 offset:17408
	ds_read_b128 v[214:217], v163 offset:18432
	ds_read_b128 v[228:231], v163 offset:19456
	ds_read_b128 v[232:235], v163 offset:20480
	ds_read_b128 v[236:239], v163 offset:21504
	ds_read_b128 v[240:243], v163 offset:22528
	ds_read_b128 v[244:247], v163 offset:23552
	global_load_lds_dwordx4 v[150:151], off
	s_add_i32 m0, s66, 0x2000
	v_lshl_add_u64 v[184:185], s[64:65], 0, v[134:135]
	s_add_u32 s64, s64, s0
	s_addc_u32 s65, s65, s1
	s_add_i32 s66, s45, 0x14000
	global_load_lds_dwordx4 v[184:185], off
	s_mov_b32 m0, s66
	global_load_lds_dwordx4 v138, s[64:65]
	s_add_i32 m0, s66, 0x2000
	v_lshl_add_u64 v[218:219], s[30:31], 0, v[140:141]
	global_load_lds_dwordx4 v134, s[64:65]
	s_mov_b32 m0, s47
	v_lshl_add_u64 v[248:249], s[30:31], 0, v[136:137]
	global_load_lds_dwordx4 v[218:219], off
	s_mov_b32 m0, s48
	s_nop 0
	global_load_lds_dwordx4 v[248:249], off
	s_waitcnt vmcnt(8)
	s_waitcnt lgkmcnt(0)
	s_barrier
	v_mfma_f32_16x16x32_bf16 v[66:69], v[164:167], v[206:209], v[66:69]
	v_mfma_f32_16x16x32_bf16 v[62:65], v[172:175], v[206:209], v[62:65]
	v_mfma_f32_16x16x32_bf16 v[50:53], v[164:167], v[214:217], v[50:53]
	v_mfma_f32_16x16x32_bf16 v[46:49], v[172:175], v[214:217], v[46:49]
	v_mfma_f32_16x16x32_bf16 v[34:37], v[164:167], v[232:235], v[34:37]
	v_mfma_f32_16x16x32_bf16 v[30:33], v[172:175], v[232:235], v[30:33]
	v_mfma_f32_16x16x32_bf16 v[18:21], v[164:167], v[240:243], v[18:21]
	v_mfma_f32_16x16x32_bf16 v[14:17], v[172:175], v[240:243], v[14:17]
	v_mfma_f32_16x16x32_bf16 v[66:69], v[168:171], v[210:213], v[66:69]
	v_mfma_f32_16x16x32_bf16 v[62:65], v[176:179], v[210:213], v[62:65]
	v_mfma_f32_16x16x32_bf16 v[50:53], v[168:171], v[228:231], v[50:53]
	v_mfma_f32_16x16x32_bf16 v[46:49], v[176:179], v[228:231], v[46:49]
	v_mfma_f32_16x16x32_bf16 v[34:37], v[168:171], v[236:239], v[34:37]
	v_mfma_f32_16x16x32_bf16 v[30:33], v[176:179], v[236:239], v[30:33]
	v_mfma_f32_16x16x32_bf16 v[18:21], v[168:171], v[244:247], v[18:21]
	v_mfma_f32_16x16x32_bf16 v[14:17], v[176:179], v[244:247], v[14:17]
	v_mfma_f32_16x16x32_bf16 v[58:61], v[180:183], v[206:209], v[58:61]
	v_mfma_f32_16x16x32_bf16 v[54:57], v[198:201], v[206:209], v[54:57]
	v_mfma_f32_16x16x32_bf16 v[42:45], v[180:183], v[214:217], v[42:45]
	v_mfma_f32_16x16x32_bf16 v[38:41], v[198:201], v[214:217], v[38:41]
	v_mfma_f32_16x16x32_bf16 v[26:29], v[180:183], v[232:235], v[26:29]
	v_mfma_f32_16x16x32_bf16 v[22:25], v[198:201], v[232:235], v[22:25]
	v_mfma_f32_16x16x32_bf16 v[10:13], v[180:183], v[240:243], v[10:13]
	v_mfma_f32_16x16x32_bf16 v[6:9], v[198:201], v[240:243], v[6:9]
	v_mfma_f32_16x16x32_bf16 v[58:61], v[194:197], v[210:213], v[58:61]
	v_mfma_f32_16x16x32_bf16 v[54:57], v[202:205], v[210:213], v[54:57]
	v_mfma_f32_16x16x32_bf16 v[42:45], v[194:197], v[228:231], v[42:45]
	v_mfma_f32_16x16x32_bf16 v[38:41], v[202:205], v[228:231], v[38:41]
	v_mfma_f32_16x16x32_bf16 v[26:29], v[194:197], v[236:239], v[26:29]
	v_mfma_f32_16x16x32_bf16 v[22:25], v[202:205], v[236:239], v[22:25]
	v_mfma_f32_16x16x32_bf16 v[10:13], v[194:197], v[244:247], v[10:13]
	v_mfma_f32_16x16x32_bf16 v[6:9], v[202:205], v[244:247], v[6:9]
	s_barrier
; #define PG8_STAGE(bufoff, gbase, voff) do { _Pragma("unroll") for (int _i = 0; _i < 2; ++_i) \
;         __builtin_amdgcn_global_load_lds((const unsigned*)((const char*)(gbase) + (voff)[_i]), (PG8_LAS unsigned*)(lds + (bufoff) + ldsw + _i * 8192), 16, 0, 0); } while (0)
; #define PG8_LDA(dst, b, h) do { _Pragma("unroll") for (int m = 0; m < 4; ++m) _Pragma("unroll") for (int k = 0; k < 2; ++k) dst[m][k] = *(const PG8_LAS bf16x8*)(lds + PG8_SA(b, h) + aoff + m * 2048 + k * 1024); } while (0)
; #define PG8_LDB(dst, b, h) do { _Pragma("unroll") for (int n = 0; n < 2; ++n) _Pragma("unroll") for (int k = 0; k < 2; ++k) dst[n][k] = *(const PG8_LAS bf16x8*)(lds + PG8_SB(b, h) + boff + n * 2048 + k * 1024); } while (0)
; #define PG8_MMA(ai, bj, At, Bt) do { __builtin_amdgcn_s_setprio(1); _Pragma("unroll") for (int m = 0; m < 4; ++m) _Pragma("unroll") for (int n = 0; n < 2; ++n) _Pragma("unroll") for (int k = 0; k < 2; ++k) \
;         acc[ai][bj][m][n] = __builtin_amdgcn_mfma_f32_16x16x32_bf16(Bt[n][k], At[m][k], acc[ai][bj][m][n], 0, 0, 0); __builtin_amdgcn_s_setprio(0); } while (0)
; #define PG8_WAIT_V(n) asm volatile("s_waitcnt vmcnt(" #n ")" ::: "memory")
; #define PG8_WAIT_L(n) asm volatile("s_waitcnt lgkmcnt(" #n ")" ::: "memory")
; #define PG8_BAR __builtin_amdgcn_s_barrier()
; #define PG8_SCHED __builtin_amdgcn_sched_barrier(0)
; template <class Epi, class Sched, bool ALIGN_EPI = false, bool SP2 = false>
; __device__ __forceinline__ void gemm_phase(PG8_LAS unsigned char* lds, const Gemm g, const Sched& S, const Epi& E, const int wv) {
;     ...
;             PG8_LDB(B0, 1, 0); PG8_LDB(B1, 1, 1); PG8_SCHED; PG8_LDA(At, 1, 0); PG8_STAGE(PG8_SA(0, 1), a2 + hstepA, voffA);
;             PG8_WAIT_V(8); PG8_WAIT_L(0); PG8_BAR; PG8_MMA(0, 0, At, B0); PG8_MMA(0, 1, At, B1); PG8_BAR; PG8_SCHED;
;             PG8_LDA(At, 1, 1); PG8_STAGE(PG8_SB(1, 0), b3, voffB); PG8_STAGE(PG8_SB(1, 1), b3 + hstepB, voffB); PG8_STAGE(PG8_SA(1, 0), a3, voffA);
;             PG8_WAIT_V(8); PG8_WAIT_L(0); PG8_BAR; PG8_MMA(1, 0, At, B0); PG8_MMA(1, 1, At, B1); PG8_BAR; PG8_SCHED;
	ds_read_b128 v[164:167], v152
	ds_read_b128 v[168:171], v152 offset:1024
	ds_read_b128 v[172:175], v152 offset:2048
	ds_read_b128 v[176:179], v152 offset:3072
	ds_read_b128 v[180:183], v154
	ds_read_b128 v[194:197], v154 offset:1024
	ds_read_b128 v[198:201], v154 offset:2048
	ds_read_b128 v[202:205], v154 offset:3072
	s_add_u32 s30, s30, 0x80000
	s_addc_u32 s31, s31, 0
	s_mov_b32 m0, s49
	ds_read_b128 v[206:209], v163 offset:32768
	ds_read_b128 v[210:213], v163 offset:33792
	ds_read_b128 v[214:217], v163 offset:34816
	ds_read_b128 v[228:231], v163 offset:35840
	ds_read_b128 v[232:235], v163 offset:36864
	ds_read_b128 v[236:239], v163 offset:37888
	ds_read_b128 v[240:243], v163 offset:38912
	ds_read_b128 v[244:247], v163 offset:39936
	global_load_lds_dwordx4 v140, s[30:31]
	s_mov_b32 m0, s50
	s_nop 0
	global_load_lds_dwordx4 v136, s[30:31]
	s_waitcnt vmcnt(8)
	s_waitcnt lgkmcnt(0)
	s_barrier
	v_mfma_f32_16x16x32_bf16 v[130:133], v[164:167], v[206:209], v[130:133]
	v_mfma_f32_16x16x32_bf16 v[126:129], v[172:175], v[206:209], v[126:129]
	v_mfma_f32_16x16x32_bf16 v[114:117], v[164:167], v[214:217], v[114:117]
	v_mfma_f32_16x16x32_bf16 v[110:113], v[172:175], v[214:217], v[110:113]
	v_mfma_f32_16x16x32_bf16 v[98:101], v[164:167], v[232:235], v[98:101]
	v_mfma_f32_16x16x32_bf16 v[94:97], v[172:175], v[232:235], v[94:97]
	v_mfma_f32_16x16x32_bf16 v[82:85], v[164:167], v[240:243], v[82:85]
	v_mfma_f32_16x16x32_bf16 v[78:81], v[172:175], v[240:243], v[78:81]
	v_mfma_f32_16x16x32_bf16 v[130:133], v[168:171], v[210:213], v[130:133]
	v_mfma_f32_16x16x32_bf16 v[126:129], v[176:179], v[210:213], v[126:129]
	v_mfma_f32_16x16x32_bf16 v[114:117], v[168:171], v[228:231], v[114:117]
	v_mfma_f32_16x16x32_bf16 v[110:113], v[176:179], v[228:231], v[110:113]
	v_mfma_f32_16x16x32_bf16 v[98:101], v[168:171], v[236:239], v[98:101]
	v_mfma_f32_16x16x32_bf16 v[94:97], v[176:179], v[236:239], v[94:97]
	v_mfma_f32_16x16x32_bf16 v[82:85], v[168:171], v[244:247], v[82:85]
	v_mfma_f32_16x16x32_bf16 v[78:81], v[176:179], v[244:247], v[78:81]
	v_mfma_f32_16x16x32_bf16 v[122:125], v[180:183], v[206:209], v[122:125]
	v_mfma_f32_16x16x32_bf16 v[118:121], v[198:201], v[206:209], v[118:121]
	v_mfma_f32_16x16x32_bf16 v[106:109], v[180:183], v[214:217], v[106:109]
	v_mfma_f32_16x16x32_bf16 v[102:105], v[198:201], v[214:217], v[102:105]
	v_mfma_f32_16x16x32_bf16 v[90:93], v[180:183], v[232:235], v[90:93]
	v_mfma_f32_16x16x32_bf16 v[86:89], v[198:201], v[232:235], v[86:89]
	v_mfma_f32_16x16x32_bf16 v[74:77], v[180:183], v[240:243], v[74:77]
	v_mfma_f32_16x16x32_bf16 v[70:73], v[198:201], v[240:243], v[70:73]
	v_mfma_f32_16x16x32_bf16 v[122:125], v[194:197], v[210:213], v[122:125]
	v_mfma_f32_16x16x32_bf16 v[118:121], v[202:205], v[210:213], v[118:121]
	v_mfma_f32_16x16x32_bf16 v[106:109], v[194:197], v[228:231], v[106:109]
	v_mfma_f32_16x16x32_bf16 v[102:105], v[202:205], v[228:231], v[102:105]
	v_mfma_f32_16x16x32_bf16 v[90:93], v[194:197], v[236:239], v[90:93]
	v_mfma_f32_16x16x32_bf16 v[86:89], v[202:205], v[236:239], v[86:89]
	v_mfma_f32_16x16x32_bf16 v[74:77], v[194:197], v[244:247], v[74:77]
	v_mfma_f32_16x16x32_bf16 v[70:73], v[202:205], v[244:247], v[70:73]
	s_barrier
	s_add_i32 s30, s45, 0x18000
	s_add_i32 m0, s30, 0xffffff80
	ds_read_b128 v[206:209], v163 offset:49152
	ds_read_b128 v[210:213], v163 offset:50176
	ds_read_b128 v[214:217], v163 offset:51200
	ds_read_b128 v[228:231], v163 offset:52224
	ds_read_b128 v[232:235], v163 offset:53248
	ds_read_b128 v[236:239], v163 offset:54272
	ds_read_b128 v[240:243], v163 offset:55296
	ds_read_b128 v[244:247], v163 offset:56320
	global_load_lds_dwordx4 v[150:151], off offset:128
	s_add_i32 m0, s30, 0x1f80
	s_add_i32 s30, s45, 0x1c000
	global_load_lds_dwordx4 v[184:185], off offset:128
	s_add_i32 m0, s30, 0xffffff80
	s_nop 0
	global_load_lds_dwordx4 v138, s[64:65] offset:128
	s_add_i32 m0, s30, 0x1f80
	s_nop 0
	global_load_lds_dwordx4 v134, s[64:65] offset:128
	s_add_i32 m0, s53, 0xffffff80
	s_nop 0
	global_load_lds_dwordx4 v[218:219], off offset:128
	s_add_i32 m0, s54, 0xffffff80
	s_nop 0
	global_load_lds_dwordx4 v[248:249], off offset:128
	s_waitcnt vmcnt(8)
	s_waitcnt lgkmcnt(0)
	s_barrier
	v_mfma_f32_16x16x32_bf16 v[66:69], v[164:167], v[206:209], v[66:69]
	v_mfma_f32_16x16x32_bf16 v[62:65], v[172:175], v[206:209], v[62:65]
	v_mfma_f32_16x16x32_bf16 v[50:53], v[164:167], v[214:217], v[50:53]
	v_mfma_f32_16x16x32_bf16 v[46:49], v[172:175], v[214:217], v[46:49]
	v_mfma_f32_16x16x32_bf16 v[34:37], v[164:167], v[232:235], v[34:37]
	v_mfma_f32_16x16x32_bf16 v[30:33], v[172:175], v[232:235], v[30:33]
	v_mfma_f32_16x16x32_bf16 v[18:21], v[164:167], v[240:243], v[18:21]
	v_mfma_f32_16x16x32_bf16 v[14:17], v[172:175], v[240:243], v[14:17]
	v_mfma_f32_16x16x32_bf16 v[66:69], v[168:171], v[210:213], v[66:69]
	v_mfma_f32_16x16x32_bf16 v[62:65], v[176:179], v[210:213], v[62:65]
	v_mfma_f32_16x16x32_bf16 v[50:53], v[168:171], v[228:231], v[50:53]
	v_mfma_f32_16x16x32_bf16 v[46:49], v[176:179], v[228:231], v[46:49]
	v_mfma_f32_16x16x32_bf16 v[34:37], v[168:171], v[236:239], v[34:37]
	v_mfma_f32_16x16x32_bf16 v[30:33], v[176:179], v[236:239], v[30:33]
	v_mfma_f32_16x16x32_bf16 v[18:21], v[168:171], v[244:247], v[18:21]
	v_mfma_f32_16x16x32_bf16 v[14:17], v[176:179], v[244:247], v[14:17]
	v_mfma_f32_16x16x32_bf16 v[58:61], v[180:183], v[206:209], v[58:61]
	v_mfma_f32_16x16x32_bf16 v[54:57], v[198:201], v[206:209], v[54:57]
	v_mfma_f32_16x16x32_bf16 v[42:45], v[180:183], v[214:217], v[42:45]
	v_mfma_f32_16x16x32_bf16 v[38:41], v[198:201], v[214:217], v[38:41]
	v_mfma_f32_16x16x32_bf16 v[26:29], v[180:183], v[232:235], v[26:29]
	v_mfma_f32_16x16x32_bf16 v[22:25], v[198:201], v[232:235], v[22:25]
	v_mfma_f32_16x16x32_bf16 v[10:13], v[180:183], v[240:243], v[10:13]
	v_mfma_f32_16x16x32_bf16 v[6:9], v[198:201], v[240:243], v[6:9]
	v_mfma_f32_16x16x32_bf16 v[58:61], v[194:197], v[210:213], v[58:61]
	v_mfma_f32_16x16x32_bf16 v[54:57], v[202:205], v[210:213], v[54:57]
	v_mfma_f32_16x16x32_bf16 v[42:45], v[194:197], v[228:231], v[42:45]
	v_mfma_f32_16x16x32_bf16 v[38:41], v[202:205], v[228:231], v[38:41]
	v_mfma_f32_16x16x32_bf16 v[26:29], v[194:197], v[236:239], v[26:29]
	v_mfma_f32_16x16x32_bf16 v[22:25], v[202:205], v[236:239], v[22:25]
	v_mfma_f32_16x16x32_bf16 v[10:13], v[194:197], v[244:247], v[10:13]
	v_mfma_f32_16x16x32_bf16 v[6:9], v[202:205], v[244:247], v[6:9]
	s_barrier
	s_add_u32 s28, s28, 0x100
	s_addc_u32 s29, s29, 0
	s_add_u32 s41, s41, 0x100
	s_addc_u32 s62, s62, 0
	s_cmp_ge_i32 s63, s55
	s_mov_b32 s30, s63
	s_cbranch_scc0 .LBB0_1074
	v_readlane_b32 s67, v255, 30

; #define PG8_STAGE(bufoff, gbase, voff) do { _Pragma("unroll") for (int _i = 0; _i < 2; ++_i) \
;         __builtin_amdgcn_global_load_lds((const unsigned*)((const char*)(gbase) + (voff)[_i]), (PG8_LAS unsigned*)(lds + (bufoff) + ldsw + _i * 8192), 16, 0, 0); } while (0)
; #define PG8_LDA(dst, b, h) do { _Pragma("unroll") for (int m = 0; m < 4; ++m) _Pragma("unroll") for (int k = 0; k < 2; ++k) dst[m][k] = *(const PG8_LAS bf16x8*)(lds + PG8_SA(b, h) + aoff + m * 2048 + k * 1024); } while (0)
; #define PG8_LDB(dst, b, h) do { _Pragma("unroll") for (int n = 0; n < 2; ++n) _Pragma("unroll") for (int k = 0; k < 2; ++k) dst[n][k] = *(const PG8_LAS bf16x8*)(lds + PG8_SB(b, h) + boff + n * 2048 + k * 1024); } while (0)
; #define PG8_MMA(ai, bj, At, Bt) do { __builtin_amdgcn_s_setprio(1); _Pragma("unroll") for (int m = 0; m < 4; ++m) _Pragma("unroll") for (int n = 0; n < 2; ++n) _Pragma("unroll") for (int k = 0; k < 2; ++k) \
;         acc[ai][bj][m][n] = __builtin_amdgcn_mfma_f32_16x16x32_bf16(Bt[n][k], At[m][k], acc[ai][bj][m][n], 0, 0, 0); __builtin_amdgcn_s_setprio(0); } while (0)
; #define PG8_WAIT_V(n) asm volatile("s_waitcnt vmcnt(" #n ")" ::: "memory")
; #define PG8_WAIT_L(n) asm volatile("s_waitcnt lgkmcnt(" #n ")" ::: "memory")
; template <class Epi, class Sched, bool ALIGN_EPI = false, bool SP2 = false>
; __device__ __forceinline__ void gemm_phase(PG8_LAS unsigned char* lds, const Gemm g, const Sched& S, const Epi& E, const int wv) {
;     ...
;             const bool last = (t == nt - 2);
;             const char* a1 = cA + (size_t)(t + 1) * kstep;
;             const char* a2 = last ? nA : cA + (size_t)(t + 2) * kstep; const char* b2 = last ? nB : cB + (size_t)(t + 2) * kstep;
;             const char* a3 = a2 + kstep; const char* b3 = b2 + kstep;
;             if (last && has_next) S.a_ready(nxt);
;             if constexpr (SP2) {
;             PG8_LDB(B0, 0, 0); PG8_LDB(B1, 0, 1); PG8_SCHED; PG8_LDA(At, 0, 0); PG8_STAGE(PG8_SA(1, 1), a1 + hstepA, voffA);
;             PG8_WAIT_V(8); PG8_WAIT_L(0); PG8_BAR; PG8_MMA(0, 0, At, B0); PG8_MMA(0, 1, At, B1); PG8_BAR; PG8_SCHED;
;             PG8_LDA(At, 0, 1); PG8_STAGE(PG8_SB(0, 0), b2, voffB); PG8_STAGE(PG8_SB(0, 1), b2 + hstepB, voffB); PG8_STAGE(PG8_SA(0, 0), a2, voffA);
;             PG8_WAIT_V(8); PG8_WAIT_L(0); PG8_BAR; PG8_MMA(1, 0, At, B0); PG8_MMA(1, 1, At, B1); PG8_BAR; PG8_SCHED;
.LBB0_1385:
	s_add_i32 s70, s52, 2
	s_add_u32 s71, s44, 0xfffc0080
	s_addc_u32 s53, s45, -1
	s_cmp_eq_u32 s65, s52
	s_cselect_b32 s53, s13, s53
	s_cselect_b32 s52, s19, s71
	s_cselect_b32 s73, s15, s55
	s_cselect_b32 s72, s14, s54
	ds_read_b128 v[114:117], v201
	ds_read_b128 v[126:129], v201 offset:1024
	ds_read_b128 v[138:141], v201 offset:2048
	ds_read_b128 v[142:145], v201 offset:3072
	ds_read_b128 v[146:149], v203
	ds_read_b128 v[150:153], v203 offset:1024
	ds_read_b128 v[154:157], v203 offset:2048
	ds_read_b128 v[158:161], v203 offset:3072
	s_add_i32 m0, s51, 0xc000
	ds_read_b128 v[162:165], v235
	ds_read_b128 v[166:169], v235 offset:1024
	ds_read_b128 v[170:173], v235 offset:2048
	ds_read_b128 v[174:177], v235 offset:3072
	ds_read_b128 v[178:181], v235 offset:4096
	ds_read_b128 v[182:185], v235 offset:5120
	ds_read_b128 v[204:207], v235 offset:6144
	ds_read_b128 v[208:211], v235 offset:7168
	global_load_lds_dwordx4 v200, s[44:45]
	s_add_i32 m0, s51, 0xe000
	s_nop 0
	global_load_lds_dwordx4 v202, s[44:45]
	s_waitcnt vmcnt(8)
	s_waitcnt lgkmcnt(0)
	s_barrier
	v_mfma_f32_16x16x32_bf16 v[134:137], v[114:117], v[162:165], v[134:137]
	v_mfma_f32_16x16x32_bf16 v[130:133], v[138:141], v[162:165], v[130:133]
	v_mfma_f32_16x16x32_bf16 v[110:113], v[114:117], v[170:173], v[110:113]
	v_mfma_f32_16x16x32_bf16 v[106:109], v[138:141], v[170:173], v[106:109]
	v_mfma_f32_16x16x32_bf16 v[94:97], v[114:117], v[178:181], v[94:97]
	v_mfma_f32_16x16x32_bf16 v[90:93], v[138:141], v[178:181], v[90:93]
	v_mfma_f32_16x16x32_bf16 v[78:81], v[114:117], v[204:207], v[78:81]
	v_mfma_f32_16x16x32_bf16 v[74:77], v[138:141], v[204:207], v[74:77]
	v_mfma_f32_16x16x32_bf16 v[134:137], v[126:129], v[166:169], v[134:137]
	v_mfma_f32_16x16x32_bf16 v[130:133], v[142:145], v[166:169], v[130:133]
	v_mfma_f32_16x16x32_bf16 v[110:113], v[126:129], v[174:177], v[110:113]
	v_mfma_f32_16x16x32_bf16 v[106:109], v[142:145], v[174:177], v[106:109]
	v_mfma_f32_16x16x32_bf16 v[94:97], v[126:129], v[182:185], v[94:97]
	v_mfma_f32_16x16x32_bf16 v[90:93], v[142:145], v[182:185], v[90:93]
	v_mfma_f32_16x16x32_bf16 v[78:81], v[126:129], v[208:211], v[78:81]
	v_mfma_f32_16x16x32_bf16 v[74:77], v[142:145], v[208:211], v[74:77]
	v_mfma_f32_16x16x32_bf16 v[122:125], v[146:149], v[162:165], v[122:125]
	v_mfma_f32_16x16x32_bf16 v[118:121], v[154:157], v[162:165], v[118:121]
	v_mfma_f32_16x16x32_bf16 v[102:105], v[146:149], v[170:173], v[102:105]
	v_mfma_f32_16x16x32_bf16 v[98:101], v[154:157], v[170:173], v[98:101]
	v_mfma_f32_16x16x32_bf16 v[86:89], v[146:149], v[178:181], v[86:89]
	v_mfma_f32_16x16x32_bf16 v[82:85], v[154:157], v[178:181], v[82:85]
	v_mfma_f32_16x16x32_bf16 v[70:73], v[146:149], v[204:207], v[70:73]
	v_mfma_f32_16x16x32_bf16 v[66:69], v[154:157], v[204:207], v[66:69]
	v_mfma_f32_16x16x32_bf16 v[122:125], v[150:153], v[166:169], v[122:125]
	v_mfma_f32_16x16x32_bf16 v[118:121], v[158:161], v[166:169], v[118:121]
	v_mfma_f32_16x16x32_bf16 v[102:105], v[150:153], v[174:177], v[102:105]
	v_mfma_f32_16x16x32_bf16 v[98:101], v[158:161], v[174:177], v[98:101]
	v_mfma_f32_16x16x32_bf16 v[86:89], v[150:153], v[182:185], v[86:89]
	v_mfma_f32_16x16x32_bf16 v[82:85], v[158:161], v[182:185], v[82:85]
	v_mfma_f32_16x16x32_bf16 v[70:73], v[150:153], v[208:211], v[70:73]
	v_mfma_f32_16x16x32_bf16 v[66:69], v[158:161], v[208:211], v[66:69]
	s_barrier
	s_add_i32 s74, s3, 0x10000
	v_lshl_add_u64 v[190:191], s[72:73], 0, v[0:1]
	s_mov_b32 m0, s74
	ds_read_b128 v[162:165], v235 offset:16384
	ds_read_b128 v[166:169], v235 offset:17408
	ds_read_b128 v[170:173], v235 offset:18432
	ds_read_b128 v[174:177], v235 offset:19456
	ds_read_b128 v[178:181], v235 offset:20480
	ds_read_b128 v[182:185], v235 offset:21504
	ds_read_b128 v[204:207], v235 offset:22528
	ds_read_b128 v[208:211], v235 offset:23552
	global_load_lds_dwordx4 v[190:191], off
	s_add_i32 m0, s74, 0x2000
	v_lshl_add_u64 v[192:193], s[72:73], 0, v[198:199]
	s_add_u32 s72, s72, s24
	s_addc_u32 s73, s73, s25
	s_add_i32 s71, s3, 0x14000
	global_load_lds_dwordx4 v[192:193], off
	s_mov_b32 m0, s71
	global_load_lds_dwordx4 v0, s[72:73]
	s_add_i32 m0, s71, 0x2000
	v_lshl_add_u64 v[216:217], s[52:53], 0, v[194:195]
	global_load_lds_dwordx4 v198, s[72:73]
	s_mov_b32 m0, s51
	v_lshl_add_u64 v[218:219], s[52:53], 0, v[196:197]
	global_load_lds_dwordx4 v[216:217], off
	s_mov_b32 m0, s59
	s_nop 0
	global_load_lds_dwordx4 v[218:219], off
	s_waitcnt vmcnt(8)
	s_waitcnt lgkmcnt(0)
	s_barrier
	v_mfma_f32_16x16x32_bf16 v[62:65], v[114:117], v[162:165], v[62:65]
	v_mfma_f32_16x16x32_bf16 v[58:61], v[138:141], v[162:165], v[58:61]
	v_mfma_f32_16x16x32_bf16 v[46:49], v[114:117], v[170:173], v[46:49]
	v_mfma_f32_16x16x32_bf16 v[42:45], v[138:141], v[170:173], v[42:45]
	v_mfma_f32_16x16x32_bf16 v[30:33], v[114:117], v[178:181], v[30:33]
	v_mfma_f32_16x16x32_bf16 v[26:29], v[138:141], v[178:181], v[26:29]
	v_mfma_f32_16x16x32_bf16 v[14:17], v[114:117], v[204:207], v[14:17]
	v_mfma_f32_16x16x32_bf16 v[10:13], v[138:141], v[204:207], v[10:13]
	v_mfma_f32_16x16x32_bf16 v[62:65], v[126:129], v[166:169], v[62:65]
	v_mfma_f32_16x16x32_bf16 v[58:61], v[142:145], v[166:169], v[58:61]
	v_mfma_f32_16x16x32_bf16 v[46:49], v[126:129], v[174:177], v[46:49]
	v_mfma_f32_16x16x32_bf16 v[42:45], v[142:145], v[174:177], v[42:45]
	v_mfma_f32_16x16x32_bf16 v[30:33], v[126:129], v[182:185], v[30:33]
	v_mfma_f32_16x16x32_bf16 v[26:29], v[142:145], v[182:185], v[26:29]
	v_mfma_f32_16x16x32_bf16 v[14:17], v[126:129], v[208:211], v[14:17]
	v_mfma_f32_16x16x32_bf16 v[10:13], v[142:145], v[208:211], v[10:13]
	v_mfma_f32_16x16x32_bf16 v[54:57], v[146:149], v[162:165], v[54:57]
	v_mfma_f32_16x16x32_bf16 v[50:53], v[154:157], v[162:165], v[50:53]
	v_mfma_f32_16x16x32_bf16 v[38:41], v[146:149], v[170:173], v[38:41]
	v_mfma_f32_16x16x32_bf16 v[34:37], v[154:157], v[170:173], v[34:37]
	v_mfma_f32_16x16x32_bf16 v[22:25], v[146:149], v[178:181], v[22:25]
	v_mfma_f32_16x16x32_bf16 v[18:21], v[154:157], v[178:181], v[18:21]
	v_mfma_f32_16x16x32_bf16 v[6:9], v[146:149], v[204:207], v[6:9]
	v_mfma_f32_16x16x32_bf16 v[2:5], v[154:157], v[204:207], v[2:5]
	v_mfma_f32_16x16x32_bf16 v[54:57], v[150:153], v[166:169], v[54:57]
	v_mfma_f32_16x16x32_bf16 v[50:53], v[158:161], v[166:169], v[50:53]
	v_mfma_f32_16x16x32_bf16 v[38:41], v[150:153], v[174:177], v[38:41]
	v_mfma_f32_16x16x32_bf16 v[34:37], v[158:161], v[174:177], v[34:37]
	v_mfma_f32_16x16x32_bf16 v[22:25], v[150:153], v[182:185], v[22:25]
	v_mfma_f32_16x16x32_bf16 v[18:21], v[158:161], v[182:185], v[18:21]
	v_mfma_f32_16x16x32_bf16 v[6:9], v[150:153], v[208:211], v[6:9]
	v_mfma_f32_16x16x32_bf16 v[2:5], v[158:161], v[208:211], v[2:5]
	s_barrier
; #define PG8_STAGE(bufoff, gbase, voff) do { _Pragma("unroll") for (int _i = 0; _i < 2; ++_i) \
;         __builtin_amdgcn_global_load_lds((const unsigned*)((const char*)(gbase) + (voff)[_i]), (PG8_LAS unsigned*)(lds + (bufoff) + ldsw + _i * 8192), 16, 0, 0); } while (0)
; #define PG8_LDA(dst, b, h) do { _Pragma("unroll") for (int m = 0; m < 4; ++m) _Pragma("unroll") for (int k = 0; k < 2; ++k) dst[m][k] = *(const PG8_LAS bf16x8*)(lds + PG8_SA(b, h) + aoff + m * 2048 + k * 1024); } while (0)
; #define PG8_LDB(dst, b, h) do { _Pragma("unroll") for (int n = 0; n < 2; ++n) _Pragma("unroll") for (int k = 0; k < 2; ++k) dst[n][k] = *(const PG8_LAS bf16x8*)(lds + PG8_SB(b, h) + boff + n * 2048 + k * 1024); } while (0)
; #define PG8_MMA(ai, bj, At, Bt) do { __builtin_amdgcn_s_setprio(1); _Pragma("unroll") for (int m = 0; m < 4; ++m) _Pragma("unroll") for (int n = 0; n < 2; ++n) _Pragma("unroll") for (int k = 0; k < 2; ++k) \
;         acc[ai][bj][m][n] = __builtin_amdgcn_mfma_f32_16x16x32_bf16(Bt[n][k], At[m][k], acc[ai][bj][m][n], 0, 0, 0); __builtin_amdgcn_s_setprio(0); } while (0)
; #define PG8_WAIT_V(n) asm volatile("s_waitcnt vmcnt(" #n ")" ::: "memory")
; #define PG8_WAIT_L(n) asm volatile("s_waitcnt lgkmcnt(" #n ")" ::: "memory")
; #define PG8_BAR __builtin_amdgcn_s_barrier()
; #define PG8_SCHED __builtin_amdgcn_sched_barrier(0)
; template <class Epi, class Sched, bool ALIGN_EPI = false, bool SP2 = false>
; __device__ __forceinline__ void gemm_phase(PG8_LAS unsigned char* lds, const Gemm g, const Sched& S, const Epi& E, const int wv) {
;     ...
;             PG8_LDB(B0, 1, 0); PG8_LDB(B1, 1, 1); PG8_SCHED; PG8_LDA(At, 1, 0); PG8_STAGE(PG8_SA(0, 1), a2 + hstepA, voffA);
;             PG8_WAIT_V(8); PG8_WAIT_L(0); PG8_BAR; PG8_MMA(0, 0, At, B0); PG8_MMA(0, 1, At, B1); PG8_BAR; PG8_SCHED;
;             PG8_LDA(At, 1, 1); PG8_STAGE(PG8_SB(1, 0), b3, voffB); PG8_STAGE(PG8_SB(1, 1), b3 + hstepB, voffB); PG8_STAGE(PG8_SA(1, 0), a3, voffA);
;             PG8_WAIT_V(8); PG8_WAIT_L(0); PG8_BAR; PG8_MMA(1, 0, At, B0); PG8_MMA(1, 1, At, B1); PG8_BAR; PG8_SCHED;
	ds_read_b128 v[114:117], v236
	ds_read_b128 v[126:129], v236 offset:1024
	ds_read_b128 v[138:141], v236 offset:2048
	ds_read_b128 v[142:145], v236 offset:3072
	ds_read_b128 v[146:149], v237
	ds_read_b128 v[150:153], v237 offset:1024
	ds_read_b128 v[154:157], v237 offset:2048
	ds_read_b128 v[158:161], v237 offset:3072
	s_add_u32 s52, s52, 0x40000
	s_addc_u32 s53, s53, 0
	s_mov_b32 m0, s60
	ds_read_b128 v[162:165], v235 offset:32768
	ds_read_b128 v[166:169], v235 offset:33792
	ds_read_b128 v[170:173], v235 offset:34816
	ds_read_b128 v[174:177], v235 offset:35840
	ds_read_b128 v[178:181], v235 offset:36864
	ds_read_b128 v[182:185], v235 offset:37888
	ds_read_b128 v[204:207], v235 offset:38912
	ds_read_b128 v[208:211], v235 offset:39936
	global_load_lds_dwordx4 v194, s[52:53]
	s_mov_b32 m0, s61
	s_nop 0
	global_load_lds_dwordx4 v196, s[52:53]
	s_waitcnt vmcnt(8)
	s_waitcnt lgkmcnt(0)
	s_barrier
	v_mfma_f32_16x16x32_bf16 v[134:137], v[114:117], v[162:165], v[134:137]
	v_mfma_f32_16x16x32_bf16 v[130:133], v[138:141], v[162:165], v[130:133]
	v_mfma_f32_16x16x32_bf16 v[110:113], v[114:117], v[170:173], v[110:113]
	v_mfma_f32_16x16x32_bf16 v[106:109], v[138:141], v[170:173], v[106:109]
	v_mfma_f32_16x16x32_bf16 v[94:97], v[114:117], v[178:181], v[94:97]
	v_mfma_f32_16x16x32_bf16 v[90:93], v[138:141], v[178:181], v[90:93]
	v_mfma_f32_16x16x32_bf16 v[78:81], v[114:117], v[204:207], v[78:81]
	v_mfma_f32_16x16x32_bf16 v[74:77], v[138:141], v[204:207], v[74:77]
	v_mfma_f32_16x16x32_bf16 v[134:137], v[126:129], v[166:169], v[134:137]
	v_mfma_f32_16x16x32_bf16 v[130:133], v[142:145], v[166:169], v[130:133]
	v_mfma_f32_16x16x32_bf16 v[110:113], v[126:129], v[174:177], v[110:113]
	v_mfma_f32_16x16x32_bf16 v[106:109], v[142:145], v[174:177], v[106:109]
	v_mfma_f32_16x16x32_bf16 v[94:97], v[126:129], v[182:185], v[94:97]
	v_mfma_f32_16x16x32_bf16 v[90:93], v[142:145], v[182:185], v[90:93]
	v_mfma_f32_16x16x32_bf16 v[78:81], v[126:129], v[208:211], v[78:81]
	v_mfma_f32_16x16x32_bf16 v[74:77], v[142:145], v[208:211], v[74:77]
	v_mfma_f32_16x16x32_bf16 v[122:125], v[146:149], v[162:165], v[122:125]
	v_mfma_f32_16x16x32_bf16 v[118:121], v[154:157], v[162:165], v[118:121]
	v_mfma_f32_16x16x32_bf16 v[102:105], v[146:149], v[170:173], v[102:105]
	v_mfma_f32_16x16x32_bf16 v[98:101], v[154:157], v[170:173], v[98:101]
	v_mfma_f32_16x16x32_bf16 v[86:89], v[146:149], v[178:181], v[86:89]
	v_mfma_f32_16x16x32_bf16 v[82:85], v[154:157], v[178:181], v[82:85]
	v_mfma_f32_16x16x32_bf16 v[70:73], v[146:149], v[204:207], v[70:73]
	v_mfma_f32_16x16x32_bf16 v[66:69], v[154:157], v[204:207], v[66:69]
	v_mfma_f32_16x16x32_bf16 v[122:125], v[150:153], v[166:169], v[122:125]
	v_mfma_f32_16x16x32_bf16 v[118:121], v[158:161], v[166:169], v[118:121]
	v_mfma_f32_16x16x32_bf16 v[102:105], v[150:153], v[174:177], v[102:105]
	v_mfma_f32_16x16x32_bf16 v[98:101], v[158:161], v[174:177], v[98:101]
	v_mfma_f32_16x16x32_bf16 v[86:89], v[150:153], v[182:185], v[86:89]
	v_mfma_f32_16x16x32_bf16 v[82:85], v[158:161], v[182:185], v[82:85]
	v_mfma_f32_16x16x32_bf16 v[70:73], v[150:153], v[208:211], v[70:73]
	v_mfma_f32_16x16x32_bf16 v[66:69], v[158:161], v[208:211], v[66:69]
	s_barrier
	s_add_i32 s52, s3, 0x18000
	s_add_i32 m0, s52, 0xffffff80
	ds_read_b128 v[162:165], v235 offset:49152
	ds_read_b128 v[166:169], v235 offset:50176
	ds_read_b128 v[170:173], v235 offset:51200
	ds_read_b128 v[174:177], v235 offset:52224
	ds_read_b128 v[178:181], v235 offset:53248
	ds_read_b128 v[182:185], v235 offset:54272
	ds_read_b128 v[204:207], v235 offset:55296
	ds_read_b128 v[208:211], v235 offset:56320
	global_load_lds_dwordx4 v[190:191], off offset:128
	s_add_i32 m0, s52, 0x1f80
	s_add_i32 s52, s3, 0x1c000
	global_load_lds_dwordx4 v[192:193], off offset:128
	s_add_i32 m0, s52, 0xffffff80
	s_nop 0
	global_load_lds_dwordx4 v0, s[72:73] offset:128
	s_add_i32 m0, s52, 0x1f80
	s_nop 0
	global_load_lds_dwordx4 v198, s[72:73] offset:128
	s_add_i32 m0, s63, 0xffffff80
	s_nop 0
	global_load_lds_dwordx4 v[216:217], off offset:128
	s_add_i32 m0, s64, 0xffffff80
	s_nop 0
	global_load_lds_dwordx4 v[218:219], off offset:128
	s_waitcnt vmcnt(8)
	s_waitcnt lgkmcnt(0)
	s_barrier
	v_mfma_f32_16x16x32_bf16 v[62:65], v[114:117], v[162:165], v[62:65]
	v_mfma_f32_16x16x32_bf16 v[58:61], v[138:141], v[162:165], v[58:61]
	v_mfma_f32_16x16x32_bf16 v[46:49], v[114:117], v[170:173], v[46:49]
	v_mfma_f32_16x16x32_bf16 v[42:45], v[138:141], v[170:173], v[42:45]
	v_mfma_f32_16x16x32_bf16 v[30:33], v[114:117], v[178:181], v[30:33]
	v_mfma_f32_16x16x32_bf16 v[26:29], v[138:141], v[178:181], v[26:29]
	v_mfma_f32_16x16x32_bf16 v[14:17], v[114:117], v[204:207], v[14:17]
	v_mfma_f32_16x16x32_bf16 v[10:13], v[138:141], v[204:207], v[10:13]
	v_mfma_f32_16x16x32_bf16 v[62:65], v[126:129], v[166:169], v[62:65]
	v_mfma_f32_16x16x32_bf16 v[58:61], v[142:145], v[166:169], v[58:61]
	v_mfma_f32_16x16x32_bf16 v[46:49], v[126:129], v[174:177], v[46:49]
	v_mfma_f32_16x16x32_bf16 v[42:45], v[142:145], v[174:177], v[42:45]
	v_mfma_f32_16x16x32_bf16 v[30:33], v[126:129], v[182:185], v[30:33]
	v_mfma_f32_16x16x32_bf16 v[26:29], v[142:145], v[182:185], v[26:29]
	v_mfma_f32_16x16x32_bf16 v[14:17], v[126:129], v[208:211], v[14:17]
	v_mfma_f32_16x16x32_bf16 v[10:13], v[142:145], v[208:211], v[10:13]
	v_mfma_f32_16x16x32_bf16 v[54:57], v[146:149], v[162:165], v[54:57]
	v_mfma_f32_16x16x32_bf16 v[50:53], v[154:157], v[162:165], v[50:53]
	v_mfma_f32_16x16x32_bf16 v[38:41], v[146:149], v[170:173], v[38:41]
	v_mfma_f32_16x16x32_bf16 v[34:37], v[154:157], v[170:173], v[34:37]
	v_mfma_f32_16x16x32_bf16 v[22:25], v[146:149], v[178:181], v[22:25]
	v_mfma_f32_16x16x32_bf16 v[18:21], v[154:157], v[178:181], v[18:21]
	v_mfma_f32_16x16x32_bf16 v[6:9], v[146:149], v[204:207], v[6:9]
	v_mfma_f32_16x16x32_bf16 v[2:5], v[154:157], v[204:207], v[2:5]
	v_mfma_f32_16x16x32_bf16 v[54:57], v[150:153], v[166:169], v[54:57]
	v_mfma_f32_16x16x32_bf16 v[50:53], v[158:161], v[166:169], v[50:53]
	v_mfma_f32_16x16x32_bf16 v[38:41], v[150:153], v[174:177], v[38:41]
	v_mfma_f32_16x16x32_bf16 v[34:37], v[158:161], v[174:177], v[34:37]
	v_mfma_f32_16x16x32_bf16 v[22:25], v[150:153], v[182:185], v[22:25]
	v_mfma_f32_16x16x32_bf16 v[18:21], v[158:161], v[182:185], v[18:21]
	v_mfma_f32_16x16x32_bf16 v[6:9], v[150:153], v[208:211], v[6:9]
	v_mfma_f32_16x16x32_bf16 v[2:5], v[158:161], v[208:211], v[2:5]
	s_barrier
	s_add_u32 s44, s44, 0x100
	s_addc_u32 s45, s45, 0
	s_add_u32 s54, s54, 0x100
	s_addc_u32 s55, s55, 0
	s_cmp_ge_i32 s70, s62
	s_mov_b32 s52, s70
	s_cbranch_scc0 .LBB0_1385
	s_mov_b32 s72, 0x10000
	s_mov_b32 s73, 0x12000
	s_mov_b32 s74, 0x14000
	s_mov_b32 s70, 0x18000
	s_mov_b32 s71, 0x3f317217
	s_and_b64 vcc, exec, s[46:47]
	s_cbranch_vccz .LBB0_1361

; #define PG8_STAGE(bufoff, gbase, voff) do { _Pragma("unroll") for (int _i = 0; _i < 2; ++_i) \
;         __builtin_amdgcn_global_load_lds((const unsigned*)((const char*)(gbase) + (voff)[_i]), (PG8_LAS unsigned*)(lds + (bufoff) + ldsw + _i * 8192), 16, 0, 0); } while (0)
; #define PG8_LDA(dst, b, h) do { _Pragma("unroll") for (int m = 0; m < 4; ++m) _Pragma("unroll") for (int k = 0; k < 2; ++k) dst[m][k] = *(const PG8_LAS bf16x8*)(lds + PG8_SA(b, h) + aoff + m * 2048 + k * 1024); } while (0)
; #define PG8_LDB(dst, b, h) do { _Pragma("unroll") for (int n = 0; n < 2; ++n) _Pragma("unroll") for (int k = 0; k < 2; ++k) dst[n][k] = *(const PG8_LAS bf16x8*)(lds + PG8_SB(b, h) + boff + n * 2048 + k * 1024); } while (0)
; #define PG8_MMA(ai, bj, At, Bt) do { __builtin_amdgcn_s_setprio(1); _Pragma("unroll") for (int m = 0; m < 4; ++m) _Pragma("unroll") for (int n = 0; n < 2; ++n) _Pragma("unroll") for (int k = 0; k < 2; ++k) \
;         acc[ai][bj][m][n] = __builtin_amdgcn_mfma_f32_16x16x32_bf16(Bt[n][k], At[m][k], acc[ai][bj][m][n], 0, 0, 0); __builtin_amdgcn_s_setprio(0); } while (0)
; #define PG8_WAIT_V(n) asm volatile("s_waitcnt vmcnt(" #n ")" ::: "memory")
; #define PG8_WAIT_L(n) asm volatile("s_waitcnt lgkmcnt(" #n ")" ::: "memory")
; template <class Epi, class Sched, bool ALIGN_EPI = false, bool SP2 = false>
; __device__ __forceinline__ void gemm_phase(PG8_LAS unsigned char* lds, const Gemm g, const Sched& S, const Epi& E, const int wv) {
;     ...
;             const bool last = (t == nt - 2);
;             const char* a1 = cA + (size_t)(t + 1) * kstep;
;             const char* a2 = last ? nA : cA + (size_t)(t + 2) * kstep; const char* b2 = last ? nB : cB + (size_t)(t + 2) * kstep;
;             const char* a3 = a2 + kstep; const char* b3 = b2 + kstep;
;             if (last && has_next) S.a_ready(nxt);
;             if constexpr (SP2) {
;             PG8_LDB(B0, 0, 0); PG8_LDB(B1, 0, 1); PG8_SCHED; PG8_LDA(At, 0, 0); PG8_STAGE(PG8_SA(1, 1), a1 + hstepA, voffA);
;             PG8_WAIT_V(8); PG8_WAIT_L(0); PG8_BAR; PG8_MMA(0, 0, At, B0); PG8_MMA(0, 1, At, B1); PG8_BAR; PG8_SCHED;
;             PG8_LDA(At, 0, 1); PG8_STAGE(PG8_SB(0, 0), b2, voffB); PG8_STAGE(PG8_SB(0, 1), b2 + hstepB, voffB); PG8_STAGE(PG8_SA(0, 0), a2, voffA);
;             PG8_WAIT_V(8); PG8_WAIT_L(0); PG8_BAR; PG8_MMA(1, 0, At, B0); PG8_MMA(1, 1, At, B1); PG8_BAR; PG8_SCHED;
.LBB0_1495:
	s_add_i32 s52, s46, 2
	s_add_u32 s14, s48, 0x100
	s_addc_u32 s15, s49, 0
	s_cmp_eq_u32 s72, s46
	s_cselect_b32 s47, s11, s15
	s_cselect_b32 s46, s13, s14
	s_cselect_b32 s77, s87, s51
	s_cselect_b32 s76, s86, s35
	ds_read_b128 v[138:141], v192
	ds_read_b128 v[142:145], v192 offset:1024
	ds_read_b128 v[146:149], v192 offset:2048
	ds_read_b128 v[150:153], v192 offset:3072
	ds_read_b128 v[154:157], v193
	ds_read_b128 v[158:161], v193 offset:1024
	ds_read_b128 v[162:165], v193 offset:2048
	ds_read_b128 v[166:169], v193 offset:3072
	s_add_i32 m0, s64, 0xc000
	ds_read_b128 v[194:197], v211
	ds_read_b128 v[198:201], v211 offset:1024
	ds_read_b128 v[202:205], v211 offset:2048
	ds_read_b128 v[214:217], v211 offset:3072
	ds_read_b128 v[228:231], v211 offset:4096
	ds_read_b128 v[232:235], v211 offset:5120
	ds_read_b128 v[236:239], v211 offset:6144
	ds_read_b128 v[240:243], v211 offset:7168
	global_load_lds_dwordx4 v182, s[48:49]
	v_lshl_add_u64 v[190:191], s[48:49], 0, v[184:185]
	s_add_i32 m0, s64, 0xe000
	s_nop 0
	global_load_lds_dwordx4 v[190:191], off
	s_waitcnt vmcnt(8)
	s_waitcnt lgkmcnt(0)
	s_barrier
	v_mfma_f32_16x16x32_bf16 v[118:121], v[138:141], v[194:197], v[118:121]
	v_mfma_f32_16x16x32_bf16 v[46:49], v[146:149], v[194:197], v[46:49]
	v_mfma_f32_16x16x32_bf16 v[110:113], v[138:141], v[202:205], v[110:113]
	v_mfma_f32_16x16x32_bf16 v[38:41], v[146:149], v[202:205], v[38:41]
	v_mfma_f32_16x16x32_bf16 v[134:137], v[138:141], v[228:231], v[134:137]
	v_mfma_f32_16x16x32_bf16 v[62:65], v[146:149], v[228:231], v[62:65]
	v_mfma_f32_16x16x32_bf16 v[130:133], v[138:141], v[236:239], v[130:133]
	v_mfma_f32_16x16x32_bf16 v[58:61], v[146:149], v[236:239], v[58:61]
	v_mfma_f32_16x16x32_bf16 v[118:121], v[142:145], v[198:201], v[118:121]
	v_mfma_f32_16x16x32_bf16 v[46:49], v[150:153], v[198:201], v[46:49]
	v_mfma_f32_16x16x32_bf16 v[110:113], v[142:145], v[214:217], v[110:113]
	v_mfma_f32_16x16x32_bf16 v[38:41], v[150:153], v[214:217], v[38:41]
	v_mfma_f32_16x16x32_bf16 v[134:137], v[142:145], v[232:235], v[134:137]
	v_mfma_f32_16x16x32_bf16 v[62:65], v[150:153], v[232:235], v[62:65]
	v_mfma_f32_16x16x32_bf16 v[130:133], v[142:145], v[240:243], v[130:133]
	v_mfma_f32_16x16x32_bf16 v[58:61], v[150:153], v[240:243], v[58:61]
	v_mfma_f32_16x16x32_bf16 v[114:117], v[154:157], v[194:197], v[114:117]
	v_mfma_f32_16x16x32_bf16 v[42:45], v[162:165], v[194:197], v[42:45]
	v_mfma_f32_16x16x32_bf16 v[106:109], v[154:157], v[202:205], v[106:109]
	v_mfma_f32_16x16x32_bf16 v[34:37], v[162:165], v[202:205], v[34:37]
	v_mfma_f32_16x16x32_bf16 v[126:129], v[154:157], v[228:231], v[126:129]
	v_mfma_f32_16x16x32_bf16 v[54:57], v[162:165], v[228:231], v[54:57]
	v_mfma_f32_16x16x32_bf16 v[122:125], v[154:157], v[236:239], v[122:125]
	v_mfma_f32_16x16x32_bf16 v[50:53], v[162:165], v[236:239], v[50:53]
	v_mfma_f32_16x16x32_bf16 v[114:117], v[158:161], v[198:201], v[114:117]
	v_mfma_f32_16x16x32_bf16 v[42:45], v[166:169], v[198:201], v[42:45]
	v_mfma_f32_16x16x32_bf16 v[106:109], v[158:161], v[214:217], v[106:109]
	v_mfma_f32_16x16x32_bf16 v[34:37], v[166:169], v[214:217], v[34:37]
	v_mfma_f32_16x16x32_bf16 v[126:129], v[158:161], v[232:235], v[126:129]
	v_mfma_f32_16x16x32_bf16 v[54:57], v[166:169], v[232:235], v[54:57]
	v_mfma_f32_16x16x32_bf16 v[122:125], v[158:161], v[240:243], v[122:125]
	v_mfma_f32_16x16x32_bf16 v[50:53], v[166:169], v[240:243], v[50:53]
	s_barrier
	s_add_i32 s48, s63, 0x10000
	s_mov_b32 m0, s48
	ds_read_b128 v[194:197], v211 offset:16384
	ds_read_b128 v[198:201], v211 offset:17408
	ds_read_b128 v[202:205], v211 offset:18432
	ds_read_b128 v[214:217], v211 offset:19456
	ds_read_b128 v[228:231], v211 offset:20480
	ds_read_b128 v[232:235], v211 offset:21504
	ds_read_b128 v[236:239], v211 offset:22528
	ds_read_b128 v[240:243], v211 offset:23552
	global_load_lds_dwordx4 v0, s[76:77]
	s_add_i32 m0, s48, 0x2000
	s_add_u32 s48, s76, s16
	s_addc_u32 s49, s77, s17
	s_add_i32 s53, s63, 0x14000
	global_load_lds_dwordx4 v174, s[76:77]
	s_mov_b32 m0, s53
	global_load_lds_dwordx4 v0, s[48:49]
	s_add_i32 m0, s53, 0x2000
	v_lshl_add_u64 v[246:247], s[46:47], 0, v[170:171]
	global_load_lds_dwordx4 v174, s[48:49]
	s_mov_b32 m0, s64
	v_lshl_add_u64 v[248:249], s[46:47], 0, v[172:173]
	global_load_lds_dwordx4 v[246:247], off
	s_mov_b32 m0, s65
	s_nop 0
	global_load_lds_dwordx4 v[248:249], off
	s_waitcnt vmcnt(8)
	s_waitcnt lgkmcnt(0)
	s_barrier
	v_mfma_f32_16x16x32_bf16 v[86:89], v[138:141], v[194:197], v[86:89]
	v_mfma_f32_16x16x32_bf16 v[14:17], v[146:149], v[194:197], v[14:17]
	v_mfma_f32_16x16x32_bf16 v[70:73], v[138:141], v[202:205], v[70:73]
	v_mfma_f32_16x16x32_bf16 v[6:9], v[146:149], v[202:205], v[6:9]
	v_mfma_f32_16x16x32_bf16 v[102:105], v[138:141], v[228:231], v[102:105]
	v_mfma_f32_16x16x32_bf16 v[30:33], v[146:149], v[228:231], v[30:33]
	v_mfma_f32_16x16x32_bf16 v[98:101], v[138:141], v[236:239], v[98:101]
	v_mfma_f32_16x16x32_bf16 v[26:29], v[146:149], v[236:239], v[26:29]
	v_mfma_f32_16x16x32_bf16 v[86:89], v[142:145], v[198:201], v[86:89]
	v_mfma_f32_16x16x32_bf16 v[14:17], v[150:153], v[198:201], v[14:17]
	v_mfma_f32_16x16x32_bf16 v[70:73], v[142:145], v[214:217], v[70:73]
	v_mfma_f32_16x16x32_bf16 v[6:9], v[150:153], v[214:217], v[6:9]
	v_mfma_f32_16x16x32_bf16 v[102:105], v[142:145], v[232:235], v[102:105]
	v_mfma_f32_16x16x32_bf16 v[30:33], v[150:153], v[232:235], v[30:33]
	v_mfma_f32_16x16x32_bf16 v[98:101], v[142:145], v[240:243], v[98:101]
	v_mfma_f32_16x16x32_bf16 v[26:29], v[150:153], v[240:243], v[26:29]
	v_mfma_f32_16x16x32_bf16 v[82:85], v[154:157], v[194:197], v[82:85]
	v_mfma_f32_16x16x32_bf16 v[10:13], v[162:165], v[194:197], v[10:13]
	v_mfma_f32_16x16x32_bf16 v[66:69], v[154:157], v[202:205], v[66:69]
	v_mfma_f32_16x16x32_bf16 v[2:5], v[162:165], v[202:205], v[2:5]
	v_mfma_f32_16x16x32_bf16 v[94:97], v[154:157], v[228:231], v[94:97]
	v_mfma_f32_16x16x32_bf16 v[22:25], v[162:165], v[228:231], v[22:25]
	v_mfma_f32_16x16x32_bf16 v[90:93], v[154:157], v[236:239], v[90:93]
	v_mfma_f32_16x16x32_bf16 v[18:21], v[162:165], v[236:239], v[18:21]
	v_mfma_f32_16x16x32_bf16 v[82:85], v[158:161], v[198:201], v[82:85]
	v_mfma_f32_16x16x32_bf16 v[10:13], v[166:169], v[198:201], v[10:13]
	v_mfma_f32_16x16x32_bf16 v[66:69], v[158:161], v[214:217], v[66:69]
	v_mfma_f32_16x16x32_bf16 v[2:5], v[166:169], v[214:217], v[2:5]
	v_mfma_f32_16x16x32_bf16 v[94:97], v[158:161], v[232:235], v[94:97]
	v_mfma_f32_16x16x32_bf16 v[22:25], v[166:169], v[232:235], v[22:25]
	v_mfma_f32_16x16x32_bf16 v[90:93], v[158:161], v[240:243], v[90:93]
	v_mfma_f32_16x16x32_bf16 v[18:21], v[166:169], v[240:243], v[18:21]
	s_barrier
; #define PG8_STAGE(bufoff, gbase, voff) do { _Pragma("unroll") for (int _i = 0; _i < 2; ++_i) \
;         __builtin_amdgcn_global_load_lds((const unsigned*)((const char*)(gbase) + (voff)[_i]), (PG8_LAS unsigned*)(lds + (bufoff) + ldsw + _i * 8192), 16, 0, 0); } while (0)
; #define PG8_LDA(dst, b, h) do { _Pragma("unroll") for (int m = 0; m < 4; ++m) _Pragma("unroll") for (int k = 0; k < 2; ++k) dst[m][k] = *(const PG8_LAS bf16x8*)(lds + PG8_SA(b, h) + aoff + m * 2048 + k * 1024); } while (0)
; #define PG8_LDB(dst, b, h) do { _Pragma("unroll") for (int n = 0; n < 2; ++n) _Pragma("unroll") for (int k = 0; k < 2; ++k) dst[n][k] = *(const PG8_LAS bf16x8*)(lds + PG8_SB(b, h) + boff + n * 2048 + k * 1024); } while (0)
; #define PG8_MMA(ai, bj, At, Bt) do { __builtin_amdgcn_s_setprio(1); _Pragma("unroll") for (int m = 0; m < 4; ++m) _Pragma("unroll") for (int n = 0; n < 2; ++n) _Pragma("unroll") for (int k = 0; k < 2; ++k) \
;         acc[ai][bj][m][n] = __builtin_amdgcn_mfma_f32_16x16x32_bf16(Bt[n][k], At[m][k], acc[ai][bj][m][n], 0, 0, 0); __builtin_amdgcn_s_setprio(0); } while (0)
; #define PG8_WAIT_V(n) asm volatile("s_waitcnt vmcnt(" #n ")" ::: "memory")
; #define PG8_WAIT_L(n) asm volatile("s_waitcnt lgkmcnt(" #n ")" ::: "memory")
; #define PG8_BAR __builtin_amdgcn_s_barrier()
; #define PG8_SCHED __builtin_amdgcn_sched_barrier(0)
; template <class Epi, class Sched, bool ALIGN_EPI = false, bool SP2 = false>
; __device__ __forceinline__ void gemm_phase(PG8_LAS unsigned char* lds, const Gemm g, const Sched& S, const Epi& E, const int wv) {
;     ...
;             PG8_LDB(B0, 1, 0); PG8_LDB(B1, 1, 1); PG8_SCHED; PG8_LDA(At, 1, 0); PG8_STAGE(PG8_SA(0, 1), a2 + hstepA, voffA);
;             PG8_WAIT_V(8); PG8_WAIT_L(0); PG8_BAR; PG8_MMA(0, 0, At, B0); PG8_MMA(0, 1, At, B1); PG8_BAR; PG8_SCHED;
;             PG8_LDA(At, 1, 1); PG8_STAGE(PG8_SB(1, 0), b3, voffB); PG8_STAGE(PG8_SB(1, 1), b3 + hstepB, voffB); PG8_STAGE(PG8_SA(1, 0), a3, voffA);
;             PG8_WAIT_V(8); PG8_WAIT_L(0); PG8_BAR; PG8_MMA(1, 0, At, B0); PG8_MMA(1, 1, At, B1); PG8_BAR; PG8_SCHED;
	ds_read_b128 v[138:141], v213
	ds_read_b128 v[142:145], v213 offset:1024
	ds_read_b128 v[146:149], v213 offset:2048
	ds_read_b128 v[150:153], v213 offset:3072
	ds_read_b128 v[154:157], v227
	ds_read_b128 v[158:161], v227 offset:1024
	ds_read_b128 v[162:165], v227 offset:2048
	ds_read_b128 v[166:169], v227 offset:3072
	s_add_u32 s46, s46, 0x80000
	s_addc_u32 s47, s47, 0
	s_mov_b32 m0, s66
	ds_read_b128 v[194:197], v211 offset:32768
	ds_read_b128 v[198:201], v211 offset:33792
	ds_read_b128 v[202:205], v211 offset:34816
	ds_read_b128 v[214:217], v211 offset:35840
	ds_read_b128 v[228:231], v211 offset:36864
	ds_read_b128 v[232:235], v211 offset:37888
	ds_read_b128 v[236:239], v211 offset:38912
	ds_read_b128 v[240:243], v211 offset:39936
	global_load_lds_dwordx4 v170, s[46:47]
	s_mov_b32 m0, s67
	s_nop 0
	global_load_lds_dwordx4 v172, s[46:47]
	s_waitcnt vmcnt(8)
	s_waitcnt lgkmcnt(0)
	s_barrier
	v_mfma_f32_16x16x32_bf16 v[118:121], v[138:141], v[194:197], v[118:121]
	v_mfma_f32_16x16x32_bf16 v[46:49], v[146:149], v[194:197], v[46:49]
	v_mfma_f32_16x16x32_bf16 v[110:113], v[138:141], v[202:205], v[110:113]
	v_mfma_f32_16x16x32_bf16 v[38:41], v[146:149], v[202:205], v[38:41]
	v_mfma_f32_16x16x32_bf16 v[134:137], v[138:141], v[228:231], v[134:137]
	v_mfma_f32_16x16x32_bf16 v[62:65], v[146:149], v[228:231], v[62:65]
	v_mfma_f32_16x16x32_bf16 v[130:133], v[138:141], v[236:239], v[130:133]
	v_mfma_f32_16x16x32_bf16 v[58:61], v[146:149], v[236:239], v[58:61]
	v_mfma_f32_16x16x32_bf16 v[118:121], v[142:145], v[198:201], v[118:121]
	v_mfma_f32_16x16x32_bf16 v[46:49], v[150:153], v[198:201], v[46:49]
	v_mfma_f32_16x16x32_bf16 v[110:113], v[142:145], v[214:217], v[110:113]
	v_mfma_f32_16x16x32_bf16 v[38:41], v[150:153], v[214:217], v[38:41]
	v_mfma_f32_16x16x32_bf16 v[134:137], v[142:145], v[232:235], v[134:137]
	v_mfma_f32_16x16x32_bf16 v[62:65], v[150:153], v[232:235], v[62:65]
	v_mfma_f32_16x16x32_bf16 v[130:133], v[142:145], v[240:243], v[130:133]
	v_mfma_f32_16x16x32_bf16 v[58:61], v[150:153], v[240:243], v[58:61]
	v_mfma_f32_16x16x32_bf16 v[114:117], v[154:157], v[194:197], v[114:117]
	v_mfma_f32_16x16x32_bf16 v[42:45], v[162:165], v[194:197], v[42:45]
	v_mfma_f32_16x16x32_bf16 v[106:109], v[154:157], v[202:205], v[106:109]
	v_mfma_f32_16x16x32_bf16 v[34:37], v[162:165], v[202:205], v[34:37]
	v_mfma_f32_16x16x32_bf16 v[126:129], v[154:157], v[228:231], v[126:129]
	v_mfma_f32_16x16x32_bf16 v[54:57], v[162:165], v[228:231], v[54:57]
	v_mfma_f32_16x16x32_bf16 v[122:125], v[154:157], v[236:239], v[122:125]
	v_mfma_f32_16x16x32_bf16 v[50:53], v[162:165], v[236:239], v[50:53]
	v_mfma_f32_16x16x32_bf16 v[114:117], v[158:161], v[198:201], v[114:117]
	v_mfma_f32_16x16x32_bf16 v[42:45], v[166:169], v[198:201], v[42:45]
	v_mfma_f32_16x16x32_bf16 v[106:109], v[158:161], v[214:217], v[106:109]
	v_mfma_f32_16x16x32_bf16 v[34:37], v[166:169], v[214:217], v[34:37]
	v_mfma_f32_16x16x32_bf16 v[126:129], v[158:161], v[232:235], v[126:129]
	v_mfma_f32_16x16x32_bf16 v[54:57], v[166:169], v[232:235], v[54:57]
	v_mfma_f32_16x16x32_bf16 v[122:125], v[158:161], v[240:243], v[122:125]
	v_mfma_f32_16x16x32_bf16 v[50:53], v[166:169], v[240:243], v[50:53]
	s_barrier
	s_add_i32 s46, s63, 0x18000
	s_add_i32 m0, s46, 0xffffff80
	ds_read_b128 v[194:197], v211 offset:49152
	ds_read_b128 v[198:201], v211 offset:50176
	ds_read_b128 v[202:205], v211 offset:51200
	ds_read_b128 v[214:217], v211 offset:52224
	ds_read_b128 v[228:231], v211 offset:53248
	ds_read_b128 v[232:235], v211 offset:54272
	ds_read_b128 v[236:239], v211 offset:55296
	ds_read_b128 v[240:243], v211 offset:56320
	global_load_lds_dwordx4 v0, s[76:77] offset:128
	s_add_i32 m0, s46, 0x1f80
	s_add_i32 s46, s63, 0x1c000
	global_load_lds_dwordx4 v174, s[76:77] offset:128
	s_add_i32 m0, s46, 0xffffff80
	s_nop 0
	global_load_lds_dwordx4 v0, s[48:49] offset:128
	s_add_i32 m0, s46, 0x1f80
	s_nop 0
	global_load_lds_dwordx4 v174, s[48:49] offset:128
	s_add_i32 m0, s70, 0xffffff80
	s_nop 0
	global_load_lds_dwordx4 v[246:247], off offset:128
	s_add_i32 m0, s71, 0xffffff80
	s_nop 0
	global_load_lds_dwordx4 v[248:249], off offset:128
	s_waitcnt vmcnt(8)
	s_waitcnt lgkmcnt(0)
	s_barrier
	v_mfma_f32_16x16x32_bf16 v[86:89], v[138:141], v[194:197], v[86:89]
	v_mfma_f32_16x16x32_bf16 v[14:17], v[146:149], v[194:197], v[14:17]
	v_mfma_f32_16x16x32_bf16 v[70:73], v[138:141], v[202:205], v[70:73]
	v_mfma_f32_16x16x32_bf16 v[6:9], v[146:149], v[202:205], v[6:9]
	v_mfma_f32_16x16x32_bf16 v[102:105], v[138:141], v[228:231], v[102:105]
	v_mfma_f32_16x16x32_bf16 v[30:33], v[146:149], v[228:231], v[30:33]
	v_mfma_f32_16x16x32_bf16 v[98:101], v[138:141], v[236:239], v[98:101]
	v_mfma_f32_16x16x32_bf16 v[26:29], v[146:149], v[236:239], v[26:29]
	v_mfma_f32_16x16x32_bf16 v[86:89], v[142:145], v[198:201], v[86:89]
	v_mfma_f32_16x16x32_bf16 v[14:17], v[150:153], v[198:201], v[14:17]
	v_mfma_f32_16x16x32_bf16 v[70:73], v[142:145], v[214:217], v[70:73]
	v_mfma_f32_16x16x32_bf16 v[6:9], v[150:153], v[214:217], v[6:9]
	v_mfma_f32_16x16x32_bf16 v[102:105], v[142:145], v[232:235], v[102:105]
	v_mfma_f32_16x16x32_bf16 v[30:33], v[150:153], v[232:235], v[30:33]
	v_mfma_f32_16x16x32_bf16 v[98:101], v[142:145], v[240:243], v[98:101]
	v_mfma_f32_16x16x32_bf16 v[26:29], v[150:153], v[240:243], v[26:29]
	v_mfma_f32_16x16x32_bf16 v[82:85], v[154:157], v[194:197], v[82:85]
	v_mfma_f32_16x16x32_bf16 v[10:13], v[162:165], v[194:197], v[10:13]
	v_mfma_f32_16x16x32_bf16 v[66:69], v[154:157], v[202:205], v[66:69]
	v_mfma_f32_16x16x32_bf16 v[2:5], v[162:165], v[202:205], v[2:5]
	v_mfma_f32_16x16x32_bf16 v[94:97], v[154:157], v[228:231], v[94:97]
	v_mfma_f32_16x16x32_bf16 v[22:25], v[162:165], v[228:231], v[22:25]
	v_mfma_f32_16x16x32_bf16 v[90:93], v[154:157], v[236:239], v[90:93]
	v_mfma_f32_16x16x32_bf16 v[18:21], v[162:165], v[236:239], v[18:21]
	v_mfma_f32_16x16x32_bf16 v[82:85], v[158:161], v[198:201], v[82:85]
	v_mfma_f32_16x16x32_bf16 v[10:13], v[166:169], v[198:201], v[10:13]
	v_mfma_f32_16x16x32_bf16 v[66:69], v[158:161], v[214:217], v[66:69]
	v_mfma_f32_16x16x32_bf16 v[2:5], v[166:169], v[214:217], v[2:5]
	v_mfma_f32_16x16x32_bf16 v[94:97], v[158:161], v[232:235], v[94:97]
	v_mfma_f32_16x16x32_bf16 v[22:25], v[166:169], v[232:235], v[22:25]
	v_mfma_f32_16x16x32_bf16 v[90:93], v[158:161], v[240:243], v[90:93]
	v_mfma_f32_16x16x32_bf16 v[18:21], v[166:169], v[240:243], v[18:21]
	s_barrier
	s_add_u32 s35, s35, 0x100
	s_addc_u32 s51, s51, 0
	s_cmp_ge_i32 s52, s68
	s_mov_b64 s[48:49], s[14:15]
	s_mov_b32 s46, s52
	s_cbranch_scc0 .LBB0_1495
	s_movk_i32 s78, 0x7ff
	s_movk_i32 s76, 0x3000
	s_and_b64 vcc, exec, s[30:31]
	s_cbranch_vccz .LBB0_1470

; #define PG8_STAGE(bufoff, gbase, voff) do { _Pragma("unroll") for (int _i = 0; _i < 2; ++_i) \
;         __builtin_amdgcn_global_load_lds((const unsigned*)((const char*)(gbase) + (voff)[_i]), (PG8_LAS unsigned*)(lds + (bufoff) + ldsw + _i * 8192), 16, 0, 0); } while (0)
; #define PG8_LDA(dst, b, h) do { _Pragma("unroll") for (int m = 0; m < 4; ++m) _Pragma("unroll") for (int k = 0; k < 2; ++k) dst[m][k] = *(const PG8_LAS bf16x8*)(lds + PG8_SA(b, h) + aoff + m * 2048 + k * 1024); } while (0)
; #define PG8_LDB(dst, b, h) do { _Pragma("unroll") for (int n = 0; n < 2; ++n) _Pragma("unroll") for (int k = 0; k < 2; ++k) dst[n][k] = *(const PG8_LAS bf16x8*)(lds + PG8_SB(b, h) + boff + n * 2048 + k * 1024); } while (0)
; #define PG8_MMA(ai, bj, At, Bt) do { __builtin_amdgcn_s_setprio(1); _Pragma("unroll") for (int m = 0; m < 4; ++m) _Pragma("unroll") for (int n = 0; n < 2; ++n) _Pragma("unroll") for (int k = 0; k < 2; ++k) \
;         acc[ai][bj][m][n] = __builtin_amdgcn_mfma_f32_16x16x32_bf16(Bt[n][k], At[m][k], acc[ai][bj][m][n], 0, 0, 0); __builtin_amdgcn_s_setprio(0); } while (0)
; #define PG8_WAIT_V(n) asm volatile("s_waitcnt vmcnt(" #n ")" ::: "memory")
; #define PG8_WAIT_L(n) asm volatile("s_waitcnt lgkmcnt(" #n ")" ::: "memory")
; template <class Epi, class Sched, bool ALIGN_EPI = false, bool SP2 = false>
; __device__ __forceinline__ void gemm_phase(PG8_LAS unsigned char* lds, const Gemm g, const Sched& S, const Epi& E, const int wv) {
;     ...
;             const bool last = (t == nt - 2);
;             const char* a1 = cA + (size_t)(t + 1) * kstep;
;             const char* a2 = last ? nA : cA + (size_t)(t + 2) * kstep; const char* b2 = last ? nB : cB + (size_t)(t + 2) * kstep;
;             const char* a3 = a2 + kstep; const char* b3 = b2 + kstep;
;             if (last && has_next) S.a_ready(nxt);
;             if constexpr (SP2) {
;             PG8_LDB(B0, 0, 0); PG8_LDB(B1, 0, 1); PG8_SCHED; PG8_LDA(At, 0, 0); PG8_STAGE(PG8_SA(1, 1), a1 + hstepA, voffA);
;             PG8_WAIT_V(8); PG8_WAIT_L(0); PG8_BAR; PG8_MMA(0, 0, At, B0); PG8_MMA(0, 1, At, B1); PG8_BAR; PG8_SCHED;
;             PG8_LDA(At, 0, 1); PG8_STAGE(PG8_SB(0, 0), b2, voffB); PG8_STAGE(PG8_SB(0, 1), b2 + hstepB, voffB); PG8_STAGE(PG8_SA(0, 0), a2, voffA);
;             PG8_WAIT_V(8); PG8_WAIT_L(0); PG8_BAR; PG8_MMA(1, 0, At, B0); PG8_MMA(1, 1, At, B1); PG8_BAR; PG8_SCHED;
.LBB0_1676:
	s_add_i32 s67, s44, 2
	s_add_u32 s34, s30, 0x100
	s_addc_u32 s35, s31, 0
	s_cmp_eq_u32 s59, s44
	s_cselect_b32 s45, s13, s35
	s_cselect_b32 s44, s12, s34
	s_cselect_b32 s69, s15, s66
	s_cselect_b32 s68, s14, s65
	ds_read_b128 v[114:117], v197
	ds_read_b128 v[126:129], v197 offset:1024
	ds_read_b128 v[138:141], v197 offset:2048
	ds_read_b128 v[142:145], v197 offset:3072
	ds_read_b128 v[146:149], v201
	ds_read_b128 v[150:153], v201 offset:1024
	ds_read_b128 v[154:157], v201 offset:2048
	ds_read_b128 v[158:161], v201 offset:3072
	s_add_i32 m0, s52, 0xc000
	ds_read_b128 v[162:165], v235
	ds_read_b128 v[166:169], v235 offset:1024
	ds_read_b128 v[170:173], v235 offset:2048
	ds_read_b128 v[174:177], v235 offset:3072
	ds_read_b128 v[178:181], v235 offset:4096
	ds_read_b128 v[182:185], v235 offset:5120
	ds_read_b128 v[204:207], v235 offset:6144
	ds_read_b128 v[208:211], v235 offset:7168
	global_load_lds_dwordx4 v200, s[30:31]
	s_add_i32 m0, s52, 0xe000
	s_nop 0
	global_load_lds_dwordx4 v202, s[30:31]
	s_waitcnt vmcnt(8)
	s_waitcnt lgkmcnt(0)
	s_barrier
	v_mfma_f32_16x16x32_bf16 v[134:137], v[114:117], v[162:165], v[134:137]
	v_mfma_f32_16x16x32_bf16 v[130:133], v[138:141], v[162:165], v[130:133]
	v_mfma_f32_16x16x32_bf16 v[110:113], v[114:117], v[170:173], v[110:113]
	v_mfma_f32_16x16x32_bf16 v[106:109], v[138:141], v[170:173], v[106:109]
	v_mfma_f32_16x16x32_bf16 v[94:97], v[114:117], v[178:181], v[94:97]
	v_mfma_f32_16x16x32_bf16 v[90:93], v[138:141], v[178:181], v[90:93]
	v_mfma_f32_16x16x32_bf16 v[78:81], v[114:117], v[204:207], v[78:81]
	v_mfma_f32_16x16x32_bf16 v[74:77], v[138:141], v[204:207], v[74:77]
	v_mfma_f32_16x16x32_bf16 v[134:137], v[126:129], v[166:169], v[134:137]
	v_mfma_f32_16x16x32_bf16 v[130:133], v[142:145], v[166:169], v[130:133]
	v_mfma_f32_16x16x32_bf16 v[110:113], v[126:129], v[174:177], v[110:113]
	v_mfma_f32_16x16x32_bf16 v[106:109], v[142:145], v[174:177], v[106:109]
	v_mfma_f32_16x16x32_bf16 v[94:97], v[126:129], v[182:185], v[94:97]
	v_mfma_f32_16x16x32_bf16 v[90:93], v[142:145], v[182:185], v[90:93]
	v_mfma_f32_16x16x32_bf16 v[78:81], v[126:129], v[208:211], v[78:81]
	v_mfma_f32_16x16x32_bf16 v[74:77], v[142:145], v[208:211], v[74:77]
	v_mfma_f32_16x16x32_bf16 v[122:125], v[146:149], v[162:165], v[122:125]
	v_mfma_f32_16x16x32_bf16 v[118:121], v[154:157], v[162:165], v[118:121]
	v_mfma_f32_16x16x32_bf16 v[102:105], v[146:149], v[170:173], v[102:105]
	v_mfma_f32_16x16x32_bf16 v[98:101], v[154:157], v[170:173], v[98:101]
	v_mfma_f32_16x16x32_bf16 v[86:89], v[146:149], v[178:181], v[86:89]
	v_mfma_f32_16x16x32_bf16 v[82:85], v[154:157], v[178:181], v[82:85]
	v_mfma_f32_16x16x32_bf16 v[70:73], v[146:149], v[204:207], v[70:73]
	v_mfma_f32_16x16x32_bf16 v[66:69], v[154:157], v[204:207], v[66:69]
	v_mfma_f32_16x16x32_bf16 v[122:125], v[150:153], v[166:169], v[122:125]
	v_mfma_f32_16x16x32_bf16 v[118:121], v[158:161], v[166:169], v[118:121]
	v_mfma_f32_16x16x32_bf16 v[102:105], v[150:153], v[174:177], v[102:105]
	v_mfma_f32_16x16x32_bf16 v[98:101], v[158:161], v[174:177], v[98:101]
	v_mfma_f32_16x16x32_bf16 v[86:89], v[150:153], v[182:185], v[86:89]
	v_mfma_f32_16x16x32_bf16 v[82:85], v[158:161], v[182:185], v[82:85]
	v_mfma_f32_16x16x32_bf16 v[70:73], v[150:153], v[208:211], v[70:73]
	v_mfma_f32_16x16x32_bf16 v[66:69], v[158:161], v[208:211], v[66:69]
	s_barrier
	s_add_i32 s30, s47, 0x10000
	v_lshl_add_u64 v[190:191], s[68:69], 0, v[0:1]
	s_mov_b32 m0, s30
	ds_read_b128 v[162:165], v235 offset:16384
	ds_read_b128 v[166:169], v235 offset:17408
	ds_read_b128 v[170:173], v235 offset:18432
	ds_read_b128 v[174:177], v235 offset:19456
	ds_read_b128 v[178:181], v235 offset:20480
	ds_read_b128 v[182:185], v235 offset:21504
	ds_read_b128 v[204:207], v235 offset:22528
	ds_read_b128 v[208:211], v235 offset:23552
	global_load_lds_dwordx4 v[190:191], off
	s_add_i32 m0, s30, 0x2000
	s_add_u32 s30, s68, s2
	v_lshl_add_u64 v[192:193], s[68:69], 0, v[198:199]
	s_addc_u32 s31, s69, s3
	s_add_i32 s68, s47, 0x14000
	global_load_lds_dwordx4 v[192:193], off
	v_lshl_add_u64 v[212:213], s[30:31], 0, v[0:1]
	s_mov_b32 m0, s68
	v_lshl_add_u64 v[214:215], s[30:31], 0, v[198:199]
	global_load_lds_dwordx4 v[212:213], off
	s_add_i32 m0, s68, 0x2000
	global_load_lds_dwordx4 v[214:215], off
	s_mov_b32 m0, s52
	global_load_lds_dwordx4 v194, s[44:45]
	s_mov_b32 m0, s53
	s_nop 0
	global_load_lds_dwordx4 v196, s[44:45]
	s_waitcnt vmcnt(8)
	s_waitcnt lgkmcnt(0)
	s_barrier
	v_mfma_f32_16x16x32_bf16 v[62:65], v[114:117], v[162:165], v[62:65]
	v_mfma_f32_16x16x32_bf16 v[58:61], v[138:141], v[162:165], v[58:61]
	v_mfma_f32_16x16x32_bf16 v[46:49], v[114:117], v[170:173], v[46:49]
	v_mfma_f32_16x16x32_bf16 v[42:45], v[138:141], v[170:173], v[42:45]
	v_mfma_f32_16x16x32_bf16 v[30:33], v[114:117], v[178:181], v[30:33]
	v_mfma_f32_16x16x32_bf16 v[26:29], v[138:141], v[178:181], v[26:29]
	v_mfma_f32_16x16x32_bf16 v[14:17], v[114:117], v[204:207], v[14:17]
	v_mfma_f32_16x16x32_bf16 v[10:13], v[138:141], v[204:207], v[10:13]
	v_mfma_f32_16x16x32_bf16 v[62:65], v[126:129], v[166:169], v[62:65]
	v_mfma_f32_16x16x32_bf16 v[58:61], v[142:145], v[166:169], v[58:61]
	v_mfma_f32_16x16x32_bf16 v[46:49], v[126:129], v[174:177], v[46:49]
	v_mfma_f32_16x16x32_bf16 v[42:45], v[142:145], v[174:177], v[42:45]
	v_mfma_f32_16x16x32_bf16 v[30:33], v[126:129], v[182:185], v[30:33]
	v_mfma_f32_16x16x32_bf16 v[26:29], v[142:145], v[182:185], v[26:29]
	v_mfma_f32_16x16x32_bf16 v[14:17], v[126:129], v[208:211], v[14:17]
	v_mfma_f32_16x16x32_bf16 v[10:13], v[142:145], v[208:211], v[10:13]
	v_mfma_f32_16x16x32_bf16 v[54:57], v[146:149], v[162:165], v[54:57]
	v_mfma_f32_16x16x32_bf16 v[50:53], v[154:157], v[162:165], v[50:53]
	v_mfma_f32_16x16x32_bf16 v[38:41], v[146:149], v[170:173], v[38:41]
	v_mfma_f32_16x16x32_bf16 v[34:37], v[154:157], v[170:173], v[34:37]
	v_mfma_f32_16x16x32_bf16 v[22:25], v[146:149], v[178:181], v[22:25]
	v_mfma_f32_16x16x32_bf16 v[18:21], v[154:157], v[178:181], v[18:21]
	v_mfma_f32_16x16x32_bf16 v[6:9], v[146:149], v[204:207], v[6:9]
	v_mfma_f32_16x16x32_bf16 v[2:5], v[154:157], v[204:207], v[2:5]
	v_mfma_f32_16x16x32_bf16 v[54:57], v[150:153], v[166:169], v[54:57]
	v_mfma_f32_16x16x32_bf16 v[50:53], v[158:161], v[166:169], v[50:53]
	v_mfma_f32_16x16x32_bf16 v[38:41], v[150:153], v[174:177], v[38:41]
	v_mfma_f32_16x16x32_bf16 v[34:37], v[158:161], v[174:177], v[34:37]
	v_mfma_f32_16x16x32_bf16 v[22:25], v[150:153], v[182:185], v[22:25]
	v_mfma_f32_16x16x32_bf16 v[18:21], v[158:161], v[182:185], v[18:21]
	v_mfma_f32_16x16x32_bf16 v[6:9], v[150:153], v[208:211], v[6:9]
	v_mfma_f32_16x16x32_bf16 v[2:5], v[158:161], v[208:211], v[2:5]
	s_barrier
; #define PG8_STAGE(bufoff, gbase, voff) do { _Pragma("unroll") for (int _i = 0; _i < 2; ++_i) \
;         __builtin_amdgcn_global_load_lds((const unsigned*)((const char*)(gbase) + (voff)[_i]), (PG8_LAS unsigned*)(lds + (bufoff) + ldsw + _i * 8192), 16, 0, 0); } while (0)
; #define PG8_LDA(dst, b, h) do { _Pragma("unroll") for (int m = 0; m < 4; ++m) _Pragma("unroll") for (int k = 0; k < 2; ++k) dst[m][k] = *(const PG8_LAS bf16x8*)(lds + PG8_SA(b, h) + aoff + m * 2048 + k * 1024); } while (0)
; #define PG8_LDB(dst, b, h) do { _Pragma("unroll") for (int n = 0; n < 2; ++n) _Pragma("unroll") for (int k = 0; k < 2; ++k) dst[n][k] = *(const PG8_LAS bf16x8*)(lds + PG8_SB(b, h) + boff + n * 2048 + k * 1024); } while (0)
; #define PG8_MMA(ai, bj, At, Bt) do { __builtin_amdgcn_s_setprio(1); _Pragma("unroll") for (int m = 0; m < 4; ++m) _Pragma("unroll") for (int n = 0; n < 2; ++n) _Pragma("unroll") for (int k = 0; k < 2; ++k) \
;         acc[ai][bj][m][n] = __builtin_amdgcn_mfma_f32_16x16x32_bf16(Bt[n][k], At[m][k], acc[ai][bj][m][n], 0, 0, 0); __builtin_amdgcn_s_setprio(0); } while (0)
; #define PG8_WAIT_V(n) asm volatile("s_waitcnt vmcnt(" #n ")" ::: "memory")
; #define PG8_WAIT_L(n) asm volatile("s_waitcnt lgkmcnt(" #n ")" ::: "memory")
; #define PG8_BAR __builtin_amdgcn_s_barrier()
; #define PG8_SCHED __builtin_amdgcn_sched_barrier(0)
; template <class Epi, class Sched, bool ALIGN_EPI = false, bool SP2 = false>
; __device__ __forceinline__ void gemm_phase(PG8_LAS unsigned char* lds, const Gemm g, const Sched& S, const Epi& E, const int wv) {
;     ...
;             PG8_LDB(B0, 1, 0); PG8_LDB(B1, 1, 1); PG8_SCHED; PG8_LDA(At, 1, 0); PG8_STAGE(PG8_SA(0, 1), a2 + hstepA, voffA);
;             PG8_WAIT_V(8); PG8_WAIT_L(0); PG8_BAR; PG8_MMA(0, 0, At, B0); PG8_MMA(0, 1, At, B1); PG8_BAR; PG8_SCHED;
;             PG8_LDA(At, 1, 1); PG8_STAGE(PG8_SB(1, 0), b3, voffB); PG8_STAGE(PG8_SB(1, 1), b3 + hstepB, voffB); PG8_STAGE(PG8_SA(1, 0), a3, voffA);
;             PG8_WAIT_V(8); PG8_WAIT_L(0); PG8_BAR; PG8_MMA(1, 0, At, B0); PG8_MMA(1, 1, At, B1); PG8_BAR; PG8_SCHED;
	ds_read_b128 v[114:117], v203
	ds_read_b128 v[126:129], v203 offset:1024
	ds_read_b128 v[138:141], v203 offset:2048
	ds_read_b128 v[142:145], v203 offset:3072
	ds_read_b128 v[146:149], v216
	ds_read_b128 v[150:153], v216 offset:1024
	ds_read_b128 v[154:157], v216 offset:2048
	ds_read_b128 v[158:161], v216 offset:3072
	s_add_u32 s30, s44, 0x180000
	s_addc_u32 s31, s45, 0
	s_mov_b32 m0, s54
	ds_read_b128 v[162:165], v235 offset:32768
	ds_read_b128 v[166:169], v235 offset:33792
	ds_read_b128 v[170:173], v235 offset:34816
	ds_read_b128 v[174:177], v235 offset:35840
	ds_read_b128 v[178:181], v235 offset:36864
	ds_read_b128 v[182:185], v235 offset:37888
	ds_read_b128 v[204:207], v235 offset:38912
	ds_read_b128 v[208:211], v235 offset:39936
	global_load_lds_dwordx4 v194, s[30:31]
	s_mov_b32 m0, s55
	s_nop 0
	global_load_lds_dwordx4 v196, s[30:31]
	s_waitcnt vmcnt(8)
	s_waitcnt lgkmcnt(0)
	s_barrier
	v_mfma_f32_16x16x32_bf16 v[134:137], v[114:117], v[162:165], v[134:137]
	v_mfma_f32_16x16x32_bf16 v[130:133], v[138:141], v[162:165], v[130:133]
	v_mfma_f32_16x16x32_bf16 v[110:113], v[114:117], v[170:173], v[110:113]
	v_mfma_f32_16x16x32_bf16 v[106:109], v[138:141], v[170:173], v[106:109]
	v_mfma_f32_16x16x32_bf16 v[94:97], v[114:117], v[178:181], v[94:97]
	v_mfma_f32_16x16x32_bf16 v[90:93], v[138:141], v[178:181], v[90:93]
	v_mfma_f32_16x16x32_bf16 v[78:81], v[114:117], v[204:207], v[78:81]
	v_mfma_f32_16x16x32_bf16 v[74:77], v[138:141], v[204:207], v[74:77]
	v_mfma_f32_16x16x32_bf16 v[134:137], v[126:129], v[166:169], v[134:137]
	v_mfma_f32_16x16x32_bf16 v[130:133], v[142:145], v[166:169], v[130:133]
	v_mfma_f32_16x16x32_bf16 v[110:113], v[126:129], v[174:177], v[110:113]
	v_mfma_f32_16x16x32_bf16 v[106:109], v[142:145], v[174:177], v[106:109]
	v_mfma_f32_16x16x32_bf16 v[94:97], v[126:129], v[182:185], v[94:97]
	v_mfma_f32_16x16x32_bf16 v[90:93], v[142:145], v[182:185], v[90:93]
	v_mfma_f32_16x16x32_bf16 v[78:81], v[126:129], v[208:211], v[78:81]
	v_mfma_f32_16x16x32_bf16 v[74:77], v[142:145], v[208:211], v[74:77]
	v_mfma_f32_16x16x32_bf16 v[122:125], v[146:149], v[162:165], v[122:125]
	v_mfma_f32_16x16x32_bf16 v[118:121], v[154:157], v[162:165], v[118:121]
	v_mfma_f32_16x16x32_bf16 v[102:105], v[146:149], v[170:173], v[102:105]
	v_mfma_f32_16x16x32_bf16 v[98:101], v[154:157], v[170:173], v[98:101]
	v_mfma_f32_16x16x32_bf16 v[86:89], v[146:149], v[178:181], v[86:89]
	v_mfma_f32_16x16x32_bf16 v[82:85], v[154:157], v[178:181], v[82:85]
	v_mfma_f32_16x16x32_bf16 v[70:73], v[146:149], v[204:207], v[70:73]
	v_mfma_f32_16x16x32_bf16 v[66:69], v[154:157], v[204:207], v[66:69]
	v_mfma_f32_16x16x32_bf16 v[122:125], v[150:153], v[166:169], v[122:125]
	v_mfma_f32_16x16x32_bf16 v[118:121], v[158:161], v[166:169], v[118:121]
	v_mfma_f32_16x16x32_bf16 v[102:105], v[150:153], v[174:177], v[102:105]
	v_mfma_f32_16x16x32_bf16 v[98:101], v[158:161], v[174:177], v[98:101]
	v_mfma_f32_16x16x32_bf16 v[86:89], v[150:153], v[182:185], v[86:89]
	v_mfma_f32_16x16x32_bf16 v[82:85], v[158:161], v[182:185], v[82:85]
	v_mfma_f32_16x16x32_bf16 v[70:73], v[150:153], v[208:211], v[70:73]
	v_mfma_f32_16x16x32_bf16 v[66:69], v[158:161], v[208:211], v[66:69]
	s_barrier
	s_add_i32 s30, s47, 0x18000
	s_add_i32 m0, s30, 0xffffff80
	ds_read_b128 v[162:165], v235 offset:49152
	ds_read_b128 v[166:169], v235 offset:50176
	ds_read_b128 v[170:173], v235 offset:51200
	ds_read_b128 v[174:177], v235 offset:52224
	ds_read_b128 v[178:181], v235 offset:53248
	ds_read_b128 v[182:185], v235 offset:54272
	ds_read_b128 v[204:207], v235 offset:55296
	ds_read_b128 v[208:211], v235 offset:56320
	global_load_lds_dwordx4 v[190:191], off offset:128
	s_add_i32 m0, s30, 0x1f80
	s_add_i32 s30, s47, 0x1c000
	global_load_lds_dwordx4 v[192:193], off offset:128
	s_add_i32 m0, s30, 0xffffff80
	s_nop 0
	global_load_lds_dwordx4 v[212:213], off offset:128
	s_add_i32 m0, s30, 0x1f80
	s_nop 0
	global_load_lds_dwordx4 v[214:215], off offset:128
	s_add_i32 m0, s57, 0xffffff80
	s_nop 0
	global_load_lds_dwordx4 v194, s[44:45] offset:128
	s_add_i32 m0, s58, 0xffffff80
	s_nop 0
	global_load_lds_dwordx4 v196, s[44:45] offset:128
	s_waitcnt vmcnt(8)
	s_waitcnt lgkmcnt(0)
	s_barrier
	v_mfma_f32_16x16x32_bf16 v[62:65], v[114:117], v[162:165], v[62:65]
	v_mfma_f32_16x16x32_bf16 v[58:61], v[138:141], v[162:165], v[58:61]
	v_mfma_f32_16x16x32_bf16 v[46:49], v[114:117], v[170:173], v[46:49]
	v_mfma_f32_16x16x32_bf16 v[42:45], v[138:141], v[170:173], v[42:45]
	v_mfma_f32_16x16x32_bf16 v[30:33], v[114:117], v[178:181], v[30:33]
	v_mfma_f32_16x16x32_bf16 v[26:29], v[138:141], v[178:181], v[26:29]
	v_mfma_f32_16x16x32_bf16 v[14:17], v[114:117], v[204:207], v[14:17]
	v_mfma_f32_16x16x32_bf16 v[10:13], v[138:141], v[204:207], v[10:13]
	v_mfma_f32_16x16x32_bf16 v[62:65], v[126:129], v[166:169], v[62:65]
	v_mfma_f32_16x16x32_bf16 v[58:61], v[142:145], v[166:169], v[58:61]
	v_mfma_f32_16x16x32_bf16 v[46:49], v[126:129], v[174:177], v[46:49]
	v_mfma_f32_16x16x32_bf16 v[42:45], v[142:145], v[174:177], v[42:45]
	v_mfma_f32_16x16x32_bf16 v[30:33], v[126:129], v[182:185], v[30:33]
	v_mfma_f32_16x16x32_bf16 v[26:29], v[142:145], v[182:185], v[26:29]
	v_mfma_f32_16x16x32_bf16 v[14:17], v[126:129], v[208:211], v[14:17]
	v_mfma_f32_16x16x32_bf16 v[10:13], v[142:145], v[208:211], v[10:13]
	v_mfma_f32_16x16x32_bf16 v[54:57], v[146:149], v[162:165], v[54:57]
	v_mfma_f32_16x16x32_bf16 v[50:53], v[154:157], v[162:165], v[50:53]
	v_mfma_f32_16x16x32_bf16 v[38:41], v[146:149], v[170:173], v[38:41]
	v_mfma_f32_16x16x32_bf16 v[34:37], v[154:157], v[170:173], v[34:37]
	v_mfma_f32_16x16x32_bf16 v[22:25], v[146:149], v[178:181], v[22:25]
	v_mfma_f32_16x16x32_bf16 v[18:21], v[154:157], v[178:181], v[18:21]
	v_mfma_f32_16x16x32_bf16 v[6:9], v[146:149], v[204:207], v[6:9]
	v_mfma_f32_16x16x32_bf16 v[2:5], v[154:157], v[204:207], v[2:5]
	v_mfma_f32_16x16x32_bf16 v[54:57], v[150:153], v[166:169], v[54:57]
	v_mfma_f32_16x16x32_bf16 v[50:53], v[158:161], v[166:169], v[50:53]
	v_mfma_f32_16x16x32_bf16 v[38:41], v[150:153], v[174:177], v[38:41]
	v_mfma_f32_16x16x32_bf16 v[34:37], v[158:161], v[174:177], v[34:37]
	v_mfma_f32_16x16x32_bf16 v[22:25], v[150:153], v[182:185], v[22:25]
	v_mfma_f32_16x16x32_bf16 v[18:21], v[158:161], v[182:185], v[18:21]
	v_mfma_f32_16x16x32_bf16 v[6:9], v[150:153], v[208:211], v[6:9]
	v_mfma_f32_16x16x32_bf16 v[2:5], v[158:161], v[208:211], v[2:5]
	s_barrier
	s_add_u32 s65, s65, 0x100
	s_addc_u32 s66, s66, 0
	s_cmp_ge_i32 s67, s56
	s_mov_b64 s[30:31], s[34:35]
	s_mov_b32 s44, s67
	s_cbranch_scc0 .LBB0_1676
	s_movk_i32 s68, 0x4000
	s_movk_i32 s69, 0x6000
	s_mov_b32 s70, 0x18000
	s_mov_b32 s71, 0x3f317217
	s_and_b64 vcc, exec, s[28:29]
	s_cbranch_vccz .LBB0_1652
